# GEMM K-loops: the redundant s_setprio 0 / s_setprio 1 pair in the middle of every 32-MFMA block removed (priority stays raised through the block); on top of all35
# speedup vs baseline: 1.0010x; 1.0010x over previous
; template <class Epi, class Sched, bool ALIGN_EPI = false, bool SP2 = false>
; __device__ __forceinline__ void gemm_phase(PG8_LAS unsigned char* lds, const Gemm g, const Sched& S, const Epi& E, const int wid) {
;     ...
;         const bool has_next = S.next(ui + 1, nxt);
;         const char* nA = has_next ? (const char*)g.A + (size_t)nxt.pm * tstep : cA; const char* nB = has_next ? (const char*)g.Bt + (size_t)nxt.pn * tstep : cB;
;         for (int t = 0; t < nt; t += 2) {
;             const bool last = (t == nt - 2);
;             const char* a1 = cA + (size_t)(t + 1) * kstep;
;             const char* a2 = last ? nA : cA + (size_t)(t + 2) * kstep; const char* b2 = last ? nB : cB + (size_t)(t + 2) * kstep;
;             const char* a3 = a2 + kstep; const char* b3 = b2 + kstep;
.LBB0_268:
	s_ashr_i32 s15, s14, 31
	s_lshl_b64 s[16:17], s[14:15], 19
	s_add_u32 s16, s80, s16
	s_addc_u32 s17, s81, s17
	s_and_b64 s[18:19], s[4:5], exec
	s_cselect_b32 s15, s17, s23
	s_cselect_b32 s44, s16, s22
	s_ashr_i32 s13, s12, 31
	s_lshl_b64 s[18:19], s[12:13], 19
	s_add_u32 s18, s10, s18
	s_addc_u32 s19, s11, s19
	s_and_b64 s[26:27], s[4:5], exec
	s_cselect_b32 s13, s19, s25
	s_cselect_b32 s45, s18, s24
	s_add_u32 s22, s22, 0x40080
	s_addc_u32 s23, s23, 0
	s_add_u32 s46, s24, 0x100

; template <class Epi, class Sched, bool ALIGN_EPI = false, bool SP2 = false>
; __device__ __forceinline__ void gemm_phase(PG8_LAS unsigned char* lds, const Gemm g, const Sched& S, const Epi& E, const int wid) {
;     ...
;         for (int t = 0; t < nt; t += 2) {
;             const bool last = (t == nt - 2);
	s_addc_u32 s47, s25, 0
	s_mov_b32 s48, -2


; #define PG8_STAGE(bufoff, gbase, voff) do { _Pragma("unroll") for (int _i = 0; _i < 2; ++_i) \
;         __builtin_amdgcn_global_load_lds((const unsigned*)((const char*)(gbase) + (voff)[_i]), (PG8_LAS unsigned*)(lds + (bufoff) + ldsw + _i * 8192), 16, 0, 0); } while (0)
; #define PG8_LDA(dst, b, h) do { _Pragma("unroll") for (int m = 0; m < 4; ++m) _Pragma("unroll") for (int k = 0; k < 2; ++k) dst[m][k] = *(const PG8_LAS bf16x8*)(lds + PG8_SA(b, h) + aoff + m * 2048 + k * 1024); } while (0)
; #define PG8_LDB(dst, b, h) do { _Pragma("unroll") for (int n = 0; n < 2; ++n) _Pragma("unroll") for (int k = 0; k < 2; ++k) dst[n][k] = *(const PG8_LAS bf16x8*)(lds + PG8_SB(b, h) + boff + n * 2048 + k * 1024); } while (0)
; #define PG8_MMA(ai, bj, At, Bt) do { __builtin_amdgcn_s_setprio(1); _Pragma("unroll") for (int m = 0; m < 4; ++m) _Pragma("unroll") for (int n = 0; n < 2; ++n) _Pragma("unroll") for (int k = 0; k < 2; ++k) \
;         acc[ai][bj][m][n] = __builtin_amdgcn_mfma_f32_16x16x32_bf16(Bt[n][k], At[m][k], acc[ai][bj][m][n], 0, 0, 0); __builtin_amdgcn_s_setprio(0); } while (0)
; #define PG8_WAIT_V(n) asm volatile("s_waitcnt vmcnt(" #n ")" ::: "memory")
; #define PG8_WAIT_L(n) asm volatile("s_waitcnt lgkmcnt(" #n ")" ::: "memory")
; #define PG8_BAR __builtin_amdgcn_s_barrier()
; #define PG8_SCHED __builtin_amdgcn_sched_barrier(0)
; template <class Epi, class Sched, bool ALIGN_EPI = false, bool SP2 = false>
; __device__ __forceinline__ void gemm_phase(PG8_LAS unsigned char* lds, const Gemm g, const Sched& S, const Epi& E, const int wid) {
;     ...
;             PG8_LDB(B0, 0, 0); PG8_LDB(B1, 0, 1); PG8_SCHED; PG8_LDA(At, 0, 0); PG8_STAGE(PG8_SA(1, 1), a1 + hstep, voffA);
;             PG8_WAIT_V(8); PG8_WAIT_L(0); PG8_BAR; PG8_MMA(0, 0, At, B0); PG8_MMA(0, 1, At, B1); PG8_BAR; PG8_SCHED;
;             PG8_LDA(At, 0, 1); PG8_STAGE(PG8_SB(0, 0), b2, voffB); PG8_STAGE(PG8_SB(0, 1), b2 + hstep, voffB); PG8_STAGE(PG8_SA(0, 0), a2, voffA);
;             PG8_WAIT_V(8); PG8_WAIT_L(0); PG8_BAR; PG8_MMA(1, 0, At, B0); PG8_MMA(1, 1, At, B1); PG8_BAR; PG8_SCHED;
	ds_read_b128 v[144:147], v151
	ds_read_b128 v[154:157], v151 offset:1024
	ds_read_b128 v[158:161], v151 offset:2048
	ds_read_b128 v[162:165], v151 offset:3072
	ds_read_b128 v[166:169], v152
	ds_read_b128 v[170:173], v152 offset:1024
	ds_read_b128 v[174:177], v152 offset:2048
	ds_read_b128 v[178:181], v152 offset:3072
	s_add_u32 s24, s22, 0xfffc0080
	s_addc_u32 s25, s23, -1
	s_cmp_eq_u32 s48, 12
	s_cselect_b32 s27, s15, s25
	s_cselect_b32 s26, s44, s24
	s_cselect_b32 s25, s13, s47
	s_cselect_b32 s24, s45, s46
	v_lshl_add_u64 v[206:207], s[22:23], 0, v[136:137]
	s_add_i32 m0, s21, 0xc000
	ds_read_b128 v[182:185], v153
	ds_read_b128 v[186:189], v153 offset:1024
	ds_read_b128 v[190:193], v153 offset:2048
	ds_read_b128 v[194:197], v153 offset:3072
	ds_read_b128 v[198:201], v153 offset:4096
	ds_read_b128 v[202:205], v153 offset:5120
	ds_read_b128 v[212:215], v153 offset:6144
	ds_read_b128 v[216:219], v153 offset:7168
	global_load_lds_dwordx4 v[206:207], off
	v_lshl_add_u64 v[206:207], s[22:23], 0, v[138:139]
	s_add_i32 m0, s21, 0xe000
	s_nop 0
	global_load_lds_dwordx4 v[206:207], off
	s_waitcnt vmcnt(8)
	s_waitcnt lgkmcnt(0)
	s_barrier
	s_setprio 1
	s_waitcnt lgkmcnt(0)
	v_mfma_f32_16x16x32_bf16 v[124:127], v[144:147], v[182:185], 0
	v_mfma_f32_16x16x32_bf16 v[116:119], v[158:161], v[182:185], 0
	v_mfma_f32_16x16x32_bf16 v[108:111], v[144:147], v[190:193], 0
	v_mfma_f32_16x16x32_bf16 v[100:103], v[158:161], v[190:193], 0
	v_mfma_f32_16x16x32_bf16 v[92:95], v[144:147], v[198:201], 0
	v_mfma_f32_16x16x32_bf16 v[84:87], v[158:161], v[198:201], 0
	v_mfma_f32_16x16x32_bf16 v[76:79], v[144:147], v[212:215], 0
	v_mfma_f32_16x16x32_bf16 v[68:71], v[158:161], v[212:215], 0
	v_mfma_f32_16x16x32_bf16 v[124:127], v[154:157], v[186:189], v[124:127]
	v_mfma_f32_16x16x32_bf16 v[116:119], v[162:165], v[186:189], v[116:119]
	v_mfma_f32_16x16x32_bf16 v[108:111], v[154:157], v[194:197], v[108:111]
	v_mfma_f32_16x16x32_bf16 v[100:103], v[162:165], v[194:197], v[100:103]
	v_mfma_f32_16x16x32_bf16 v[92:95], v[154:157], v[202:205], v[92:95]
	v_mfma_f32_16x16x32_bf16 v[84:87], v[162:165], v[202:205], v[84:87]
	v_mfma_f32_16x16x32_bf16 v[76:79], v[154:157], v[216:219], v[76:79]
	v_mfma_f32_16x16x32_bf16 v[68:71], v[162:165], v[216:219], v[68:71]
	v_mfma_f32_16x16x32_bf16 v[120:123], v[166:169], v[182:185], 0
	v_mfma_f32_16x16x32_bf16 v[112:115], v[174:177], v[182:185], 0
	v_mfma_f32_16x16x32_bf16 v[104:107], v[166:169], v[190:193], 0
	v_mfma_f32_16x16x32_bf16 v[96:99], v[174:177], v[190:193], 0
	v_mfma_f32_16x16x32_bf16 v[88:91], v[166:169], v[198:201], 0
	v_mfma_f32_16x16x32_bf16 v[80:83], v[174:177], v[198:201], 0
	v_mfma_f32_16x16x32_bf16 v[72:75], v[166:169], v[212:215], 0
	v_mfma_f32_16x16x32_bf16 v[64:67], v[174:177], v[212:215], 0
	v_mfma_f32_16x16x32_bf16 v[120:123], v[170:173], v[186:189], v[120:123]
	v_mfma_f32_16x16x32_bf16 v[112:115], v[178:181], v[186:189], v[112:115]
	v_mfma_f32_16x16x32_bf16 v[104:107], v[170:173], v[194:197], v[104:107]
	v_mfma_f32_16x16x32_bf16 v[96:99], v[178:181], v[194:197], v[96:99]
	v_mfma_f32_16x16x32_bf16 v[88:91], v[170:173], v[202:205], v[88:91]
	v_mfma_f32_16x16x32_bf16 v[80:83], v[178:181], v[202:205], v[80:83]
	v_mfma_f32_16x16x32_bf16 v[72:75], v[170:173], v[216:219], v[72:75]
	v_mfma_f32_16x16x32_bf16 v[64:67], v[178:181], v[216:219], v[64:67]
	s_setprio 0
	s_barrier
	s_add_i32 s49, s40, s9
	v_lshl_add_u64 v[206:207], s[24:25], 0, v[132:133]
	s_mov_b32 m0, s49
	ds_read_b128 v[182:185], v153 offset:16384
	ds_read_b128 v[186:189], v153 offset:17408
	ds_read_b128 v[190:193], v153 offset:18432
	ds_read_b128 v[194:197], v153 offset:19456
	ds_read_b128 v[198:201], v153 offset:20480
	ds_read_b128 v[202:205], v153 offset:21504
	ds_read_b128 v[212:215], v153 offset:22528
	ds_read_b128 v[216:219], v153 offset:23552
	global_load_lds_dwordx4 v[206:207], off
	s_add_i32 m0, s49, 0x2000
	s_add_u32 s50, s24, 0x40000
	v_lshl_add_u64 v[220:221], s[24:25], 0, v[128:129]
	s_addc_u32 s51, s25, 0
	s_add_i32 s49, s41, s9
	global_load_lds_dwordx4 v[220:221], off
	v_lshl_add_u64 v[222:223], s[50:51], 0, v[132:133]
	s_mov_b32 m0, s49
	v_lshl_add_u64 v[224:225], s[26:27], 0, v[130:131]
	global_load_lds_dwordx4 v[222:223], off
	v_lshl_add_u64 v[222:223], s[50:51], 0, v[128:129]
	s_add_i32 m0, s49, 0x2000
	s_nop 0
	global_load_lds_dwordx4 v[222:223], off
	v_lshl_add_u64 v[222:223], s[26:27], 0, v[134:135]
	s_mov_b32 m0, s21
	s_nop 0
	global_load_lds_dwordx4 v[222:223], off
	s_mov_b32 m0, s30
	s_nop 0
	global_load_lds_dwordx4 v[224:225], off
	s_waitcnt vmcnt(8)
	s_waitcnt lgkmcnt(0)
	s_barrier
	s_setprio 1
	s_waitcnt lgkmcnt(0)
	v_mfma_f32_16x16x32_bf16 v[60:63], v[144:147], v[182:185], 0
	v_mfma_f32_16x16x32_bf16 v[52:55], v[158:161], v[182:185], 0
	v_mfma_f32_16x16x32_bf16 v[44:47], v[144:147], v[190:193], 0
	v_mfma_f32_16x16x32_bf16 v[36:39], v[158:161], v[190:193], 0
	v_mfma_f32_16x16x32_bf16 v[28:31], v[144:147], v[198:201], 0
	v_mfma_f32_16x16x32_bf16 v[20:23], v[158:161], v[198:201], 0
	v_mfma_f32_16x16x32_bf16 v[12:15], v[144:147], v[212:215], 0
	v_mfma_f32_16x16x32_bf16 v[4:7], v[158:161], v[212:215], 0
	v_mfma_f32_16x16x32_bf16 v[60:63], v[154:157], v[186:189], v[60:63]
	v_mfma_f32_16x16x32_bf16 v[52:55], v[162:165], v[186:189], v[52:55]
	v_mfma_f32_16x16x32_bf16 v[44:47], v[154:157], v[194:197], v[44:47]
	v_mfma_f32_16x16x32_bf16 v[36:39], v[162:165], v[194:197], v[36:39]
	v_mfma_f32_16x16x32_bf16 v[28:31], v[154:157], v[202:205], v[28:31]
	v_mfma_f32_16x16x32_bf16 v[20:23], v[162:165], v[202:205], v[20:23]
	v_mfma_f32_16x16x32_bf16 v[12:15], v[154:157], v[216:219], v[12:15]
	v_mfma_f32_16x16x32_bf16 v[4:7], v[162:165], v[216:219], v[4:7]
	v_mfma_f32_16x16x32_bf16 v[56:59], v[166:169], v[182:185], 0
	v_mfma_f32_16x16x32_bf16 v[48:51], v[174:177], v[182:185], 0
	v_mfma_f32_16x16x32_bf16 v[40:43], v[166:169], v[190:193], 0
	v_mfma_f32_16x16x32_bf16 v[32:35], v[174:177], v[190:193], 0
	v_mfma_f32_16x16x32_bf16 v[24:27], v[166:169], v[198:201], 0
	v_mfma_f32_16x16x32_bf16 v[16:19], v[174:177], v[198:201], 0
	v_mfma_f32_16x16x32_bf16 v[8:11], v[166:169], v[212:215], 0
	v_mfma_f32_16x16x32_bf16 v[0:3], v[174:177], v[212:215], 0
	v_mfma_f32_16x16x32_bf16 v[56:59], v[170:173], v[186:189], v[56:59]
	v_mfma_f32_16x16x32_bf16 v[48:51], v[178:181], v[186:189], v[48:51]
	v_mfma_f32_16x16x32_bf16 v[40:43], v[170:173], v[194:197], v[40:43]
	v_mfma_f32_16x16x32_bf16 v[32:35], v[178:181], v[194:197], v[32:35]
	v_mfma_f32_16x16x32_bf16 v[24:27], v[170:173], v[202:205], v[24:27]
	v_mfma_f32_16x16x32_bf16 v[16:19], v[178:181], v[202:205], v[16:19]
	v_mfma_f32_16x16x32_bf16 v[8:11], v[170:173], v[216:219], v[8:11]
	v_mfma_f32_16x16x32_bf16 v[0:3], v[178:181], v[216:219], v[0:3]
	s_setprio 0
	s_barrier
; #define PG8_STAGE(bufoff, gbase, voff) do { _Pragma("unroll") for (int _i = 0; _i < 2; ++_i) \
;         __builtin_amdgcn_global_load_lds((const unsigned*)((const char*)(gbase) + (voff)[_i]), (PG8_LAS unsigned*)(lds + (bufoff) + ldsw + _i * 8192), 16, 0, 0); } while (0)
; #define PG8_LDA(dst, b, h) do { _Pragma("unroll") for (int m = 0; m < 4; ++m) _Pragma("unroll") for (int k = 0; k < 2; ++k) dst[m][k] = *(const PG8_LAS bf16x8*)(lds + PG8_SA(b, h) + aoff + m * 2048 + k * 1024); } while (0)
; #define PG8_LDB(dst, b, h) do { _Pragma("unroll") for (int n = 0; n < 2; ++n) _Pragma("unroll") for (int k = 0; k < 2; ++k) dst[n][k] = *(const PG8_LAS bf16x8*)(lds + PG8_SB(b, h) + boff + n * 2048 + k * 1024); } while (0)
; #define PG8_MMA(ai, bj, At, Bt) do { __builtin_amdgcn_s_setprio(1); _Pragma("unroll") for (int m = 0; m < 4; ++m) _Pragma("unroll") for (int n = 0; n < 2; ++n) _Pragma("unroll") for (int k = 0; k < 2; ++k) \
;         acc[ai][bj][m][n] = __builtin_amdgcn_mfma_f32_16x16x32_bf16(Bt[n][k], At[m][k], acc[ai][bj][m][n], 0, 0, 0); __builtin_amdgcn_s_setprio(0); } while (0)
; #define PG8_WAIT_V(n) asm volatile("s_waitcnt vmcnt(" #n ")" ::: "memory")
; #define PG8_WAIT_L(n) asm volatile("s_waitcnt lgkmcnt(" #n ")" ::: "memory")
; #define PG8_BAR __builtin_amdgcn_s_barrier()
; #define PG8_SCHED __builtin_amdgcn_sched_barrier(0)
; template <class Epi, class Sched, bool ALIGN_EPI = false, bool SP2 = false>
; __device__ __forceinline__ void gemm_phase(PG8_LAS unsigned char* lds, const Gemm g, const Sched& S, const Epi& E, const int wid) {
;     ...
;             PG8_LDB(B0, 1, 0); PG8_LDB(B1, 1, 1); PG8_SCHED; PG8_LDA(At, 1, 0); PG8_STAGE(PG8_SA(0, 1), a2 + hstep, voffA);
;             PG8_WAIT_V(8); PG8_WAIT_L(0); PG8_BAR; PG8_MMA(0, 0, At, B0); PG8_MMA(0, 1, At, B1); PG8_BAR; PG8_SCHED;
;             PG8_LDA(At, 1, 1); PG8_STAGE(PG8_SB(1, 0), b3, voffB); PG8_STAGE(PG8_SB(1, 1), b3 + hstep, voffB); PG8_STAGE(PG8_SA(1, 0), a3, voffA);
;             PG8_WAIT_V(8); PG8_WAIT_L(0); PG8_BAR; PG8_MMA(1, 0, At, B0); PG8_MMA(1, 1, At, B1); PG8_BAR; PG8_SCHED;
	s_add_i32 s49, 0, 0x18000
	s_add_i32 s50, 0, 0x1c000
	v_add_u32_e32 v162, s49, v149
	v_add_u32_e32 v178, s50, v149
	ds_read_b128 v[144:147], v162
	ds_read_b128 v[154:157], v162 offset:1024
	ds_read_b128 v[158:161], v162 offset:2048
	ds_read_b128 v[162:165], v162 offset:3072
	ds_read_b128 v[166:169], v178
	ds_read_b128 v[170:173], v178 offset:1024
	ds_read_b128 v[174:177], v178 offset:2048
	ds_read_b128 v[178:181], v178 offset:3072
	s_add_u32 s26, s26, 0x40000
	s_addc_u32 s27, s27, 0
	s_mov_b32 m0, s31
	v_lshl_add_u64 v[226:227], s[26:27], 0, v[134:135]
	ds_read_b128 v[182:185], v153 offset:32768
	ds_read_b128 v[186:189], v153 offset:33792
	ds_read_b128 v[190:193], v153 offset:34816
	ds_read_b128 v[194:197], v153 offset:35840
	ds_read_b128 v[198:201], v153 offset:36864
	ds_read_b128 v[202:205], v153 offset:37888
	ds_read_b128 v[212:215], v153 offset:38912
	ds_read_b128 v[216:219], v153 offset:39936
	global_load_lds_dwordx4 v[226:227], off
	v_lshl_add_u64 v[226:227], s[26:27], 0, v[130:131]
	s_mov_b32 m0, s33
	s_nop 0
	global_load_lds_dwordx4 v[226:227], off
	s_waitcnt vmcnt(8)
	s_waitcnt lgkmcnt(0)
	s_barrier
	s_setprio 1
	s_waitcnt lgkmcnt(0)
	v_mfma_f32_16x16x32_bf16 v[124:127], v[144:147], v[182:185], v[124:127]
	v_mfma_f32_16x16x32_bf16 v[116:119], v[158:161], v[182:185], v[116:119]
	v_mfma_f32_16x16x32_bf16 v[108:111], v[144:147], v[190:193], v[108:111]
	v_mfma_f32_16x16x32_bf16 v[100:103], v[158:161], v[190:193], v[100:103]
	v_mfma_f32_16x16x32_bf16 v[92:95], v[144:147], v[198:201], v[92:95]
	v_mfma_f32_16x16x32_bf16 v[84:87], v[158:161], v[198:201], v[84:87]
	v_mfma_f32_16x16x32_bf16 v[76:79], v[144:147], v[212:215], v[76:79]
	v_mfma_f32_16x16x32_bf16 v[68:71], v[158:161], v[212:215], v[68:71]
	v_mfma_f32_16x16x32_bf16 v[124:127], v[154:157], v[186:189], v[124:127]
	v_mfma_f32_16x16x32_bf16 v[116:119], v[162:165], v[186:189], v[116:119]
	v_mfma_f32_16x16x32_bf16 v[108:111], v[154:157], v[194:197], v[108:111]
	v_mfma_f32_16x16x32_bf16 v[100:103], v[162:165], v[194:197], v[100:103]
	v_mfma_f32_16x16x32_bf16 v[92:95], v[154:157], v[202:205], v[92:95]
	v_mfma_f32_16x16x32_bf16 v[84:87], v[162:165], v[202:205], v[84:87]
	v_mfma_f32_16x16x32_bf16 v[76:79], v[154:157], v[216:219], v[76:79]
	v_mfma_f32_16x16x32_bf16 v[68:71], v[162:165], v[216:219], v[68:71]
	v_mfma_f32_16x16x32_bf16 v[120:123], v[166:169], v[182:185], v[120:123]
	v_mfma_f32_16x16x32_bf16 v[112:115], v[174:177], v[182:185], v[112:115]
	v_mfma_f32_16x16x32_bf16 v[104:107], v[166:169], v[190:193], v[104:107]
	v_mfma_f32_16x16x32_bf16 v[96:99], v[174:177], v[190:193], v[96:99]
	v_mfma_f32_16x16x32_bf16 v[88:91], v[166:169], v[198:201], v[88:91]
	v_mfma_f32_16x16x32_bf16 v[80:83], v[174:177], v[198:201], v[80:83]
	v_mfma_f32_16x16x32_bf16 v[72:75], v[166:169], v[212:215], v[72:75]
	v_mfma_f32_16x16x32_bf16 v[64:67], v[174:177], v[212:215], v[64:67]
	v_mfma_f32_16x16x32_bf16 v[120:123], v[170:173], v[186:189], v[120:123]
	v_mfma_f32_16x16x32_bf16 v[112:115], v[178:181], v[186:189], v[112:115]
	v_mfma_f32_16x16x32_bf16 v[104:107], v[170:173], v[194:197], v[104:107]
	v_mfma_f32_16x16x32_bf16 v[96:99], v[178:181], v[194:197], v[96:99]
	v_mfma_f32_16x16x32_bf16 v[88:91], v[170:173], v[202:205], v[88:91]
	v_mfma_f32_16x16x32_bf16 v[80:83], v[178:181], v[202:205], v[80:83]
	v_mfma_f32_16x16x32_bf16 v[72:75], v[170:173], v[216:219], v[72:75]
	v_mfma_f32_16x16x32_bf16 v[64:67], v[178:181], v[216:219], v[64:67]
	s_setprio 0
	s_barrier
	s_add_i32 s26, s49, s9
	v_lshl_add_u64 v[206:207], v[206:207], 0, s[6:7]
	s_mov_b32 m0, s26
	ds_read_b128 v[182:185], v153 offset:49152
	ds_read_b128 v[186:189], v153 offset:50176
	ds_read_b128 v[190:193], v153 offset:51200
	ds_read_b128 v[194:197], v153 offset:52224
	ds_read_b128 v[198:201], v153 offset:53248
	ds_read_b128 v[202:205], v153 offset:54272
	ds_read_b128 v[212:215], v153 offset:55296
	ds_read_b128 v[216:219], v153 offset:56320
	global_load_lds_dwordx4 v[206:207], off
	s_add_i32 m0, s26, 0x2000
	s_add_u32 s24, s24, 0x40080
	v_lshl_add_u64 v[206:207], v[220:221], 0, s[6:7]
	s_addc_u32 s25, s25, 0
	s_add_i32 s26, s50, s9
	global_load_lds_dwordx4 v[206:207], off
	v_lshl_add_u64 v[206:207], s[24:25], 0, v[132:133]
	s_mov_b32 m0, s26
	s_nop 0
	global_load_lds_dwordx4 v[206:207], off
	v_lshl_add_u64 v[206:207], s[24:25], 0, v[128:129]
	s_add_i32 m0, s26, 0x2000
	s_nop 0
	global_load_lds_dwordx4 v[206:207], off
	v_lshl_add_u64 v[206:207], v[222:223], 0, s[6:7]
	s_mov_b32 m0, s38
	s_nop 0
	global_load_lds_dwordx4 v[206:207], off
	v_lshl_add_u64 v[206:207], v[224:225], 0, s[6:7]
	s_mov_b32 m0, s39
	s_nop 0
	global_load_lds_dwordx4 v[206:207], off
	s_waitcnt vmcnt(8)
	s_waitcnt lgkmcnt(0)
	s_barrier
; #define PG8_STAGE(bufoff, gbase, voff) do { _Pragma("unroll") for (int _i = 0; _i < 2; ++_i) \
;         __builtin_amdgcn_global_load_lds((const unsigned*)((const char*)(gbase) + (voff)[_i]), (PG8_LAS unsigned*)(lds + (bufoff) + ldsw + _i * 8192), 16, 0, 0); } while (0)
; #define PG8_LDA(dst, b, h) do { _Pragma("unroll") for (int m = 0; m < 4; ++m) _Pragma("unroll") for (int k = 0; k < 2; ++k) dst[m][k] = *(const PG8_LAS bf16x8*)(lds + PG8_SA(b, h) + aoff + m * 2048 + k * 1024); } while (0)
; #define PG8_LDB(dst, b, h) do { _Pragma("unroll") for (int n = 0; n < 2; ++n) _Pragma("unroll") for (int k = 0; k < 2; ++k) dst[n][k] = *(const PG8_LAS bf16x8*)(lds + PG8_SB(b, h) + boff + n * 2048 + k * 1024); } while (0)
; #define PG8_MMA(ai, bj, At, Bt) do { __builtin_amdgcn_s_setprio(1); _Pragma("unroll") for (int m = 0; m < 4; ++m) _Pragma("unroll") for (int n = 0; n < 2; ++n) _Pragma("unroll") for (int k = 0; k < 2; ++k) \
;         acc[ai][bj][m][n] = __builtin_amdgcn_mfma_f32_16x16x32_bf16(Bt[n][k], At[m][k], acc[ai][bj][m][n], 0, 0, 0); __builtin_amdgcn_s_setprio(0); } while (0)
; #define PG8_BAR __builtin_amdgcn_s_barrier()
; template <class Epi, class Sched, bool ALIGN_EPI = false, bool SP2 = false>
; __device__ __forceinline__ void gemm_phase(PG8_LAS unsigned char* lds, const Gemm g, const Sched& S, const Epi& E, const int wid) {
;     ...
;             PG8_LDB(B0, 0, 0); PG8_LDB(B1, 0, 1); PG8_SCHED; PG8_LDA(At, 0, 0); PG8_STAGE(PG8_SA(1, 1), a1 + hstep, voffA);
;             PG8_WAIT_V(8); PG8_WAIT_L(0); PG8_BAR; PG8_MMA(0, 0, At, B0); PG8_MMA(0, 1, At, B1); PG8_BAR; PG8_SCHED;
;             PG8_LDA(At, 0, 1); PG8_STAGE(PG8_SB(0, 0), b2, voffB); PG8_STAGE(PG8_SB(0, 1), b2 + hstep, voffB); PG8_STAGE(PG8_SA(0, 0), a2, voffA);
;             PG8_WAIT_V(8); PG8_WAIT_L(0); PG8_BAR; PG8_MMA(1, 0, At, B0); PG8_MMA(1, 1, At, B1); PG8_BAR; PG8_SCHED;
;             PG8_LDB(B0, 1, 0); PG8_LDB(B1, 1, 1); PG8_SCHED; PG8_LDA(At, 1, 0); PG8_STAGE(PG8_SA(0, 1), a2 + hstep, voffA);
;             PG8_WAIT_V(8); PG8_WAIT_L(0); PG8_BAR; PG8_MMA(0, 0, At, B0); PG8_MMA(0, 1, At, B1); PG8_BAR; PG8_SCHED;
;             PG8_LDA(At, 1, 1); PG8_STAGE(PG8_SB(1, 0), b3, voffB); PG8_STAGE(PG8_SB(1, 1), b3 + hstep, voffB); PG8_STAGE(PG8_SA(1, 0), a3, voffA);
;             PG8_WAIT_V(8); PG8_WAIT_L(0); PG8_BAR; PG8_MMA(1, 0, At, B0); PG8_MMA(1, 1, At, B1); PG8_BAR; PG8_SCHED;
	s_setprio 1
	s_waitcnt lgkmcnt(0)
	v_mfma_f32_16x16x32_bf16 v[60:63], v[144:147], v[182:185], v[60:63]
	v_mfma_f32_16x16x32_bf16 v[52:55], v[158:161], v[182:185], v[52:55]
	v_mfma_f32_16x16x32_bf16 v[44:47], v[144:147], v[190:193], v[44:47]
	v_mfma_f32_16x16x32_bf16 v[36:39], v[158:161], v[190:193], v[36:39]
	v_mfma_f32_16x16x32_bf16 v[28:31], v[144:147], v[198:201], v[28:31]
	v_mfma_f32_16x16x32_bf16 v[20:23], v[158:161], v[198:201], v[20:23]
	v_mfma_f32_16x16x32_bf16 v[12:15], v[144:147], v[212:215], v[12:15]
	v_mfma_f32_16x16x32_bf16 v[4:7], v[158:161], v[212:215], v[4:7]
	v_mfma_f32_16x16x32_bf16 v[60:63], v[154:157], v[186:189], v[60:63]
	v_mfma_f32_16x16x32_bf16 v[52:55], v[162:165], v[186:189], v[52:55]
	v_mfma_f32_16x16x32_bf16 v[44:47], v[154:157], v[194:197], v[44:47]
	v_mfma_f32_16x16x32_bf16 v[36:39], v[162:165], v[194:197], v[36:39]
	v_mfma_f32_16x16x32_bf16 v[28:31], v[154:157], v[202:205], v[28:31]
	v_mfma_f32_16x16x32_bf16 v[20:23], v[162:165], v[202:205], v[20:23]
	v_mfma_f32_16x16x32_bf16 v[12:15], v[154:157], v[216:219], v[12:15]
	v_mfma_f32_16x16x32_bf16 v[4:7], v[162:165], v[216:219], v[4:7]
	v_mfma_f32_16x16x32_bf16 v[56:59], v[166:169], v[182:185], v[56:59]
	v_mfma_f32_16x16x32_bf16 v[48:51], v[174:177], v[182:185], v[48:51]
	v_mfma_f32_16x16x32_bf16 v[40:43], v[166:169], v[190:193], v[40:43]
	v_mfma_f32_16x16x32_bf16 v[32:35], v[174:177], v[190:193], v[32:35]
	v_mfma_f32_16x16x32_bf16 v[24:27], v[166:169], v[198:201], v[24:27]
	v_mfma_f32_16x16x32_bf16 v[16:19], v[174:177], v[198:201], v[16:19]
	v_mfma_f32_16x16x32_bf16 v[8:11], v[166:169], v[212:215], v[8:11]
	v_mfma_f32_16x16x32_bf16 v[0:3], v[174:177], v[212:215], v[0:3]
	v_mfma_f32_16x16x32_bf16 v[56:59], v[170:173], v[186:189], v[56:59]
	v_mfma_f32_16x16x32_bf16 v[48:51], v[178:181], v[186:189], v[48:51]
	v_mfma_f32_16x16x32_bf16 v[40:43], v[170:173], v[194:197], v[40:43]
	v_mfma_f32_16x16x32_bf16 v[32:35], v[178:181], v[194:197], v[32:35]
	v_mfma_f32_16x16x32_bf16 v[24:27], v[170:173], v[202:205], v[24:27]
	v_mfma_f32_16x16x32_bf16 v[16:19], v[178:181], v[202:205], v[16:19]
	v_mfma_f32_16x16x32_bf16 v[8:11], v[170:173], v[216:219], v[8:11]
	v_mfma_f32_16x16x32_bf16 v[0:3], v[178:181], v[216:219], v[0:3]
	s_setprio 0
	s_barrier
	s_add_i32 s48, s48, 2
	s_add_u32 s22, s22, 0x100
	s_addc_u32 s23, s23, 0
	s_add_u32 s46, s46, 0x100
	s_addc_u32 s47, s47, 0
	s_cmp_gt_u32 s48, 13
	s_cbranch_scc0 .LBB0_269
	s_branch .Lkp_exit_0
.LBB0_269:
	ds_read_b128 v[144:147], v151
	ds_read_b128 v[154:157], v151 offset:1024
	ds_read_b128 v[158:161], v151 offset:2048
	ds_read_b128 v[162:165], v151 offset:3072
	ds_read_b128 v[166:169], v152
	ds_read_b128 v[170:173], v152 offset:1024
	ds_read_b128 v[174:177], v152 offset:2048
	ds_read_b128 v[178:181], v152 offset:3072
	s_add_u32 s24, s22, 0xfffc0080
	s_addc_u32 s25, s23, -1
	s_cmp_eq_u32 s48, 12
	s_cselect_b32 s27, s15, s25
	s_cselect_b32 s26, s44, s24
	s_cselect_b32 s25, s13, s47
	s_cselect_b32 s24, s45, s46
	v_lshl_add_u64 v[206:207], s[22:23], 0, v[136:137]
	s_add_i32 m0, s21, 0xc000
	ds_read_b128 v[182:185], v153
	ds_read_b128 v[186:189], v153 offset:1024
	ds_read_b128 v[190:193], v153 offset:2048
	ds_read_b128 v[194:197], v153 offset:3072
	ds_read_b128 v[198:201], v153 offset:4096
	ds_read_b128 v[202:205], v153 offset:5120
	ds_read_b128 v[212:215], v153 offset:6144
	ds_read_b128 v[216:219], v153 offset:7168
	global_load_lds_dwordx4 v[206:207], off
	v_lshl_add_u64 v[206:207], s[22:23], 0, v[138:139]
	s_add_i32 m0, s21, 0xe000
	s_nop 0
	global_load_lds_dwordx4 v[206:207], off
	s_waitcnt vmcnt(8)
	s_waitcnt lgkmcnt(0)
	s_barrier
	s_setprio 1
	s_waitcnt lgkmcnt(0)
	v_mfma_f32_16x16x32_bf16 v[124:127], v[144:147], v[182:185], v[124:127]
	v_mfma_f32_16x16x32_bf16 v[116:119], v[158:161], v[182:185], v[116:119]
	v_mfma_f32_16x16x32_bf16 v[108:111], v[144:147], v[190:193], v[108:111]
	v_mfma_f32_16x16x32_bf16 v[100:103], v[158:161], v[190:193], v[100:103]
	v_mfma_f32_16x16x32_bf16 v[92:95], v[144:147], v[198:201], v[92:95]
	v_mfma_f32_16x16x32_bf16 v[84:87], v[158:161], v[198:201], v[84:87]
	v_mfma_f32_16x16x32_bf16 v[76:79], v[144:147], v[212:215], v[76:79]
	v_mfma_f32_16x16x32_bf16 v[68:71], v[158:161], v[212:215], v[68:71]
	v_mfma_f32_16x16x32_bf16 v[124:127], v[154:157], v[186:189], v[124:127]
	v_mfma_f32_16x16x32_bf16 v[116:119], v[162:165], v[186:189], v[116:119]
	v_mfma_f32_16x16x32_bf16 v[108:111], v[154:157], v[194:197], v[108:111]
	v_mfma_f32_16x16x32_bf16 v[100:103], v[162:165], v[194:197], v[100:103]
	v_mfma_f32_16x16x32_bf16 v[92:95], v[154:157], v[202:205], v[92:95]
	v_mfma_f32_16x16x32_bf16 v[84:87], v[162:165], v[202:205], v[84:87]
	v_mfma_f32_16x16x32_bf16 v[76:79], v[154:157], v[216:219], v[76:79]
	v_mfma_f32_16x16x32_bf16 v[68:71], v[162:165], v[216:219], v[68:71]
	v_mfma_f32_16x16x32_bf16 v[120:123], v[166:169], v[182:185], v[120:123]
	v_mfma_f32_16x16x32_bf16 v[112:115], v[174:177], v[182:185], v[112:115]
	v_mfma_f32_16x16x32_bf16 v[104:107], v[166:169], v[190:193], v[104:107]
	v_mfma_f32_16x16x32_bf16 v[96:99], v[174:177], v[190:193], v[96:99]
	v_mfma_f32_16x16x32_bf16 v[88:91], v[166:169], v[198:201], v[88:91]
	v_mfma_f32_16x16x32_bf16 v[80:83], v[174:177], v[198:201], v[80:83]
	v_mfma_f32_16x16x32_bf16 v[72:75], v[166:169], v[212:215], v[72:75]
	v_mfma_f32_16x16x32_bf16 v[64:67], v[174:177], v[212:215], v[64:67]
	v_mfma_f32_16x16x32_bf16 v[120:123], v[170:173], v[186:189], v[120:123]
	v_mfma_f32_16x16x32_bf16 v[112:115], v[178:181], v[186:189], v[112:115]
	v_mfma_f32_16x16x32_bf16 v[104:107], v[170:173], v[194:197], v[104:107]
	v_mfma_f32_16x16x32_bf16 v[96:99], v[178:181], v[194:197], v[96:99]
	v_mfma_f32_16x16x32_bf16 v[88:91], v[170:173], v[202:205], v[88:91]
	v_mfma_f32_16x16x32_bf16 v[80:83], v[178:181], v[202:205], v[80:83]
	v_mfma_f32_16x16x32_bf16 v[72:75], v[170:173], v[216:219], v[72:75]
	v_mfma_f32_16x16x32_bf16 v[64:67], v[178:181], v[216:219], v[64:67]
	s_setprio 0
	s_barrier
; #define PG8_STAGE(bufoff, gbase, voff) do { _Pragma("unroll") for (int _i = 0; _i < 2; ++_i) \
;         __builtin_amdgcn_global_load_lds((const unsigned*)((const char*)(gbase) + (voff)[_i]), (PG8_LAS unsigned*)(lds + (bufoff) + ldsw + _i * 8192), 16, 0, 0); } while (0)
; #define PG8_LDA(dst, b, h) do { _Pragma("unroll") for (int m = 0; m < 4; ++m) _Pragma("unroll") for (int k = 0; k < 2; ++k) dst[m][k] = *(const PG8_LAS bf16x8*)(lds + PG8_SA(b, h) + aoff + m * 2048 + k * 1024); } while (0)
; #define PG8_LDB(dst, b, h) do { _Pragma("unroll") for (int n = 0; n < 2; ++n) _Pragma("unroll") for (int k = 0; k < 2; ++k) dst[n][k] = *(const PG8_LAS bf16x8*)(lds + PG8_SB(b, h) + boff + n * 2048 + k * 1024); } while (0)
; #define PG8_MMA(ai, bj, At, Bt) do { __builtin_amdgcn_s_setprio(1); _Pragma("unroll") for (int m = 0; m < 4; ++m) _Pragma("unroll") for (int n = 0; n < 2; ++n) _Pragma("unroll") for (int k = 0; k < 2; ++k) \
;         acc[ai][bj][m][n] = __builtin_amdgcn_mfma_f32_16x16x32_bf16(Bt[n][k], At[m][k], acc[ai][bj][m][n], 0, 0, 0); __builtin_amdgcn_s_setprio(0); } while (0)
; #define PG8_WAIT_V(n) asm volatile("s_waitcnt vmcnt(" #n ")" ::: "memory")
; #define PG8_WAIT_L(n) asm volatile("s_waitcnt lgkmcnt(" #n ")" ::: "memory")
; #define PG8_BAR __builtin_amdgcn_s_barrier()
; #define PG8_SCHED __builtin_amdgcn_sched_barrier(0)
; template <class Epi, class Sched, bool ALIGN_EPI = false, bool SP2 = false>
; __device__ __forceinline__ void gemm_phase(PG8_LAS unsigned char* lds, const Gemm g, const Sched& S, const Epi& E, const int wid) {
;     ...
;             PG8_LDA(At, 0, 1); PG8_STAGE(PG8_SB(0, 0), b2, voffB); PG8_STAGE(PG8_SB(0, 1), b2 + hstep, voffB); PG8_STAGE(PG8_SA(0, 0), a2, voffA);
;             PG8_WAIT_V(8); PG8_WAIT_L(0); PG8_BAR; PG8_MMA(1, 0, At, B0); PG8_MMA(1, 1, At, B1); PG8_BAR; PG8_SCHED;
;             PG8_LDB(B0, 1, 0); PG8_LDB(B1, 1, 1); PG8_SCHED; PG8_LDA(At, 1, 0); PG8_STAGE(PG8_SA(0, 1), a2 + hstep, voffA);
;             PG8_WAIT_V(8); PG8_WAIT_L(0); PG8_BAR; PG8_MMA(0, 0, At, B0); PG8_MMA(0, 1, At, B1); PG8_BAR; PG8_SCHED;
	s_add_i32 s49, s40, s9
	v_lshl_add_u64 v[206:207], s[24:25], 0, v[132:133]
	s_mov_b32 m0, s49
	ds_read_b128 v[182:185], v153 offset:16384
	ds_read_b128 v[186:189], v153 offset:17408
	ds_read_b128 v[190:193], v153 offset:18432
	ds_read_b128 v[194:197], v153 offset:19456
	ds_read_b128 v[198:201], v153 offset:20480
	ds_read_b128 v[202:205], v153 offset:21504
	ds_read_b128 v[212:215], v153 offset:22528
	ds_read_b128 v[216:219], v153 offset:23552
	global_load_lds_dwordx4 v[206:207], off
	s_add_i32 m0, s49, 0x2000
	s_add_u32 s50, s24, 0x40000
	v_lshl_add_u64 v[220:221], s[24:25], 0, v[128:129]
	s_addc_u32 s51, s25, 0
	s_add_i32 s49, s41, s9
	global_load_lds_dwordx4 v[220:221], off
	v_lshl_add_u64 v[222:223], s[50:51], 0, v[132:133]
	s_mov_b32 m0, s49
	v_lshl_add_u64 v[224:225], s[26:27], 0, v[130:131]
	global_load_lds_dwordx4 v[222:223], off
	v_lshl_add_u64 v[222:223], s[50:51], 0, v[128:129]
	s_add_i32 m0, s49, 0x2000
	s_nop 0
	global_load_lds_dwordx4 v[222:223], off
	v_lshl_add_u64 v[222:223], s[26:27], 0, v[134:135]
	s_mov_b32 m0, s21
	s_nop 0
	global_load_lds_dwordx4 v[222:223], off
	s_mov_b32 m0, s30
	s_nop 0
	global_load_lds_dwordx4 v[224:225], off
	s_waitcnt vmcnt(8)
	s_waitcnt lgkmcnt(0)
	s_barrier
	s_setprio 1
	s_waitcnt lgkmcnt(0)
	v_mfma_f32_16x16x32_bf16 v[60:63], v[144:147], v[182:185], v[60:63]
	v_mfma_f32_16x16x32_bf16 v[52:55], v[158:161], v[182:185], v[52:55]
	v_mfma_f32_16x16x32_bf16 v[44:47], v[144:147], v[190:193], v[44:47]
	v_mfma_f32_16x16x32_bf16 v[36:39], v[158:161], v[190:193], v[36:39]
	v_mfma_f32_16x16x32_bf16 v[28:31], v[144:147], v[198:201], v[28:31]
	v_mfma_f32_16x16x32_bf16 v[20:23], v[158:161], v[198:201], v[20:23]
	v_mfma_f32_16x16x32_bf16 v[12:15], v[144:147], v[212:215], v[12:15]
	v_mfma_f32_16x16x32_bf16 v[4:7], v[158:161], v[212:215], v[4:7]
	v_mfma_f32_16x16x32_bf16 v[60:63], v[154:157], v[186:189], v[60:63]
	v_mfma_f32_16x16x32_bf16 v[52:55], v[162:165], v[186:189], v[52:55]
	v_mfma_f32_16x16x32_bf16 v[44:47], v[154:157], v[194:197], v[44:47]
	v_mfma_f32_16x16x32_bf16 v[36:39], v[162:165], v[194:197], v[36:39]
	v_mfma_f32_16x16x32_bf16 v[28:31], v[154:157], v[202:205], v[28:31]
	v_mfma_f32_16x16x32_bf16 v[20:23], v[162:165], v[202:205], v[20:23]
	v_mfma_f32_16x16x32_bf16 v[12:15], v[154:157], v[216:219], v[12:15]
	v_mfma_f32_16x16x32_bf16 v[4:7], v[162:165], v[216:219], v[4:7]
	v_mfma_f32_16x16x32_bf16 v[56:59], v[166:169], v[182:185], v[56:59]
	v_mfma_f32_16x16x32_bf16 v[48:51], v[174:177], v[182:185], v[48:51]
	v_mfma_f32_16x16x32_bf16 v[40:43], v[166:169], v[190:193], v[40:43]
	v_mfma_f32_16x16x32_bf16 v[32:35], v[174:177], v[190:193], v[32:35]
	v_mfma_f32_16x16x32_bf16 v[24:27], v[166:169], v[198:201], v[24:27]
	v_mfma_f32_16x16x32_bf16 v[16:19], v[174:177], v[198:201], v[16:19]
	v_mfma_f32_16x16x32_bf16 v[8:11], v[166:169], v[212:215], v[8:11]
	v_mfma_f32_16x16x32_bf16 v[0:3], v[174:177], v[212:215], v[0:3]
	v_mfma_f32_16x16x32_bf16 v[56:59], v[170:173], v[186:189], v[56:59]
	v_mfma_f32_16x16x32_bf16 v[48:51], v[178:181], v[186:189], v[48:51]
	v_mfma_f32_16x16x32_bf16 v[40:43], v[170:173], v[194:197], v[40:43]
	v_mfma_f32_16x16x32_bf16 v[32:35], v[178:181], v[194:197], v[32:35]
	v_mfma_f32_16x16x32_bf16 v[24:27], v[170:173], v[202:205], v[24:27]
	v_mfma_f32_16x16x32_bf16 v[16:19], v[178:181], v[202:205], v[16:19]
	v_mfma_f32_16x16x32_bf16 v[8:11], v[170:173], v[216:219], v[8:11]
	v_mfma_f32_16x16x32_bf16 v[0:3], v[178:181], v[216:219], v[0:3]
	s_setprio 0
	s_barrier
	s_add_i32 s49, 0, 0x18000
	s_add_i32 s50, 0, 0x1c000
	v_add_u32_e32 v162, s49, v149
	v_add_u32_e32 v178, s50, v149
	ds_read_b128 v[144:147], v162
	ds_read_b128 v[154:157], v162 offset:1024
	ds_read_b128 v[158:161], v162 offset:2048
	ds_read_b128 v[162:165], v162 offset:3072
	ds_read_b128 v[166:169], v178
	ds_read_b128 v[170:173], v178 offset:1024
	ds_read_b128 v[174:177], v178 offset:2048
	ds_read_b128 v[178:181], v178 offset:3072
	s_add_u32 s26, s26, 0x40000
	s_addc_u32 s27, s27, 0
	s_mov_b32 m0, s31
	v_lshl_add_u64 v[226:227], s[26:27], 0, v[134:135]
	ds_read_b128 v[182:185], v153 offset:32768
	ds_read_b128 v[186:189], v153 offset:33792
	ds_read_b128 v[190:193], v153 offset:34816
	ds_read_b128 v[194:197], v153 offset:35840
	ds_read_b128 v[198:201], v153 offset:36864
	ds_read_b128 v[202:205], v153 offset:37888
	ds_read_b128 v[212:215], v153 offset:38912
	ds_read_b128 v[216:219], v153 offset:39936
	global_load_lds_dwordx4 v[226:227], off
	v_lshl_add_u64 v[226:227], s[26:27], 0, v[130:131]
	s_mov_b32 m0, s33
	s_nop 0
	global_load_lds_dwordx4 v[226:227], off
	s_waitcnt vmcnt(8)
	s_waitcnt lgkmcnt(0)
	s_barrier
; #define PG8_STAGE(bufoff, gbase, voff) do { _Pragma("unroll") for (int _i = 0; _i < 2; ++_i) \
;         __builtin_amdgcn_global_load_lds((const unsigned*)((const char*)(gbase) + (voff)[_i]), (PG8_LAS unsigned*)(lds + (bufoff) + ldsw + _i * 8192), 16, 0, 0); } while (0)
; #define PG8_LDA(dst, b, h) do { _Pragma("unroll") for (int m = 0; m < 4; ++m) _Pragma("unroll") for (int k = 0; k < 2; ++k) dst[m][k] = *(const PG8_LAS bf16x8*)(lds + PG8_SA(b, h) + aoff + m * 2048 + k * 1024); } while (0)
; #define PG8_MMA(ai, bj, At, Bt) do { __builtin_amdgcn_s_setprio(1); _Pragma("unroll") for (int m = 0; m < 4; ++m) _Pragma("unroll") for (int n = 0; n < 2; ++n) _Pragma("unroll") for (int k = 0; k < 2; ++k) \
;         acc[ai][bj][m][n] = __builtin_amdgcn_mfma_f32_16x16x32_bf16(Bt[n][k], At[m][k], acc[ai][bj][m][n], 0, 0, 0); __builtin_amdgcn_s_setprio(0); } while (0)
; #define PG8_WAIT_V(n) asm volatile("s_waitcnt vmcnt(" #n ")" ::: "memory")
; #define PG8_WAIT_L(n) asm volatile("s_waitcnt lgkmcnt(" #n ")" ::: "memory")
; #define PG8_BAR __builtin_amdgcn_s_barrier()
; #define PG8_SCHED __builtin_amdgcn_sched_barrier(0)
; template <class Epi, class Sched, bool ALIGN_EPI = false, bool SP2 = false>
; __device__ __forceinline__ void gemm_phase(PG8_LAS unsigned char* lds, const Gemm g, const Sched& S, const Epi& E, const int wid) {
;     ...
;             PG8_WAIT_V(8); PG8_WAIT_L(0); PG8_BAR; PG8_MMA(0, 0, At, B0); PG8_MMA(0, 1, At, B1); PG8_BAR; PG8_SCHED;
;             PG8_LDA(At, 1, 1); PG8_STAGE(PG8_SB(1, 0), b3, voffB); PG8_STAGE(PG8_SB(1, 1), b3 + hstep, voffB); PG8_STAGE(PG8_SA(1, 0), a3, voffA);
;             PG8_WAIT_V(8); PG8_WAIT_L(0); PG8_BAR; PG8_MMA(1, 0, At, B0); PG8_MMA(1, 1, At, B1); PG8_BAR; PG8_SCHED;
	s_setprio 1
	s_waitcnt lgkmcnt(0)
	v_mfma_f32_16x16x32_bf16 v[124:127], v[144:147], v[182:185], v[124:127]
	v_mfma_f32_16x16x32_bf16 v[116:119], v[158:161], v[182:185], v[116:119]
	v_mfma_f32_16x16x32_bf16 v[108:111], v[144:147], v[190:193], v[108:111]
	v_mfma_f32_16x16x32_bf16 v[100:103], v[158:161], v[190:193], v[100:103]
	v_mfma_f32_16x16x32_bf16 v[92:95], v[144:147], v[198:201], v[92:95]
	v_mfma_f32_16x16x32_bf16 v[84:87], v[158:161], v[198:201], v[84:87]
	v_mfma_f32_16x16x32_bf16 v[76:79], v[144:147], v[212:215], v[76:79]
	v_mfma_f32_16x16x32_bf16 v[68:71], v[158:161], v[212:215], v[68:71]
	v_mfma_f32_16x16x32_bf16 v[124:127], v[154:157], v[186:189], v[124:127]
	v_mfma_f32_16x16x32_bf16 v[116:119], v[162:165], v[186:189], v[116:119]
	v_mfma_f32_16x16x32_bf16 v[108:111], v[154:157], v[194:197], v[108:111]
	v_mfma_f32_16x16x32_bf16 v[100:103], v[162:165], v[194:197], v[100:103]
	v_mfma_f32_16x16x32_bf16 v[92:95], v[154:157], v[202:205], v[92:95]
	v_mfma_f32_16x16x32_bf16 v[84:87], v[162:165], v[202:205], v[84:87]
	v_mfma_f32_16x16x32_bf16 v[76:79], v[154:157], v[216:219], v[76:79]
	v_mfma_f32_16x16x32_bf16 v[68:71], v[162:165], v[216:219], v[68:71]
	v_mfma_f32_16x16x32_bf16 v[120:123], v[166:169], v[182:185], v[120:123]
	v_mfma_f32_16x16x32_bf16 v[112:115], v[174:177], v[182:185], v[112:115]
	v_mfma_f32_16x16x32_bf16 v[104:107], v[166:169], v[190:193], v[104:107]
	v_mfma_f32_16x16x32_bf16 v[96:99], v[174:177], v[190:193], v[96:99]
	v_mfma_f32_16x16x32_bf16 v[88:91], v[166:169], v[198:201], v[88:91]
	v_mfma_f32_16x16x32_bf16 v[80:83], v[174:177], v[198:201], v[80:83]
	v_mfma_f32_16x16x32_bf16 v[72:75], v[166:169], v[212:215], v[72:75]
	v_mfma_f32_16x16x32_bf16 v[64:67], v[174:177], v[212:215], v[64:67]
	v_mfma_f32_16x16x32_bf16 v[120:123], v[170:173], v[186:189], v[120:123]
	v_mfma_f32_16x16x32_bf16 v[112:115], v[178:181], v[186:189], v[112:115]
	v_mfma_f32_16x16x32_bf16 v[104:107], v[170:173], v[194:197], v[104:107]
	v_mfma_f32_16x16x32_bf16 v[96:99], v[178:181], v[194:197], v[96:99]
	v_mfma_f32_16x16x32_bf16 v[88:91], v[170:173], v[202:205], v[88:91]
	v_mfma_f32_16x16x32_bf16 v[80:83], v[178:181], v[202:205], v[80:83]
	v_mfma_f32_16x16x32_bf16 v[72:75], v[170:173], v[216:219], v[72:75]
	v_mfma_f32_16x16x32_bf16 v[64:67], v[178:181], v[216:219], v[64:67]
	s_setprio 0
	s_barrier
	s_add_i32 s26, s49, s9
	v_lshl_add_u64 v[206:207], v[206:207], 0, s[6:7]
	s_mov_b32 m0, s26
	ds_read_b128 v[182:185], v153 offset:49152
	ds_read_b128 v[186:189], v153 offset:50176
	ds_read_b128 v[190:193], v153 offset:51200
	ds_read_b128 v[194:197], v153 offset:52224
	ds_read_b128 v[198:201], v153 offset:53248
	ds_read_b128 v[202:205], v153 offset:54272
	ds_read_b128 v[212:215], v153 offset:55296
	ds_read_b128 v[216:219], v153 offset:56320
	global_load_lds_dwordx4 v[206:207], off
	s_add_i32 m0, s26, 0x2000
	s_add_u32 s24, s24, 0x40080
	v_lshl_add_u64 v[206:207], v[220:221], 0, s[6:7]
	s_addc_u32 s25, s25, 0
	s_add_i32 s26, s50, s9
	global_load_lds_dwordx4 v[206:207], off
	v_lshl_add_u64 v[206:207], s[24:25], 0, v[132:133]
	s_mov_b32 m0, s26
	s_nop 0
	global_load_lds_dwordx4 v[206:207], off
	v_lshl_add_u64 v[206:207], s[24:25], 0, v[128:129]
	s_add_i32 m0, s26, 0x2000
	s_nop 0
	global_load_lds_dwordx4 v[206:207], off
	v_lshl_add_u64 v[206:207], v[222:223], 0, s[6:7]
	s_mov_b32 m0, s38
	s_nop 0
	global_load_lds_dwordx4 v[206:207], off
	v_lshl_add_u64 v[206:207], v[224:225], 0, s[6:7]
	s_mov_b32 m0, s39
	s_nop 0
	global_load_lds_dwordx4 v[206:207], off
	s_waitcnt vmcnt(8)
	s_waitcnt lgkmcnt(0)
	s_barrier
	s_setprio 1
	s_waitcnt lgkmcnt(0)
	v_mfma_f32_16x16x32_bf16 v[60:63], v[144:147], v[182:185], v[60:63]
	v_mfma_f32_16x16x32_bf16 v[52:55], v[158:161], v[182:185], v[52:55]
	v_mfma_f32_16x16x32_bf16 v[44:47], v[144:147], v[190:193], v[44:47]
	v_mfma_f32_16x16x32_bf16 v[36:39], v[158:161], v[190:193], v[36:39]
	v_mfma_f32_16x16x32_bf16 v[28:31], v[144:147], v[198:201], v[28:31]
	v_mfma_f32_16x16x32_bf16 v[20:23], v[158:161], v[198:201], v[20:23]
	v_mfma_f32_16x16x32_bf16 v[12:15], v[144:147], v[212:215], v[12:15]
	v_mfma_f32_16x16x32_bf16 v[4:7], v[158:161], v[212:215], v[4:7]
	v_mfma_f32_16x16x32_bf16 v[60:63], v[154:157], v[186:189], v[60:63]
	v_mfma_f32_16x16x32_bf16 v[52:55], v[162:165], v[186:189], v[52:55]
	v_mfma_f32_16x16x32_bf16 v[44:47], v[154:157], v[194:197], v[44:47]
	v_mfma_f32_16x16x32_bf16 v[36:39], v[162:165], v[194:197], v[36:39]
	v_mfma_f32_16x16x32_bf16 v[28:31], v[154:157], v[202:205], v[28:31]
	v_mfma_f32_16x16x32_bf16 v[20:23], v[162:165], v[202:205], v[20:23]
	v_mfma_f32_16x16x32_bf16 v[12:15], v[154:157], v[216:219], v[12:15]
	v_mfma_f32_16x16x32_bf16 v[4:7], v[162:165], v[216:219], v[4:7]
	v_mfma_f32_16x16x32_bf16 v[56:59], v[166:169], v[182:185], v[56:59]
	v_mfma_f32_16x16x32_bf16 v[48:51], v[174:177], v[182:185], v[48:51]
	v_mfma_f32_16x16x32_bf16 v[40:43], v[166:169], v[190:193], v[40:43]
	v_mfma_f32_16x16x32_bf16 v[32:35], v[174:177], v[190:193], v[32:35]
	v_mfma_f32_16x16x32_bf16 v[24:27], v[166:169], v[198:201], v[24:27]
	v_mfma_f32_16x16x32_bf16 v[16:19], v[174:177], v[198:201], v[16:19]
	v_mfma_f32_16x16x32_bf16 v[8:11], v[166:169], v[212:215], v[8:11]
	v_mfma_f32_16x16x32_bf16 v[0:3], v[174:177], v[212:215], v[0:3]
	v_mfma_f32_16x16x32_bf16 v[56:59], v[170:173], v[186:189], v[56:59]
	v_mfma_f32_16x16x32_bf16 v[48:51], v[178:181], v[186:189], v[48:51]
	v_mfma_f32_16x16x32_bf16 v[40:43], v[170:173], v[194:197], v[40:43]
	v_mfma_f32_16x16x32_bf16 v[32:35], v[178:181], v[194:197], v[32:35]
	v_mfma_f32_16x16x32_bf16 v[24:27], v[170:173], v[202:205], v[24:27]
	v_mfma_f32_16x16x32_bf16 v[16:19], v[178:181], v[202:205], v[16:19]
	v_mfma_f32_16x16x32_bf16 v[8:11], v[170:173], v[216:219], v[8:11]
	v_mfma_f32_16x16x32_bf16 v[0:3], v[178:181], v[216:219], v[0:3]
	s_setprio 0
	s_barrier
	s_add_i32 s48, s48, 2
	s_add_u32 s22, s22, 0x100
	s_addc_u32 s23, s23, 0
	s_add_u32 s46, s46, 0x100
	s_addc_u32 s47, s47, 0
	s_cmp_gt_u32 s48, 13
	s_cbranch_scc0 .LBB0_269

; #define PG8_STAGE(bufoff, gbase, voff) do { _Pragma("unroll") for (int _i = 0; _i < 2; ++_i) \
;         __builtin_amdgcn_global_load_lds((const unsigned*)((const char*)(gbase) + (voff)[_i]), (PG8_LAS unsigned*)(lds + (bufoff) + ldsw + _i * 8192), 16, 0, 0); } while (0)
; #define PG8_LDA(dst, b, h) do { _Pragma("unroll") for (int m = 0; m < 4; ++m) _Pragma("unroll") for (int k = 0; k < 2; ++k) dst[m][k] = *(const PG8_LAS bf16x8*)(lds + PG8_SA(b, h) + aoff + m * 2048 + k * 1024); } while (0)
; #define PG8_LDB(dst, b, h) do { _Pragma("unroll") for (int n = 0; n < 2; ++n) _Pragma("unroll") for (int k = 0; k < 2; ++k) dst[n][k] = *(const PG8_LAS bf16x8*)(lds + PG8_SB(b, h) + boff + n * 2048 + k * 1024); } while (0)
; #define PG8_MMA(ai, bj, At, Bt) do { __builtin_amdgcn_s_setprio(1); _Pragma("unroll") for (int m = 0; m < 4; ++m) _Pragma("unroll") for (int n = 0; n < 2; ++n) _Pragma("unroll") for (int k = 0; k < 2; ++k) \
;         acc[ai][bj][m][n] = __builtin_amdgcn_mfma_f32_16x16x32_bf16(Bt[n][k], At[m][k], acc[ai][bj][m][n], 0, 0, 0); __builtin_amdgcn_s_setprio(0); } while (0)
; #define PG8_WAIT_V(n) asm volatile("s_waitcnt vmcnt(" #n ")" ::: "memory")
; #define PG8_WAIT_L(n) asm volatile("s_waitcnt lgkmcnt(" #n ")" ::: "memory")
; #define PG8_BAR __builtin_amdgcn_s_barrier()
; #define PG8_SCHED __builtin_amdgcn_sched_barrier(0)
; template <class Epi, class Sched, bool ALIGN_EPI = false, bool SP2 = false>
; __device__ __forceinline__ void gemm_phase(PG8_LAS unsigned char* lds, const Gemm g, const Sched& S, const Epi& E, const int wid) {
;     ...
;             PG8_LDB(B0, 0, 0); PG8_LDB(B1, 0, 1); PG8_SCHED; PG8_LDA(At, 0, 0); PG8_STAGE(PG8_SA(1, 1), a1 + hstep, voffA);
;             PG8_WAIT_V(8); PG8_WAIT_L(0); PG8_BAR; PG8_MMA(0, 0, At, B0); PG8_MMA(0, 1, At, B1); PG8_BAR; PG8_SCHED;
;             PG8_LDA(At, 0, 1); PG8_STAGE(PG8_SB(0, 0), b2, voffB); PG8_STAGE(PG8_SB(0, 1), b2 + hstep, voffB); PG8_STAGE(PG8_SA(0, 0), a2, voffA);
;             PG8_WAIT_V(8); PG8_WAIT_L(0); PG8_BAR; PG8_MMA(1, 0, At, B0); PG8_MMA(1, 1, At, B1); PG8_BAR; PG8_SCHED;
;             PG8_LDB(B0, 1, 0); PG8_LDB(B1, 1, 1); PG8_SCHED; PG8_LDA(At, 1, 0); PG8_STAGE(PG8_SA(0, 1), a2 + hstep, voffA);
.LBB0_756:
	v_add_u32_e32 v151, s35, v149
	ds_read_b128 v[152:155], v151
	ds_read_b128 v[156:159], v151 offset:1024
	ds_read_b128 v[160:163], v151 offset:2048
	ds_read_b128 v[164:167], v151 offset:3072
	v_add_u32_e32 v151, s38, v149
	s_add_u32 s16, s2, s14
	ds_read_b128 v[168:171], v151
	ds_read_b128 v[172:175], v151 offset:1024
	ds_read_b128 v[176:179], v151 offset:2048
	ds_read_b128 v[180:183], v151 offset:3072
	s_addc_u32 s17, s3, s15
	s_add_u32 s16, s16, 0x100
	s_addc_u32 s17, s17, 0
	s_add_u32 s45, s42, s14
	s_addc_u32 s46, s43, s15
	s_cmpk_eq_i32 s14, 0x1500
	s_cselect_b32 s19, s13, s17
	s_cselect_b32 s18, s12, s16
	s_cselect_b32 s17, s9, s46
	s_cselect_b32 s16, s8, s45
	v_lshl_add_u64 v[206:207], v[144:145], 0, s[14:15]
	s_add_i32 m0, s25, 0xc000
	ds_read_b128 v[184:187], v150
	ds_read_b128 v[188:191], v150 offset:1024
	ds_read_b128 v[194:197], v150 offset:2048
	ds_read_b128 v[198:201], v150 offset:3072
	ds_read_b128 v[202:205], v150 offset:4096
	ds_read_b128 v[212:215], v150 offset:5120
	ds_read_b128 v[216:219], v150 offset:6144
	ds_read_b128 v[220:223], v150 offset:7168
	global_load_lds_dwordx4 v[206:207], off
	v_lshl_add_u64 v[206:207], v[146:147], 0, s[14:15]
	s_add_i32 m0, s25, 0xe000
	s_nop 0
	global_load_lds_dwordx4 v[206:207], off
	s_waitcnt vmcnt(8)
	s_waitcnt lgkmcnt(0)
	s_barrier
	s_setprio 1
	s_waitcnt lgkmcnt(0)
	v_mfma_f32_16x16x32_bf16 v[120:123], v[152:155], v[184:187], v[120:123]
	v_mfma_f32_16x16x32_bf16 v[124:127], v[160:163], v[184:187], v[124:127]
	v_mfma_f32_16x16x32_bf16 v[108:111], v[152:155], v[194:197], v[108:111]
	v_mfma_f32_16x16x32_bf16 v[116:119], v[160:163], v[194:197], v[116:119]
	v_mfma_f32_16x16x32_bf16 v[92:95], v[152:155], v[202:205], v[92:95]
	v_mfma_f32_16x16x32_bf16 v[112:115], v[160:163], v[202:205], v[112:115]
	v_mfma_f32_16x16x32_bf16 v[72:75], v[152:155], v[216:219], v[72:75]
	v_mfma_f32_16x16x32_bf16 v[100:103], v[160:163], v[216:219], v[100:103]
	v_mfma_f32_16x16x32_bf16 v[120:123], v[156:159], v[188:191], v[120:123]
	v_mfma_f32_16x16x32_bf16 v[124:127], v[164:167], v[188:191], v[124:127]
	v_mfma_f32_16x16x32_bf16 v[108:111], v[156:159], v[198:201], v[108:111]
	v_mfma_f32_16x16x32_bf16 v[116:119], v[164:167], v[198:201], v[116:119]
	v_mfma_f32_16x16x32_bf16 v[92:95], v[156:159], v[212:215], v[92:95]
	v_mfma_f32_16x16x32_bf16 v[112:115], v[164:167], v[212:215], v[112:115]
	v_mfma_f32_16x16x32_bf16 v[72:75], v[156:159], v[220:223], v[72:75]
	v_mfma_f32_16x16x32_bf16 v[100:103], v[164:167], v[220:223], v[100:103]
	v_mfma_f32_16x16x32_bf16 v[104:107], v[168:171], v[184:187], v[104:107]
	v_mfma_f32_16x16x32_bf16 v[88:91], v[176:179], v[184:187], v[88:91]
	v_mfma_f32_16x16x32_bf16 v[96:99], v[168:171], v[194:197], v[96:99]
	v_mfma_f32_16x16x32_bf16 v[76:79], v[176:179], v[194:197], v[76:79]
	v_mfma_f32_16x16x32_bf16 v[84:87], v[168:171], v[202:205], v[84:87]
	v_mfma_f32_16x16x32_bf16 v[68:71], v[176:179], v[202:205], v[68:71]
	v_mfma_f32_16x16x32_bf16 v[80:83], v[168:171], v[216:219], v[80:83]
	v_mfma_f32_16x16x32_bf16 v[64:67], v[176:179], v[216:219], v[64:67]
	v_mfma_f32_16x16x32_bf16 v[104:107], v[172:175], v[188:191], v[104:107]
	v_mfma_f32_16x16x32_bf16 v[88:91], v[180:183], v[188:191], v[88:91]
	v_mfma_f32_16x16x32_bf16 v[96:99], v[172:175], v[198:201], v[96:99]
	v_mfma_f32_16x16x32_bf16 v[76:79], v[180:183], v[198:201], v[76:79]
	v_mfma_f32_16x16x32_bf16 v[84:87], v[172:175], v[212:215], v[84:87]
	v_mfma_f32_16x16x32_bf16 v[68:71], v[180:183], v[212:215], v[68:71]
	v_mfma_f32_16x16x32_bf16 v[80:83], v[172:175], v[220:223], v[80:83]
	v_mfma_f32_16x16x32_bf16 v[64:67], v[180:183], v[220:223], v[64:67]
	s_setprio 0
	s_barrier
	s_add_i32 s45, s35, s23
	v_lshl_add_u64 v[206:207], s[16:17], 0, v[132:133]
	s_mov_b32 m0, s45
	ds_read_b128 v[184:187], v150 offset:16384
	ds_read_b128 v[188:191], v150 offset:17408
	ds_read_b128 v[194:197], v150 offset:18432
	ds_read_b128 v[198:201], v150 offset:19456
	ds_read_b128 v[202:205], v150 offset:20480
	ds_read_b128 v[212:215], v150 offset:21504
	ds_read_b128 v[216:219], v150 offset:22528
	ds_read_b128 v[220:223], v150 offset:23552
	global_load_lds_dwordx4 v[206:207], off
	s_add_i32 m0, s45, 0x2000
	s_add_u32 s46, s16, 0xb0000
	v_lshl_add_u64 v[224:225], s[16:17], 0, v[128:129]
	s_addc_u32 s47, s17, 0
	s_add_i32 s45, s38, s23
	global_load_lds_dwordx4 v[224:225], off
	v_lshl_add_u64 v[226:227], s[46:47], 0, v[132:133]
	s_mov_b32 m0, s45
	v_lshl_add_u64 v[228:229], s[18:19], 0, v[130:131]
	global_load_lds_dwordx4 v[226:227], off
	v_lshl_add_u64 v[226:227], s[46:47], 0, v[128:129]
	s_add_i32 m0, s45, 0x2000
	s_nop 0
	global_load_lds_dwordx4 v[226:227], off
	v_lshl_add_u64 v[226:227], s[18:19], 0, v[134:135]
	s_mov_b32 m0, s25
	s_nop 0
	global_load_lds_dwordx4 v[226:227], off
	s_mov_b32 m0, s27
	s_nop 0
	global_load_lds_dwordx4 v[228:229], off
	s_waitcnt vmcnt(8)
	s_waitcnt lgkmcnt(0)
	s_barrier
; #define PG8_STAGE(bufoff, gbase, voff) do { _Pragma("unroll") for (int _i = 0; _i < 2; ++_i) \
;         __builtin_amdgcn_global_load_lds((const unsigned*)((const char*)(gbase) + (voff)[_i]), (PG8_LAS unsigned*)(lds + (bufoff) + ldsw + _i * 8192), 16, 0, 0); } while (0)
; #define PG8_LDA(dst, b, h) do { _Pragma("unroll") for (int m = 0; m < 4; ++m) _Pragma("unroll") for (int k = 0; k < 2; ++k) dst[m][k] = *(const PG8_LAS bf16x8*)(lds + PG8_SA(b, h) + aoff + m * 2048 + k * 1024); } while (0)
; #define PG8_LDB(dst, b, h) do { _Pragma("unroll") for (int n = 0; n < 2; ++n) _Pragma("unroll") for (int k = 0; k < 2; ++k) dst[n][k] = *(const PG8_LAS bf16x8*)(lds + PG8_SB(b, h) + boff + n * 2048 + k * 1024); } while (0)
; #define PG8_MMA(ai, bj, At, Bt) do { __builtin_amdgcn_s_setprio(1); _Pragma("unroll") for (int m = 0; m < 4; ++m) _Pragma("unroll") for (int n = 0; n < 2; ++n) _Pragma("unroll") for (int k = 0; k < 2; ++k) \
;         acc[ai][bj][m][n] = __builtin_amdgcn_mfma_f32_16x16x32_bf16(Bt[n][k], At[m][k], acc[ai][bj][m][n], 0, 0, 0); __builtin_amdgcn_s_setprio(0); } while (0)
; #define PG8_WAIT_V(n) asm volatile("s_waitcnt vmcnt(" #n ")" ::: "memory")
; #define PG8_WAIT_L(n) asm volatile("s_waitcnt lgkmcnt(" #n ")" ::: "memory")
; #define PG8_BAR __builtin_amdgcn_s_barrier()
; #define PG8_SCHED __builtin_amdgcn_sched_barrier(0)
; template <class Epi, class Sched, bool ALIGN_EPI = false, bool SP2 = false>
; __device__ __forceinline__ void gemm_phase(PG8_LAS unsigned char* lds, const Gemm g, const Sched& S, const Epi& E, const int wid) {
;     ...
;             PG8_WAIT_V(8); PG8_WAIT_L(0); PG8_BAR; PG8_MMA(1, 0, At, B0); PG8_MMA(1, 1, At, B1); PG8_BAR; PG8_SCHED;
;             PG8_LDB(B0, 1, 0); PG8_LDB(B1, 1, 1); PG8_SCHED; PG8_LDA(At, 1, 0); PG8_STAGE(PG8_SA(0, 1), a2 + hstep, voffA);
;             PG8_WAIT_V(8); PG8_WAIT_L(0); PG8_BAR; PG8_MMA(0, 0, At, B0); PG8_MMA(0, 1, At, B1); PG8_BAR; PG8_SCHED;
	s_setprio 1
	s_waitcnt lgkmcnt(0)
	v_mfma_f32_16x16x32_bf16 v[60:63], v[152:155], v[184:187], v[60:63]
	v_mfma_f32_16x16x32_bf16 v[56:59], v[160:163], v[184:187], v[56:59]
	v_mfma_f32_16x16x32_bf16 v[44:47], v[152:155], v[194:197], v[44:47]
	v_mfma_f32_16x16x32_bf16 v[40:43], v[160:163], v[194:197], v[40:43]
	v_mfma_f32_16x16x32_bf16 v[28:31], v[152:155], v[202:205], v[28:31]
	v_mfma_f32_16x16x32_bf16 v[24:27], v[160:163], v[202:205], v[24:27]
	v_mfma_f32_16x16x32_bf16 v[4:7], v[152:155], v[216:219], v[4:7]
	v_mfma_f32_16x16x32_bf16 v[12:15], v[160:163], v[216:219], v[12:15]
	v_mfma_f32_16x16x32_bf16 v[60:63], v[156:159], v[188:191], v[60:63]
	v_mfma_f32_16x16x32_bf16 v[56:59], v[164:167], v[188:191], v[56:59]
	v_mfma_f32_16x16x32_bf16 v[44:47], v[156:159], v[198:201], v[44:47]
	v_mfma_f32_16x16x32_bf16 v[40:43], v[164:167], v[198:201], v[40:43]
	v_mfma_f32_16x16x32_bf16 v[28:31], v[156:159], v[212:215], v[28:31]
	v_mfma_f32_16x16x32_bf16 v[24:27], v[164:167], v[212:215], v[24:27]
	v_mfma_f32_16x16x32_bf16 v[4:7], v[156:159], v[220:223], v[4:7]
	v_mfma_f32_16x16x32_bf16 v[12:15], v[164:167], v[220:223], v[12:15]
	v_mfma_f32_16x16x32_bf16 v[52:55], v[168:171], v[184:187], v[52:55]
	v_mfma_f32_16x16x32_bf16 v[48:51], v[176:179], v[184:187], v[48:51]
	v_mfma_f32_16x16x32_bf16 v[36:39], v[168:171], v[194:197], v[36:39]
	v_mfma_f32_16x16x32_bf16 v[32:35], v[176:179], v[194:197], v[32:35]
	v_mfma_f32_16x16x32_bf16 v[20:23], v[168:171], v[202:205], v[20:23]
	v_mfma_f32_16x16x32_bf16 v[16:19], v[176:179], v[202:205], v[16:19]
	v_mfma_f32_16x16x32_bf16 v[8:11], v[168:171], v[216:219], v[8:11]
	v_mfma_f32_16x16x32_bf16 v[0:3], v[176:179], v[216:219], v[0:3]
	v_mfma_f32_16x16x32_bf16 v[52:55], v[172:175], v[188:191], v[52:55]
	v_mfma_f32_16x16x32_bf16 v[48:51], v[180:183], v[188:191], v[48:51]
	v_mfma_f32_16x16x32_bf16 v[36:39], v[172:175], v[198:201], v[36:39]
	v_mfma_f32_16x16x32_bf16 v[32:35], v[180:183], v[198:201], v[32:35]
	v_mfma_f32_16x16x32_bf16 v[20:23], v[172:175], v[212:215], v[20:23]
	v_mfma_f32_16x16x32_bf16 v[16:19], v[180:183], v[212:215], v[16:19]
	v_mfma_f32_16x16x32_bf16 v[8:11], v[172:175], v[220:223], v[8:11]
	v_mfma_f32_16x16x32_bf16 v[0:3], v[180:183], v[220:223], v[0:3]
	s_setprio 0
	s_barrier
	s_add_i32 s45, 0, 0x18000
	v_add_u32_e32 v151, s45, v149
	s_add_i32 s46, 0, 0x1c000
	ds_read_b128 v[152:155], v151
	ds_read_b128 v[156:159], v151 offset:1024
	ds_read_b128 v[160:163], v151 offset:2048
	ds_read_b128 v[164:167], v151 offset:3072
	v_add_u32_e32 v151, s46, v149
	ds_read_b128 v[168:171], v151
	ds_read_b128 v[172:175], v151 offset:1024
	ds_read_b128 v[176:179], v151 offset:2048
	ds_read_b128 v[180:183], v151 offset:3072
	s_add_u32 s18, s18, 0xb0000
	s_addc_u32 s19, s19, 0
	s_mov_b32 m0, s28
	v_lshl_add_u64 v[230:231], s[18:19], 0, v[134:135]
	ds_read_b128 v[184:187], v150 offset:32768
	ds_read_b128 v[188:191], v150 offset:33792
	ds_read_b128 v[194:197], v150 offset:34816
	ds_read_b128 v[198:201], v150 offset:35840
	ds_read_b128 v[202:205], v150 offset:36864
	ds_read_b128 v[212:215], v150 offset:37888
	ds_read_b128 v[216:219], v150 offset:38912
	ds_read_b128 v[220:223], v150 offset:39936
	global_load_lds_dwordx4 v[230:231], off
	v_lshl_add_u64 v[230:231], s[18:19], 0, v[130:131]
	s_mov_b32 m0, s29
	s_nop 0
	global_load_lds_dwordx4 v[230:231], off
	s_waitcnt vmcnt(8)
	s_waitcnt lgkmcnt(0)
	s_barrier
	s_setprio 1
	s_waitcnt lgkmcnt(0)
	v_mfma_f32_16x16x32_bf16 v[120:123], v[152:155], v[184:187], v[120:123]
	v_mfma_f32_16x16x32_bf16 v[124:127], v[160:163], v[184:187], v[124:127]
	v_mfma_f32_16x16x32_bf16 v[108:111], v[152:155], v[194:197], v[108:111]
	v_mfma_f32_16x16x32_bf16 v[116:119], v[160:163], v[194:197], v[116:119]
	v_mfma_f32_16x16x32_bf16 v[92:95], v[152:155], v[202:205], v[92:95]
	v_mfma_f32_16x16x32_bf16 v[112:115], v[160:163], v[202:205], v[112:115]
	v_mfma_f32_16x16x32_bf16 v[72:75], v[152:155], v[216:219], v[72:75]
	v_mfma_f32_16x16x32_bf16 v[100:103], v[160:163], v[216:219], v[100:103]
	v_mfma_f32_16x16x32_bf16 v[120:123], v[156:159], v[188:191], v[120:123]
	v_mfma_f32_16x16x32_bf16 v[124:127], v[164:167], v[188:191], v[124:127]
	v_mfma_f32_16x16x32_bf16 v[108:111], v[156:159], v[198:201], v[108:111]
	v_mfma_f32_16x16x32_bf16 v[116:119], v[164:167], v[198:201], v[116:119]
	v_mfma_f32_16x16x32_bf16 v[92:95], v[156:159], v[212:215], v[92:95]
	v_mfma_f32_16x16x32_bf16 v[112:115], v[164:167], v[212:215], v[112:115]
	v_mfma_f32_16x16x32_bf16 v[72:75], v[156:159], v[220:223], v[72:75]
	v_mfma_f32_16x16x32_bf16 v[100:103], v[164:167], v[220:223], v[100:103]
	v_mfma_f32_16x16x32_bf16 v[104:107], v[168:171], v[184:187], v[104:107]
	v_mfma_f32_16x16x32_bf16 v[88:91], v[176:179], v[184:187], v[88:91]
	v_mfma_f32_16x16x32_bf16 v[96:99], v[168:171], v[194:197], v[96:99]
	v_mfma_f32_16x16x32_bf16 v[76:79], v[176:179], v[194:197], v[76:79]
	v_mfma_f32_16x16x32_bf16 v[84:87], v[168:171], v[202:205], v[84:87]
	v_mfma_f32_16x16x32_bf16 v[68:71], v[176:179], v[202:205], v[68:71]
	v_mfma_f32_16x16x32_bf16 v[80:83], v[168:171], v[216:219], v[80:83]
	v_mfma_f32_16x16x32_bf16 v[64:67], v[176:179], v[216:219], v[64:67]
	v_mfma_f32_16x16x32_bf16 v[104:107], v[172:175], v[188:191], v[104:107]
	v_mfma_f32_16x16x32_bf16 v[88:91], v[180:183], v[188:191], v[88:91]
	v_mfma_f32_16x16x32_bf16 v[96:99], v[172:175], v[198:201], v[96:99]
	v_mfma_f32_16x16x32_bf16 v[76:79], v[180:183], v[198:201], v[76:79]
	v_mfma_f32_16x16x32_bf16 v[84:87], v[172:175], v[212:215], v[84:87]
	v_mfma_f32_16x16x32_bf16 v[68:71], v[180:183], v[212:215], v[68:71]
	v_mfma_f32_16x16x32_bf16 v[80:83], v[172:175], v[220:223], v[80:83]
	v_mfma_f32_16x16x32_bf16 v[64:67], v[180:183], v[220:223], v[64:67]
	s_setprio 0
	s_barrier
; #define PG8_STAGE(bufoff, gbase, voff) do { _Pragma("unroll") for (int _i = 0; _i < 2; ++_i) \
;         __builtin_amdgcn_global_load_lds((const unsigned*)((const char*)(gbase) + (voff)[_i]), (PG8_LAS unsigned*)(lds + (bufoff) + ldsw + _i * 8192), 16, 0, 0); } while (0)
; #define PG8_LDA(dst, b, h) do { _Pragma("unroll") for (int m = 0; m < 4; ++m) _Pragma("unroll") for (int k = 0; k < 2; ++k) dst[m][k] = *(const PG8_LAS bf16x8*)(lds + PG8_SA(b, h) + aoff + m * 2048 + k * 1024); } while (0)
; #define PG8_MMA(ai, bj, At, Bt) do { __builtin_amdgcn_s_setprio(1); _Pragma("unroll") for (int m = 0; m < 4; ++m) _Pragma("unroll") for (int n = 0; n < 2; ++n) _Pragma("unroll") for (int k = 0; k < 2; ++k) \
;         acc[ai][bj][m][n] = __builtin_amdgcn_mfma_f32_16x16x32_bf16(Bt[n][k], At[m][k], acc[ai][bj][m][n], 0, 0, 0); __builtin_amdgcn_s_setprio(0); } while (0)
; #define PG8_WAIT_V(n) asm volatile("s_waitcnt vmcnt(" #n ")" ::: "memory")
; #define PG8_WAIT_L(n) asm volatile("s_waitcnt lgkmcnt(" #n ")" ::: "memory")
; #define PG8_BAR __builtin_amdgcn_s_barrier()
; #define PG8_SCHED __builtin_amdgcn_sched_barrier(0)
; template <class Epi, class Sched, bool ALIGN_EPI = false, bool SP2 = false>
; __device__ __forceinline__ void gemm_phase(PG8_LAS unsigned char* lds, const Gemm g, const Sched& S, const Epi& E, const int wid) {
;     ...
;             PG8_LDA(At, 1, 1); PG8_STAGE(PG8_SB(1, 0), b3, voffB); PG8_STAGE(PG8_SB(1, 1), b3 + hstep, voffB); PG8_STAGE(PG8_SA(1, 0), a3, voffA);
;             PG8_WAIT_V(8); PG8_WAIT_L(0); PG8_BAR; PG8_MMA(1, 0, At, B0); PG8_MMA(1, 1, At, B1); PG8_BAR; PG8_SCHED;
;     ...
;         if (!has_next) break;
; #pragma unroll
;         for (int a = 0; a < 2; ++a)
; #pragma unroll
;             for (int b = 0; b < 2; ++b)
; #pragma unroll
;                 for (int m = 0; m < 4; ++m)
; #pragma unroll
;                     for (int n = 0; n < 2; ++n) acc[a][b][m][n] = (f32x4){0.f, 0.f, 0.f, 0.f};
;         cur = nxt; cA = nA; cB = nB; ++ui;
	s_add_i32 s18, s45, s23
	v_lshl_add_u64 v[206:207], v[206:207], 0, s[10:11]
	s_mov_b32 m0, s18
	ds_read_b128 v[184:187], v150 offset:49152
	ds_read_b128 v[188:191], v150 offset:50176
	ds_read_b128 v[194:197], v150 offset:51200
	ds_read_b128 v[198:201], v150 offset:52224
	ds_read_b128 v[202:205], v150 offset:53248
	ds_read_b128 v[212:215], v150 offset:54272
	ds_read_b128 v[216:219], v150 offset:55296
	ds_read_b128 v[220:223], v150 offset:56320
	global_load_lds_dwordx4 v[206:207], off
	s_add_i32 m0, s18, 0x2000
	s_add_u32 s16, s16, 0xb0080
	v_lshl_add_u64 v[206:207], v[224:225], 0, s[10:11]
	s_addc_u32 s17, s17, 0
	s_add_i32 s18, s46, s23
	global_load_lds_dwordx4 v[206:207], off
	v_lshl_add_u64 v[206:207], s[16:17], 0, v[132:133]
	s_mov_b32 m0, s18
	s_nop 0
	global_load_lds_dwordx4 v[206:207], off
	v_lshl_add_u64 v[206:207], s[16:17], 0, v[128:129]
	s_add_i32 m0, s18, 0x2000
	s_nop 0
	global_load_lds_dwordx4 v[206:207], off
	v_lshl_add_u64 v[206:207], v[226:227], 0, s[10:11]
	s_mov_b32 m0, s31
	s_nop 0
	global_load_lds_dwordx4 v[206:207], off
	v_lshl_add_u64 v[206:207], v[228:229], 0, s[10:11]
	s_mov_b32 m0, s33
	s_nop 0
	global_load_lds_dwordx4 v[206:207], off
	s_waitcnt vmcnt(8)
	s_waitcnt lgkmcnt(0)
	s_barrier
	s_setprio 1
	s_waitcnt lgkmcnt(0)
	v_mfma_f32_16x16x32_bf16 v[60:63], v[152:155], v[184:187], v[60:63]
	v_mfma_f32_16x16x32_bf16 v[56:59], v[160:163], v[184:187], v[56:59]
	v_mfma_f32_16x16x32_bf16 v[44:47], v[152:155], v[194:197], v[44:47]
	v_mfma_f32_16x16x32_bf16 v[40:43], v[160:163], v[194:197], v[40:43]
	v_mfma_f32_16x16x32_bf16 v[28:31], v[152:155], v[202:205], v[28:31]
	v_mfma_f32_16x16x32_bf16 v[24:27], v[160:163], v[202:205], v[24:27]
	v_mfma_f32_16x16x32_bf16 v[4:7], v[152:155], v[216:219], v[4:7]
	v_mfma_f32_16x16x32_bf16 v[12:15], v[160:163], v[216:219], v[12:15]
	v_mfma_f32_16x16x32_bf16 v[60:63], v[156:159], v[188:191], v[60:63]
	v_mfma_f32_16x16x32_bf16 v[56:59], v[164:167], v[188:191], v[56:59]
	v_mfma_f32_16x16x32_bf16 v[44:47], v[156:159], v[198:201], v[44:47]
	v_mfma_f32_16x16x32_bf16 v[40:43], v[164:167], v[198:201], v[40:43]
	v_mfma_f32_16x16x32_bf16 v[28:31], v[156:159], v[212:215], v[28:31]
	v_mfma_f32_16x16x32_bf16 v[24:27], v[164:167], v[212:215], v[24:27]
	v_mfma_f32_16x16x32_bf16 v[4:7], v[156:159], v[220:223], v[4:7]
	v_mfma_f32_16x16x32_bf16 v[12:15], v[164:167], v[220:223], v[12:15]
	v_mfma_f32_16x16x32_bf16 v[52:55], v[168:171], v[184:187], v[52:55]
	v_mfma_f32_16x16x32_bf16 v[48:51], v[176:179], v[184:187], v[48:51]
	v_mfma_f32_16x16x32_bf16 v[36:39], v[168:171], v[194:197], v[36:39]
	v_mfma_f32_16x16x32_bf16 v[32:35], v[176:179], v[194:197], v[32:35]
	v_mfma_f32_16x16x32_bf16 v[20:23], v[168:171], v[202:205], v[20:23]
	v_mfma_f32_16x16x32_bf16 v[16:19], v[176:179], v[202:205], v[16:19]
	v_mfma_f32_16x16x32_bf16 v[8:11], v[168:171], v[216:219], v[8:11]
	v_mfma_f32_16x16x32_bf16 v[0:3], v[176:179], v[216:219], v[0:3]
	v_mfma_f32_16x16x32_bf16 v[52:55], v[172:175], v[188:191], v[52:55]
	v_mfma_f32_16x16x32_bf16 v[48:51], v[180:183], v[188:191], v[48:51]
	v_mfma_f32_16x16x32_bf16 v[36:39], v[172:175], v[198:201], v[36:39]
	v_mfma_f32_16x16x32_bf16 v[32:35], v[180:183], v[198:201], v[32:35]
	v_mfma_f32_16x16x32_bf16 v[20:23], v[172:175], v[212:215], v[20:23]
	v_mfma_f32_16x16x32_bf16 v[16:19], v[180:183], v[212:215], v[16:19]
	v_mfma_f32_16x16x32_bf16 v[8:11], v[172:175], v[220:223], v[8:11]
	v_mfma_f32_16x16x32_bf16 v[0:3], v[180:183], v[220:223], v[0:3]
	s_setprio 0
	s_barrier
	s_add_i32 s44, s44, 2
	s_add_u32 s14, s14, 0x100
	s_addc_u32 s15, s15, 0
	s_cmp_gt_u32 s44, 41
	s_cbranch_scc0 .LBB0_756
	s_add_u32 s14, s42, 0xffffff00
	s_addc_u32 s15, s43, -1
	s_and_b64 vcc, exec, s[6:7]
	s_cbranch_vccnz .LBB0_743
	v_mov_b32_e32 v0, 0
	s_mov_b32 s0, s39
	s_mov_b32 s20, s40
	s_mov_b64 s[2:3], s[12:13]
	s_mov_b32 s34, s41
	v_mov_b32_e32 v1, v0
	v_mov_b32_e32 v2, v0
	v_mov_b32_e32 v3, v0
	v_mov_b32_e32 v8, v0
	v_mov_b32_e32 v9, v0
	v_mov_b32_e32 v10, v0
	v_mov_b32_e32 v11, v0
	v_mov_b32_e32 v16, v0
	v_mov_b32_e32 v17, v0
	v_mov_b32_e32 v18, v0
	v_mov_b32_e32 v19, v0
	v_mov_b32_e32 v20, v0
	v_mov_b32_e32 v21, v0
	v_mov_b32_e32 v22, v0
	v_mov_b32_e32 v23, v0
	v_mov_b32_e32 v32, v0
	v_mov_b32_e32 v33, v0
	v_mov_b32_e32 v34, v0
	v_mov_b32_e32 v35, v0
	v_mov_b32_e32 v36, v0
	v_mov_b32_e32 v37, v0
	v_mov_b32_e32 v38, v0
	v_mov_b32_e32 v39, v0
	v_mov_b32_e32 v48, v0
	v_mov_b32_e32 v49, v0
	v_mov_b32_e32 v50, v0
	v_mov_b32_e32 v51, v0
	v_mov_b32_e32 v52, v0
	v_mov_b32_e32 v53, v0
	v_mov_b32_e32 v54, v0
	v_mov_b32_e32 v55, v0
	v_mov_b32_e32 v12, v0
	v_mov_b32_e32 v13, v0
	v_mov_b32_e32 v14, v0
	v_mov_b32_e32 v15, v0
	v_mov_b32_e32 v4, v0
	v_mov_b32_e32 v5, v0
	v_mov_b32_e32 v6, v0
	v_mov_b32_e32 v7, v0
	v_mov_b32_e32 v24, v0
	v_mov_b32_e32 v25, v0
	v_mov_b32_e32 v26, v0
	v_mov_b32_e32 v27, v0
	v_mov_b32_e32 v28, v0
	v_mov_b32_e32 v29, v0
	v_mov_b32_e32 v30, v0
	v_mov_b32_e32 v31, v0
	v_mov_b32_e32 v40, v0
	v_mov_b32_e32 v41, v0
	v_mov_b32_e32 v42, v0
	v_mov_b32_e32 v43, v0
	v_mov_b32_e32 v44, v0
	v_mov_b32_e32 v45, v0
	v_mov_b32_e32 v46, v0
	v_mov_b32_e32 v47, v0
	v_mov_b32_e32 v56, v0
	v_mov_b32_e32 v57, v0
	v_mov_b32_e32 v58, v0
	v_mov_b32_e32 v59, v0
	v_mov_b32_e32 v60, v0
	v_mov_b32_e32 v61, v0
	v_mov_b32_e32 v62, v0
	v_mov_b32_e32 v63, v0
	v_mov_b32_e32 v64, v0
	v_mov_b32_e32 v65, v0
	v_mov_b32_e32 v66, v0
	v_mov_b32_e32 v67, v0
	v_mov_b32_e32 v80, v0
	v_mov_b32_e32 v81, v0
	v_mov_b32_e32 v82, v0
	v_mov_b32_e32 v83, v0
	v_mov_b32_e32 v68, v0
	v_mov_b32_e32 v69, v0
	v_mov_b32_e32 v70, v0
	v_mov_b32_e32 v71, v0
	v_mov_b32_e32 v84, v0
	v_mov_b32_e32 v85, v0
	v_mov_b32_e32 v86, v0
	v_mov_b32_e32 v87, v0
	v_mov_b32_e32 v76, v0
	v_mov_b32_e32 v77, v0
	v_mov_b32_e32 v78, v0
	v_mov_b32_e32 v79, v0
	v_mov_b32_e32 v96, v0
	v_mov_b32_e32 v97, v0
	v_mov_b32_e32 v98, v0
	v_mov_b32_e32 v99, v0
	v_mov_b32_e32 v88, v0
	v_mov_b32_e32 v89, v0
	v_mov_b32_e32 v90, v0
	v_mov_b32_e32 v91, v0
	v_mov_b32_e32 v104, v0
	v_mov_b32_e32 v105, v0
	v_mov_b32_e32 v106, v0
	v_mov_b32_e32 v107, v0
	v_mov_b32_e32 v100, v0
	v_mov_b32_e32 v101, v0
	v_mov_b32_e32 v102, v0
	v_mov_b32_e32 v103, v0
	v_mov_b32_e32 v72, v0
	v_mov_b32_e32 v73, v0
	v_mov_b32_e32 v74, v0
	v_mov_b32_e32 v75, v0
	v_mov_b32_e32 v112, v0
	v_mov_b32_e32 v113, v0
	v_mov_b32_e32 v114, v0
	v_mov_b32_e32 v115, v0
	v_mov_b32_e32 v92, v0
	v_mov_b32_e32 v93, v0
	v_mov_b32_e32 v94, v0
	v_mov_b32_e32 v95, v0
	v_mov_b32_e32 v116, v0
	v_mov_b32_e32 v117, v0
	v_mov_b32_e32 v118, v0
	v_mov_b32_e32 v119, v0
	v_mov_b32_e32 v108, v0
	v_mov_b32_e32 v109, v0
	v_mov_b32_e32 v110, v0
	v_mov_b32_e32 v111, v0
	v_mov_b32_e32 v124, v0
	v_mov_b32_e32 v125, v0
	v_mov_b32_e32 v126, v0
	v_mov_b32_e32 v127, v0
	v_mov_b32_e32 v120, v0
	v_mov_b32_e32 v121, v0
	v_mov_b32_e32 v122, v0
	v_mov_b32_e32 v123, v0
	s_andn2_b64 vcc, exec, s[4:5]
	s_cbranch_vccnz .LBB0_744

; template <class Epi, class Sched, bool ALIGN_EPI = false, bool SP2 = false>
; __device__ __forceinline__ void gemm_phase(PG8_LAS unsigned char* lds, const Gemm g, const Sched& S, const Epi& E, const int wid) {
;     ...
;         const bool has_next = S.next(ui + 1, nxt);
;         const char* nA = has_next ? (const char*)g.A + (size_t)nxt.pm * tstep : cA; const char* nB = has_next ? (const char*)g.Bt + (size_t)nxt.pn * tstep : cB;
;         for (int t = 0; t < nt; t += 2) {
;             const bool last = (t == nt - 2);
;             const char* a1 = cA + (size_t)(t + 1) * kstep;
;             const char* a2 = last ? nA : cA + (size_t)(t + 2) * kstep; const char* b2 = last ? nB : cB + (size_t)(t + 2) * kstep;
;             const char* a3 = a2 + kstep; const char* b3 = b2 + kstep;
.LBB0_881:
	s_ashr_i32 s13, s12, 31
	s_lshl_b64 s[14:15], s[12:13], 19
	s_add_u32 s14, s80, s14
	s_addc_u32 s15, s81, s15
	s_and_b64 s[18:19], s[4:5], exec
	s_cselect_b32 s13, s15, s21
	s_cselect_b32 s43, s14, s20
	s_ashr_i32 s9, s8, 31
	s_lshl_b64 s[18:19], s[8:9], 19
	s_add_u32 s18, s10, s18
	s_addc_u32 s19, s11, s19
	s_and_b64 s[24:25], s[4:5], exec
	s_cselect_b32 s9, s19, s23
	s_cselect_b32 s44, s18, s22
	s_add_u32 s20, s20, 0x40080
	s_addc_u32 s21, s21, 0
	s_add_u32 s45, s22, 0x100

; template <class Epi, class Sched, bool ALIGN_EPI = false, bool SP2 = false>
; __device__ __forceinline__ void gemm_phase(PG8_LAS unsigned char* lds, const Gemm g, const Sched& S, const Epi& E, const int wid) {
;     ...
;         for (int t = 0; t < nt; t += 2) {
;             const bool last = (t == nt - 2);
	s_addc_u32 s46, s23, 0
	s_mov_b32 s47, -2


; #define PG8_STAGE(bufoff, gbase, voff) do { _Pragma("unroll") for (int _i = 0; _i < 2; ++_i) \
;         __builtin_amdgcn_global_load_lds((const unsigned*)((const char*)(gbase) + (voff)[_i]), (PG8_LAS unsigned*)(lds + (bufoff) + ldsw + _i * 8192), 16, 0, 0); } while (0)
; #define PG8_LDA(dst, b, h) do { _Pragma("unroll") for (int m = 0; m < 4; ++m) _Pragma("unroll") for (int k = 0; k < 2; ++k) dst[m][k] = *(const PG8_LAS bf16x8*)(lds + PG8_SA(b, h) + aoff + m * 2048 + k * 1024); } while (0)
; #define PG8_LDB(dst, b, h) do { _Pragma("unroll") for (int n = 0; n < 2; ++n) _Pragma("unroll") for (int k = 0; k < 2; ++k) dst[n][k] = *(const PG8_LAS bf16x8*)(lds + PG8_SB(b, h) + boff + n * 2048 + k * 1024); } while (0)
; #define PG8_MMA(ai, bj, At, Bt) do { __builtin_amdgcn_s_setprio(1); _Pragma("unroll") for (int m = 0; m < 4; ++m) _Pragma("unroll") for (int n = 0; n < 2; ++n) _Pragma("unroll") for (int k = 0; k < 2; ++k) \
;         acc[ai][bj][m][n] = __builtin_amdgcn_mfma_f32_16x16x32_bf16(Bt[n][k], At[m][k], acc[ai][bj][m][n], 0, 0, 0); __builtin_amdgcn_s_setprio(0); } while (0)
; #define PG8_WAIT_V(n) asm volatile("s_waitcnt vmcnt(" #n ")" ::: "memory")
; #define PG8_WAIT_L(n) asm volatile("s_waitcnt lgkmcnt(" #n ")" ::: "memory")
; #define PG8_BAR __builtin_amdgcn_s_barrier()
; #define PG8_SCHED __builtin_amdgcn_sched_barrier(0)
; template <class Epi, class Sched, bool ALIGN_EPI = false, bool SP2 = false>
; __device__ __forceinline__ void gemm_phase(PG8_LAS unsigned char* lds, const Gemm g, const Sched& S, const Epi& E, const int wid) {
;     ...
;             PG8_LDB(B0, 0, 0); PG8_LDB(B1, 0, 1); PG8_SCHED; PG8_LDA(At, 0, 0); PG8_STAGE(PG8_SA(1, 1), a1 + hstep, voffA);
;             PG8_WAIT_V(8); PG8_WAIT_L(0); PG8_BAR; PG8_MMA(0, 0, At, B0); PG8_MMA(0, 1, At, B1); PG8_BAR; PG8_SCHED;
;             PG8_LDA(At, 0, 1); PG8_STAGE(PG8_SB(0, 0), b2, voffB); PG8_STAGE(PG8_SB(0, 1), b2 + hstep, voffB); PG8_STAGE(PG8_SA(0, 0), a2, voffA);
;             PG8_WAIT_V(8); PG8_WAIT_L(0); PG8_BAR; PG8_MMA(1, 0, At, B0); PG8_MMA(1, 1, At, B1); PG8_BAR; PG8_SCHED;
	ds_read_b128 v[152:155], v149
	ds_read_b128 v[156:159], v149 offset:1024
	ds_read_b128 v[160:163], v149 offset:2048
	ds_read_b128 v[164:167], v149 offset:3072
	ds_read_b128 v[168:171], v150
	ds_read_b128 v[172:175], v150 offset:1024
	ds_read_b128 v[176:179], v150 offset:2048
	ds_read_b128 v[180:183], v150 offset:3072
	s_add_u32 s22, s20, 0xfffc0080
	s_addc_u32 s23, s21, -1
	s_cmp_eq_u32 s47, 12
	s_cselect_b32 s25, s13, s23
	s_cselect_b32 s24, s43, s22
	s_cselect_b32 s23, s9, s46
	s_cselect_b32 s22, s44, s45
	v_lshl_add_u64 v[144:145], s[20:21], 0, v[136:137]
	s_add_i32 m0, s17, 0xc000
	ds_read_b128 v[184:187], v151
	ds_read_b128 v[188:191], v151 offset:1024
	ds_read_b128 v[192:195], v151 offset:2048
	ds_read_b128 v[196:199], v151 offset:3072
	ds_read_b128 v[200:203], v151 offset:4096
	ds_read_b128 v[204:207], v151 offset:5120
	ds_read_b128 v[212:215], v151 offset:6144
	ds_read_b128 v[216:219], v151 offset:7168
	global_load_lds_dwordx4 v[144:145], off
	v_lshl_add_u64 v[144:145], s[20:21], 0, v[138:139]
	s_add_i32 m0, s17, 0xe000
	s_nop 0
	global_load_lds_dwordx4 v[144:145], off
	s_waitcnt vmcnt(8)
	s_waitcnt lgkmcnt(0)
	s_barrier
	s_setprio 1
	s_waitcnt lgkmcnt(0)
	v_mfma_f32_16x16x32_bf16 v[124:127], v[152:155], v[184:187], 0
	v_mfma_f32_16x16x32_bf16 v[120:123], v[160:163], v[184:187], 0
	v_mfma_f32_16x16x32_bf16 v[116:119], v[152:155], v[192:195], 0
	v_mfma_f32_16x16x32_bf16 v[108:111], v[160:163], v[192:195], 0
	v_mfma_f32_16x16x32_bf16 v[100:103], v[152:155], v[200:203], 0
	v_mfma_f32_16x16x32_bf16 v[92:95], v[160:163], v[200:203], 0
	v_mfma_f32_16x16x32_bf16 v[84:87], v[152:155], v[212:215], 0
	v_mfma_f32_16x16x32_bf16 v[76:79], v[160:163], v[212:215], 0
	v_mfma_f32_16x16x32_bf16 v[124:127], v[156:159], v[188:191], v[124:127]
	v_mfma_f32_16x16x32_bf16 v[120:123], v[164:167], v[188:191], v[120:123]
	v_mfma_f32_16x16x32_bf16 v[116:119], v[156:159], v[196:199], v[116:119]
	v_mfma_f32_16x16x32_bf16 v[108:111], v[164:167], v[196:199], v[108:111]
	v_mfma_f32_16x16x32_bf16 v[100:103], v[156:159], v[204:207], v[100:103]
	v_mfma_f32_16x16x32_bf16 v[92:95], v[164:167], v[204:207], v[92:95]
	v_mfma_f32_16x16x32_bf16 v[84:87], v[156:159], v[216:219], v[84:87]
	v_mfma_f32_16x16x32_bf16 v[76:79], v[164:167], v[216:219], v[76:79]
	v_mfma_f32_16x16x32_bf16 v[112:115], v[168:171], v[184:187], 0
	v_mfma_f32_16x16x32_bf16 v[104:107], v[176:179], v[184:187], 0
	v_mfma_f32_16x16x32_bf16 v[96:99], v[168:171], v[192:195], 0
	v_mfma_f32_16x16x32_bf16 v[88:91], v[176:179], v[192:195], 0
	v_mfma_f32_16x16x32_bf16 v[80:83], v[168:171], v[200:203], 0
	v_mfma_f32_16x16x32_bf16 v[72:75], v[176:179], v[200:203], 0
	v_mfma_f32_16x16x32_bf16 v[68:71], v[168:171], v[212:215], 0
	v_mfma_f32_16x16x32_bf16 v[64:67], v[176:179], v[212:215], 0
	v_mfma_f32_16x16x32_bf16 v[112:115], v[172:175], v[188:191], v[112:115]
	v_mfma_f32_16x16x32_bf16 v[104:107], v[180:183], v[188:191], v[104:107]
	v_mfma_f32_16x16x32_bf16 v[96:99], v[172:175], v[196:199], v[96:99]
	v_mfma_f32_16x16x32_bf16 v[88:91], v[180:183], v[196:199], v[88:91]
	v_mfma_f32_16x16x32_bf16 v[80:83], v[172:175], v[204:207], v[80:83]
	v_mfma_f32_16x16x32_bf16 v[72:75], v[180:183], v[204:207], v[72:75]
	v_mfma_f32_16x16x32_bf16 v[68:71], v[172:175], v[216:219], v[68:71]
	v_mfma_f32_16x16x32_bf16 v[64:67], v[180:183], v[216:219], v[64:67]
	s_setprio 0
	s_barrier
	s_add_i32 s48, s39, s26
	v_lshl_add_u64 v[144:145], s[22:23], 0, v[132:133]
	s_mov_b32 m0, s48
	ds_read_b128 v[184:187], v151 offset:16384
	ds_read_b128 v[188:191], v151 offset:17408
	ds_read_b128 v[192:195], v151 offset:18432
	ds_read_b128 v[196:199], v151 offset:19456
	ds_read_b128 v[200:203], v151 offset:20480
	ds_read_b128 v[204:207], v151 offset:21504
	ds_read_b128 v[212:215], v151 offset:22528
	ds_read_b128 v[216:219], v151 offset:23552
	global_load_lds_dwordx4 v[144:145], off
	s_add_i32 m0, s48, 0x2000
	s_add_u32 s48, s22, 0x40000
	v_lshl_add_u64 v[220:221], s[22:23], 0, v[128:129]
	s_addc_u32 s49, s23, 0
	s_add_i32 s50, s40, s26
	global_load_lds_dwordx4 v[220:221], off
	v_lshl_add_u64 v[222:223], s[48:49], 0, v[132:133]
	s_mov_b32 m0, s50
	v_lshl_add_u64 v[224:225], s[24:25], 0, v[130:131]
	global_load_lds_dwordx4 v[222:223], off
	v_lshl_add_u64 v[222:223], s[48:49], 0, v[128:129]
	s_add_i32 m0, s50, 0x2000
	s_nop 0
	global_load_lds_dwordx4 v[222:223], off
	v_lshl_add_u64 v[222:223], s[24:25], 0, v[134:135]
	s_mov_b32 m0, s17
	s_nop 0
	global_load_lds_dwordx4 v[222:223], off
	s_mov_b32 m0, s29
	s_nop 0
	global_load_lds_dwordx4 v[224:225], off
	s_waitcnt vmcnt(8)
	s_waitcnt lgkmcnt(0)
	s_barrier
	s_setprio 1
	s_waitcnt lgkmcnt(0)
	v_mfma_f32_16x16x32_bf16 v[60:63], v[152:155], v[184:187], 0
	v_mfma_f32_16x16x32_bf16 v[56:59], v[160:163], v[184:187], 0
	v_mfma_f32_16x16x32_bf16 v[52:55], v[152:155], v[192:195], 0
	v_mfma_f32_16x16x32_bf16 v[44:47], v[160:163], v[192:195], 0
	v_mfma_f32_16x16x32_bf16 v[36:39], v[152:155], v[200:203], 0
	v_mfma_f32_16x16x32_bf16 v[28:31], v[160:163], v[200:203], 0
	v_mfma_f32_16x16x32_bf16 v[20:23], v[152:155], v[212:215], 0
	v_mfma_f32_16x16x32_bf16 v[12:15], v[160:163], v[212:215], 0
	v_mfma_f32_16x16x32_bf16 v[60:63], v[156:159], v[188:191], v[60:63]
	v_mfma_f32_16x16x32_bf16 v[56:59], v[164:167], v[188:191], v[56:59]
	v_mfma_f32_16x16x32_bf16 v[52:55], v[156:159], v[196:199], v[52:55]
	v_mfma_f32_16x16x32_bf16 v[44:47], v[164:167], v[196:199], v[44:47]
	v_mfma_f32_16x16x32_bf16 v[36:39], v[156:159], v[204:207], v[36:39]
	v_mfma_f32_16x16x32_bf16 v[28:31], v[164:167], v[204:207], v[28:31]
	v_mfma_f32_16x16x32_bf16 v[20:23], v[156:159], v[216:219], v[20:23]
	v_mfma_f32_16x16x32_bf16 v[12:15], v[164:167], v[216:219], v[12:15]
	v_mfma_f32_16x16x32_bf16 v[48:51], v[168:171], v[184:187], 0
	v_mfma_f32_16x16x32_bf16 v[40:43], v[176:179], v[184:187], 0
	v_mfma_f32_16x16x32_bf16 v[32:35], v[168:171], v[192:195], 0
	v_mfma_f32_16x16x32_bf16 v[24:27], v[176:179], v[192:195], 0
	v_mfma_f32_16x16x32_bf16 v[16:19], v[168:171], v[200:203], 0
	v_mfma_f32_16x16x32_bf16 v[8:11], v[176:179], v[200:203], 0
	v_mfma_f32_16x16x32_bf16 v[4:7], v[168:171], v[212:215], 0
	v_mfma_f32_16x16x32_bf16 v[0:3], v[176:179], v[212:215], 0
	v_mfma_f32_16x16x32_bf16 v[48:51], v[172:175], v[188:191], v[48:51]
	v_mfma_f32_16x16x32_bf16 v[40:43], v[180:183], v[188:191], v[40:43]
	v_mfma_f32_16x16x32_bf16 v[32:35], v[172:175], v[196:199], v[32:35]
	v_mfma_f32_16x16x32_bf16 v[24:27], v[180:183], v[196:199], v[24:27]
	v_mfma_f32_16x16x32_bf16 v[16:19], v[172:175], v[204:207], v[16:19]
	v_mfma_f32_16x16x32_bf16 v[8:11], v[180:183], v[204:207], v[8:11]
	v_mfma_f32_16x16x32_bf16 v[4:7], v[172:175], v[216:219], v[4:7]
	v_mfma_f32_16x16x32_bf16 v[0:3], v[180:183], v[216:219], v[0:3]
	s_setprio 0
	s_barrier
; #define PG8_STAGE(bufoff, gbase, voff) do { _Pragma("unroll") for (int _i = 0; _i < 2; ++_i) \
;         __builtin_amdgcn_global_load_lds((const unsigned*)((const char*)(gbase) + (voff)[_i]), (PG8_LAS unsigned*)(lds + (bufoff) + ldsw + _i * 8192), 16, 0, 0); } while (0)
; #define PG8_LDA(dst, b, h) do { _Pragma("unroll") for (int m = 0; m < 4; ++m) _Pragma("unroll") for (int k = 0; k < 2; ++k) dst[m][k] = *(const PG8_LAS bf16x8*)(lds + PG8_SA(b, h) + aoff + m * 2048 + k * 1024); } while (0)
; #define PG8_LDB(dst, b, h) do { _Pragma("unroll") for (int n = 0; n < 2; ++n) _Pragma("unroll") for (int k = 0; k < 2; ++k) dst[n][k] = *(const PG8_LAS bf16x8*)(lds + PG8_SB(b, h) + boff + n * 2048 + k * 1024); } while (0)
; #define PG8_MMA(ai, bj, At, Bt) do { __builtin_amdgcn_s_setprio(1); _Pragma("unroll") for (int m = 0; m < 4; ++m) _Pragma("unroll") for (int n = 0; n < 2; ++n) _Pragma("unroll") for (int k = 0; k < 2; ++k) \
;         acc[ai][bj][m][n] = __builtin_amdgcn_mfma_f32_16x16x32_bf16(Bt[n][k], At[m][k], acc[ai][bj][m][n], 0, 0, 0); __builtin_amdgcn_s_setprio(0); } while (0)
; #define PG8_WAIT_V(n) asm volatile("s_waitcnt vmcnt(" #n ")" ::: "memory")
; #define PG8_WAIT_L(n) asm volatile("s_waitcnt lgkmcnt(" #n ")" ::: "memory")
; #define PG8_BAR __builtin_amdgcn_s_barrier()
; #define PG8_SCHED __builtin_amdgcn_sched_barrier(0)
; template <class Epi, class Sched, bool ALIGN_EPI = false, bool SP2 = false>
; __device__ __forceinline__ void gemm_phase(PG8_LAS unsigned char* lds, const Gemm g, const Sched& S, const Epi& E, const int wid) {
;     ...
;             PG8_LDB(B0, 1, 0); PG8_LDB(B1, 1, 1); PG8_SCHED; PG8_LDA(At, 1, 0); PG8_STAGE(PG8_SA(0, 1), a2 + hstep, voffA);
;             PG8_WAIT_V(8); PG8_WAIT_L(0); PG8_BAR; PG8_MMA(0, 0, At, B0); PG8_MMA(0, 1, At, B1); PG8_BAR; PG8_SCHED;
;             PG8_LDA(At, 1, 1); PG8_STAGE(PG8_SB(1, 0), b3, voffB); PG8_STAGE(PG8_SB(1, 1), b3 + hstep, voffB); PG8_STAGE(PG8_SA(1, 0), a3, voffA);
;             PG8_WAIT_V(8); PG8_WAIT_L(0); PG8_BAR; PG8_MMA(1, 0, At, B0); PG8_MMA(1, 1, At, B1); PG8_BAR; PG8_SCHED;
	s_add_i32 s48, 0, 0x18000
	s_add_i32 s49, 0, 0x1c000
	v_add_u32_e32 v164, s48, v147
	v_add_u32_e32 v180, s49, v147
	ds_read_b128 v[152:155], v164
	ds_read_b128 v[156:159], v164 offset:1024
	ds_read_b128 v[160:163], v164 offset:2048
	ds_read_b128 v[164:167], v164 offset:3072
	ds_read_b128 v[168:171], v180
	ds_read_b128 v[172:175], v180 offset:1024
	ds_read_b128 v[176:179], v180 offset:2048
	ds_read_b128 v[180:183], v180 offset:3072
	s_add_u32 s24, s24, 0x40000
	s_addc_u32 s25, s25, 0
	s_mov_b32 m0, s30
	v_lshl_add_u64 v[226:227], s[24:25], 0, v[134:135]
	ds_read_b128 v[184:187], v151 offset:32768
	ds_read_b128 v[188:191], v151 offset:33792
	ds_read_b128 v[192:195], v151 offset:34816
	ds_read_b128 v[196:199], v151 offset:35840
	ds_read_b128 v[200:203], v151 offset:36864
	ds_read_b128 v[204:207], v151 offset:37888
	ds_read_b128 v[212:215], v151 offset:38912
	ds_read_b128 v[216:219], v151 offset:39936
	global_load_lds_dwordx4 v[226:227], off
	v_lshl_add_u64 v[226:227], s[24:25], 0, v[130:131]
	s_mov_b32 m0, s31
	s_nop 0
	global_load_lds_dwordx4 v[226:227], off
	s_waitcnt vmcnt(8)
	s_waitcnt lgkmcnt(0)
	s_barrier
	s_setprio 1
	s_waitcnt lgkmcnt(0)
	v_mfma_f32_16x16x32_bf16 v[124:127], v[152:155], v[184:187], v[124:127]
	v_mfma_f32_16x16x32_bf16 v[120:123], v[160:163], v[184:187], v[120:123]
	v_mfma_f32_16x16x32_bf16 v[116:119], v[152:155], v[192:195], v[116:119]
	v_mfma_f32_16x16x32_bf16 v[108:111], v[160:163], v[192:195], v[108:111]
	v_mfma_f32_16x16x32_bf16 v[100:103], v[152:155], v[200:203], v[100:103]
	v_mfma_f32_16x16x32_bf16 v[92:95], v[160:163], v[200:203], v[92:95]
	v_mfma_f32_16x16x32_bf16 v[84:87], v[152:155], v[212:215], v[84:87]
	v_mfma_f32_16x16x32_bf16 v[76:79], v[160:163], v[212:215], v[76:79]
	v_mfma_f32_16x16x32_bf16 v[124:127], v[156:159], v[188:191], v[124:127]
	v_mfma_f32_16x16x32_bf16 v[120:123], v[164:167], v[188:191], v[120:123]
	v_mfma_f32_16x16x32_bf16 v[116:119], v[156:159], v[196:199], v[116:119]
	v_mfma_f32_16x16x32_bf16 v[108:111], v[164:167], v[196:199], v[108:111]
	v_mfma_f32_16x16x32_bf16 v[100:103], v[156:159], v[204:207], v[100:103]
	v_mfma_f32_16x16x32_bf16 v[92:95], v[164:167], v[204:207], v[92:95]
	v_mfma_f32_16x16x32_bf16 v[84:87], v[156:159], v[216:219], v[84:87]
	v_mfma_f32_16x16x32_bf16 v[76:79], v[164:167], v[216:219], v[76:79]
	v_mfma_f32_16x16x32_bf16 v[112:115], v[168:171], v[184:187], v[112:115]
	v_mfma_f32_16x16x32_bf16 v[104:107], v[176:179], v[184:187], v[104:107]
	v_mfma_f32_16x16x32_bf16 v[96:99], v[168:171], v[192:195], v[96:99]
	v_mfma_f32_16x16x32_bf16 v[88:91], v[176:179], v[192:195], v[88:91]
	v_mfma_f32_16x16x32_bf16 v[80:83], v[168:171], v[200:203], v[80:83]
	v_mfma_f32_16x16x32_bf16 v[72:75], v[176:179], v[200:203], v[72:75]
	v_mfma_f32_16x16x32_bf16 v[68:71], v[168:171], v[212:215], v[68:71]
	v_mfma_f32_16x16x32_bf16 v[64:67], v[176:179], v[212:215], v[64:67]
	v_mfma_f32_16x16x32_bf16 v[112:115], v[172:175], v[188:191], v[112:115]
	v_mfma_f32_16x16x32_bf16 v[104:107], v[180:183], v[188:191], v[104:107]
	v_mfma_f32_16x16x32_bf16 v[96:99], v[172:175], v[196:199], v[96:99]
	v_mfma_f32_16x16x32_bf16 v[88:91], v[180:183], v[196:199], v[88:91]
	v_mfma_f32_16x16x32_bf16 v[80:83], v[172:175], v[204:207], v[80:83]
	v_mfma_f32_16x16x32_bf16 v[72:75], v[180:183], v[204:207], v[72:75]
	v_mfma_f32_16x16x32_bf16 v[68:71], v[172:175], v[216:219], v[68:71]
	v_mfma_f32_16x16x32_bf16 v[64:67], v[180:183], v[216:219], v[64:67]
	s_setprio 0
	s_barrier
	s_add_i32 s24, s48, s26
	v_lshl_add_u64 v[144:145], v[144:145], 0, s[6:7]
	s_mov_b32 m0, s24
	ds_read_b128 v[184:187], v151 offset:49152
	ds_read_b128 v[188:191], v151 offset:50176
	ds_read_b128 v[192:195], v151 offset:51200
	ds_read_b128 v[196:199], v151 offset:52224
	ds_read_b128 v[200:203], v151 offset:53248
	ds_read_b128 v[204:207], v151 offset:54272
	ds_read_b128 v[212:215], v151 offset:55296
	ds_read_b128 v[216:219], v151 offset:56320
	global_load_lds_dwordx4 v[144:145], off
	s_add_i32 m0, s24, 0x2000
	s_add_u32 s22, s22, 0x40080
	v_lshl_add_u64 v[144:145], v[220:221], 0, s[6:7]
	s_addc_u32 s23, s23, 0
	s_add_i32 s24, s49, s26
	global_load_lds_dwordx4 v[144:145], off
	v_lshl_add_u64 v[144:145], s[22:23], 0, v[132:133]
	s_mov_b32 m0, s24
	s_nop 0
	global_load_lds_dwordx4 v[144:145], off
	v_lshl_add_u64 v[144:145], s[22:23], 0, v[128:129]
	s_add_i32 m0, s24, 0x2000
	s_nop 0
	global_load_lds_dwordx4 v[144:145], off
	v_lshl_add_u64 v[144:145], v[222:223], 0, s[6:7]
	s_mov_b32 m0, s37
	s_nop 0
	global_load_lds_dwordx4 v[144:145], off
	v_lshl_add_u64 v[144:145], v[224:225], 0, s[6:7]
	s_mov_b32 m0, s38
	s_nop 0
	global_load_lds_dwordx4 v[144:145], off
	s_waitcnt vmcnt(8)
	s_waitcnt lgkmcnt(0)
	s_barrier
; #define PG8_STAGE(bufoff, gbase, voff) do { _Pragma("unroll") for (int _i = 0; _i < 2; ++_i) \
;         __builtin_amdgcn_global_load_lds((const unsigned*)((const char*)(gbase) + (voff)[_i]), (PG8_LAS unsigned*)(lds + (bufoff) + ldsw + _i * 8192), 16, 0, 0); } while (0)
; #define PG8_LDA(dst, b, h) do { _Pragma("unroll") for (int m = 0; m < 4; ++m) _Pragma("unroll") for (int k = 0; k < 2; ++k) dst[m][k] = *(const PG8_LAS bf16x8*)(lds + PG8_SA(b, h) + aoff + m * 2048 + k * 1024); } while (0)
; #define PG8_LDB(dst, b, h) do { _Pragma("unroll") for (int n = 0; n < 2; ++n) _Pragma("unroll") for (int k = 0; k < 2; ++k) dst[n][k] = *(const PG8_LAS bf16x8*)(lds + PG8_SB(b, h) + boff + n * 2048 + k * 1024); } while (0)
; #define PG8_MMA(ai, bj, At, Bt) do { __builtin_amdgcn_s_setprio(1); _Pragma("unroll") for (int m = 0; m < 4; ++m) _Pragma("unroll") for (int n = 0; n < 2; ++n) _Pragma("unroll") for (int k = 0; k < 2; ++k) \
;         acc[ai][bj][m][n] = __builtin_amdgcn_mfma_f32_16x16x32_bf16(Bt[n][k], At[m][k], acc[ai][bj][m][n], 0, 0, 0); __builtin_amdgcn_s_setprio(0); } while (0)
; #define PG8_BAR __builtin_amdgcn_s_barrier()
; template <class Epi, class Sched, bool ALIGN_EPI = false, bool SP2 = false>
; __device__ __forceinline__ void gemm_phase(PG8_LAS unsigned char* lds, const Gemm g, const Sched& S, const Epi& E, const int wid) {
;     ...
;             PG8_LDB(B0, 0, 0); PG8_LDB(B1, 0, 1); PG8_SCHED; PG8_LDA(At, 0, 0); PG8_STAGE(PG8_SA(1, 1), a1 + hstep, voffA);
;             PG8_WAIT_V(8); PG8_WAIT_L(0); PG8_BAR; PG8_MMA(0, 0, At, B0); PG8_MMA(0, 1, At, B1); PG8_BAR; PG8_SCHED;
;             PG8_LDA(At, 0, 1); PG8_STAGE(PG8_SB(0, 0), b2, voffB); PG8_STAGE(PG8_SB(0, 1), b2 + hstep, voffB); PG8_STAGE(PG8_SA(0, 0), a2, voffA);
;             PG8_WAIT_V(8); PG8_WAIT_L(0); PG8_BAR; PG8_MMA(1, 0, At, B0); PG8_MMA(1, 1, At, B1); PG8_BAR; PG8_SCHED;
;             PG8_LDB(B0, 1, 0); PG8_LDB(B1, 1, 1); PG8_SCHED; PG8_LDA(At, 1, 0); PG8_STAGE(PG8_SA(0, 1), a2 + hstep, voffA);
;             PG8_WAIT_V(8); PG8_WAIT_L(0); PG8_BAR; PG8_MMA(0, 0, At, B0); PG8_MMA(0, 1, At, B1); PG8_BAR; PG8_SCHED;
;             PG8_LDA(At, 1, 1); PG8_STAGE(PG8_SB(1, 0), b3, voffB); PG8_STAGE(PG8_SB(1, 1), b3 + hstep, voffB); PG8_STAGE(PG8_SA(1, 0), a3, voffA);
;             PG8_WAIT_V(8); PG8_WAIT_L(0); PG8_BAR; PG8_MMA(1, 0, At, B0); PG8_MMA(1, 1, At, B1); PG8_BAR; PG8_SCHED;
	s_setprio 1
	s_waitcnt lgkmcnt(0)
	v_mfma_f32_16x16x32_bf16 v[60:63], v[152:155], v[184:187], v[60:63]
	v_mfma_f32_16x16x32_bf16 v[56:59], v[160:163], v[184:187], v[56:59]
	v_mfma_f32_16x16x32_bf16 v[52:55], v[152:155], v[192:195], v[52:55]
	v_mfma_f32_16x16x32_bf16 v[44:47], v[160:163], v[192:195], v[44:47]
	v_mfma_f32_16x16x32_bf16 v[36:39], v[152:155], v[200:203], v[36:39]
	v_mfma_f32_16x16x32_bf16 v[28:31], v[160:163], v[200:203], v[28:31]
	v_mfma_f32_16x16x32_bf16 v[20:23], v[152:155], v[212:215], v[20:23]
	v_mfma_f32_16x16x32_bf16 v[12:15], v[160:163], v[212:215], v[12:15]
	v_mfma_f32_16x16x32_bf16 v[60:63], v[156:159], v[188:191], v[60:63]
	v_mfma_f32_16x16x32_bf16 v[56:59], v[164:167], v[188:191], v[56:59]
	v_mfma_f32_16x16x32_bf16 v[52:55], v[156:159], v[196:199], v[52:55]
	v_mfma_f32_16x16x32_bf16 v[44:47], v[164:167], v[196:199], v[44:47]
	v_mfma_f32_16x16x32_bf16 v[36:39], v[156:159], v[204:207], v[36:39]
	v_mfma_f32_16x16x32_bf16 v[28:31], v[164:167], v[204:207], v[28:31]
	v_mfma_f32_16x16x32_bf16 v[20:23], v[156:159], v[216:219], v[20:23]
	v_mfma_f32_16x16x32_bf16 v[12:15], v[164:167], v[216:219], v[12:15]
	v_mfma_f32_16x16x32_bf16 v[48:51], v[168:171], v[184:187], v[48:51]
	v_mfma_f32_16x16x32_bf16 v[40:43], v[176:179], v[184:187], v[40:43]
	v_mfma_f32_16x16x32_bf16 v[32:35], v[168:171], v[192:195], v[32:35]
	v_mfma_f32_16x16x32_bf16 v[24:27], v[176:179], v[192:195], v[24:27]
	v_mfma_f32_16x16x32_bf16 v[16:19], v[168:171], v[200:203], v[16:19]
	v_mfma_f32_16x16x32_bf16 v[8:11], v[176:179], v[200:203], v[8:11]
	v_mfma_f32_16x16x32_bf16 v[4:7], v[168:171], v[212:215], v[4:7]
	v_mfma_f32_16x16x32_bf16 v[0:3], v[176:179], v[212:215], v[0:3]
	v_mfma_f32_16x16x32_bf16 v[48:51], v[172:175], v[188:191], v[48:51]
	v_mfma_f32_16x16x32_bf16 v[40:43], v[180:183], v[188:191], v[40:43]
	v_mfma_f32_16x16x32_bf16 v[32:35], v[172:175], v[196:199], v[32:35]
	v_mfma_f32_16x16x32_bf16 v[24:27], v[180:183], v[196:199], v[24:27]
	v_mfma_f32_16x16x32_bf16 v[16:19], v[172:175], v[204:207], v[16:19]
	v_mfma_f32_16x16x32_bf16 v[8:11], v[180:183], v[204:207], v[8:11]
	v_mfma_f32_16x16x32_bf16 v[4:7], v[172:175], v[216:219], v[4:7]
	v_mfma_f32_16x16x32_bf16 v[0:3], v[180:183], v[216:219], v[0:3]
	s_setprio 0
	s_barrier
	s_add_i32 s47, s47, 2
	s_add_u32 s20, s20, 0x100
	s_addc_u32 s21, s21, 0
	s_add_u32 s45, s45, 0x100
	s_addc_u32 s46, s46, 0
	s_cmp_gt_u32 s47, 13
	s_cbranch_scc0 .LBB0_882
	s_branch .Lkp_exit_2
.LBB0_882:
	ds_read_b128 v[152:155], v149
	ds_read_b128 v[156:159], v149 offset:1024
	ds_read_b128 v[160:163], v149 offset:2048
	ds_read_b128 v[164:167], v149 offset:3072
	ds_read_b128 v[168:171], v150
	ds_read_b128 v[172:175], v150 offset:1024
	ds_read_b128 v[176:179], v150 offset:2048
	ds_read_b128 v[180:183], v150 offset:3072
	s_add_u32 s22, s20, 0xfffc0080
	s_addc_u32 s23, s21, -1
	s_cmp_eq_u32 s47, 12
	s_cselect_b32 s25, s13, s23
	s_cselect_b32 s24, s43, s22
	s_cselect_b32 s23, s9, s46
	s_cselect_b32 s22, s44, s45
	v_lshl_add_u64 v[144:145], s[20:21], 0, v[136:137]
	s_add_i32 m0, s17, 0xc000
	ds_read_b128 v[184:187], v151
	ds_read_b128 v[188:191], v151 offset:1024
	ds_read_b128 v[192:195], v151 offset:2048
	ds_read_b128 v[196:199], v151 offset:3072
	ds_read_b128 v[200:203], v151 offset:4096
	ds_read_b128 v[204:207], v151 offset:5120
	ds_read_b128 v[212:215], v151 offset:6144
	ds_read_b128 v[216:219], v151 offset:7168
	global_load_lds_dwordx4 v[144:145], off
	v_lshl_add_u64 v[144:145], s[20:21], 0, v[138:139]
	s_add_i32 m0, s17, 0xe000
	s_nop 0
	global_load_lds_dwordx4 v[144:145], off
	s_waitcnt vmcnt(8)
	s_waitcnt lgkmcnt(0)
	s_barrier
	s_setprio 1
	s_waitcnt lgkmcnt(0)
	v_mfma_f32_16x16x32_bf16 v[124:127], v[152:155], v[184:187], v[124:127]
	v_mfma_f32_16x16x32_bf16 v[120:123], v[160:163], v[184:187], v[120:123]
	v_mfma_f32_16x16x32_bf16 v[116:119], v[152:155], v[192:195], v[116:119]
	v_mfma_f32_16x16x32_bf16 v[108:111], v[160:163], v[192:195], v[108:111]
	v_mfma_f32_16x16x32_bf16 v[100:103], v[152:155], v[200:203], v[100:103]
	v_mfma_f32_16x16x32_bf16 v[92:95], v[160:163], v[200:203], v[92:95]
	v_mfma_f32_16x16x32_bf16 v[84:87], v[152:155], v[212:215], v[84:87]
	v_mfma_f32_16x16x32_bf16 v[76:79], v[160:163], v[212:215], v[76:79]
	v_mfma_f32_16x16x32_bf16 v[124:127], v[156:159], v[188:191], v[124:127]
	v_mfma_f32_16x16x32_bf16 v[120:123], v[164:167], v[188:191], v[120:123]
	v_mfma_f32_16x16x32_bf16 v[116:119], v[156:159], v[196:199], v[116:119]
	v_mfma_f32_16x16x32_bf16 v[108:111], v[164:167], v[196:199], v[108:111]
	v_mfma_f32_16x16x32_bf16 v[100:103], v[156:159], v[204:207], v[100:103]
	v_mfma_f32_16x16x32_bf16 v[92:95], v[164:167], v[204:207], v[92:95]
	v_mfma_f32_16x16x32_bf16 v[84:87], v[156:159], v[216:219], v[84:87]
	v_mfma_f32_16x16x32_bf16 v[76:79], v[164:167], v[216:219], v[76:79]
	v_mfma_f32_16x16x32_bf16 v[112:115], v[168:171], v[184:187], v[112:115]
	v_mfma_f32_16x16x32_bf16 v[104:107], v[176:179], v[184:187], v[104:107]
	v_mfma_f32_16x16x32_bf16 v[96:99], v[168:171], v[192:195], v[96:99]
	v_mfma_f32_16x16x32_bf16 v[88:91], v[176:179], v[192:195], v[88:91]
	v_mfma_f32_16x16x32_bf16 v[80:83], v[168:171], v[200:203], v[80:83]
	v_mfma_f32_16x16x32_bf16 v[72:75], v[176:179], v[200:203], v[72:75]
	v_mfma_f32_16x16x32_bf16 v[68:71], v[168:171], v[212:215], v[68:71]
	v_mfma_f32_16x16x32_bf16 v[64:67], v[176:179], v[212:215], v[64:67]
	v_mfma_f32_16x16x32_bf16 v[112:115], v[172:175], v[188:191], v[112:115]
	v_mfma_f32_16x16x32_bf16 v[104:107], v[180:183], v[188:191], v[104:107]
	v_mfma_f32_16x16x32_bf16 v[96:99], v[172:175], v[196:199], v[96:99]
	v_mfma_f32_16x16x32_bf16 v[88:91], v[180:183], v[196:199], v[88:91]
	v_mfma_f32_16x16x32_bf16 v[80:83], v[172:175], v[204:207], v[80:83]
	v_mfma_f32_16x16x32_bf16 v[72:75], v[180:183], v[204:207], v[72:75]
	v_mfma_f32_16x16x32_bf16 v[68:71], v[172:175], v[216:219], v[68:71]
	v_mfma_f32_16x16x32_bf16 v[64:67], v[180:183], v[216:219], v[64:67]
	s_setprio 0
	s_barrier
; #define PG8_STAGE(bufoff, gbase, voff) do { _Pragma("unroll") for (int _i = 0; _i < 2; ++_i) \
;         __builtin_amdgcn_global_load_lds((const unsigned*)((const char*)(gbase) + (voff)[_i]), (PG8_LAS unsigned*)(lds + (bufoff) + ldsw + _i * 8192), 16, 0, 0); } while (0)
; #define PG8_LDA(dst, b, h) do { _Pragma("unroll") for (int m = 0; m < 4; ++m) _Pragma("unroll") for (int k = 0; k < 2; ++k) dst[m][k] = *(const PG8_LAS bf16x8*)(lds + PG8_SA(b, h) + aoff + m * 2048 + k * 1024); } while (0)
; #define PG8_LDB(dst, b, h) do { _Pragma("unroll") for (int n = 0; n < 2; ++n) _Pragma("unroll") for (int k = 0; k < 2; ++k) dst[n][k] = *(const PG8_LAS bf16x8*)(lds + PG8_SB(b, h) + boff + n * 2048 + k * 1024); } while (0)
; #define PG8_MMA(ai, bj, At, Bt) do { __builtin_amdgcn_s_setprio(1); _Pragma("unroll") for (int m = 0; m < 4; ++m) _Pragma("unroll") for (int n = 0; n < 2; ++n) _Pragma("unroll") for (int k = 0; k < 2; ++k) \
;         acc[ai][bj][m][n] = __builtin_amdgcn_mfma_f32_16x16x32_bf16(Bt[n][k], At[m][k], acc[ai][bj][m][n], 0, 0, 0); __builtin_amdgcn_s_setprio(0); } while (0)
; #define PG8_WAIT_V(n) asm volatile("s_waitcnt vmcnt(" #n ")" ::: "memory")
; #define PG8_WAIT_L(n) asm volatile("s_waitcnt lgkmcnt(" #n ")" ::: "memory")
; #define PG8_BAR __builtin_amdgcn_s_barrier()
; #define PG8_SCHED __builtin_amdgcn_sched_barrier(0)
; template <class Epi, class Sched, bool ALIGN_EPI = false, bool SP2 = false>
; __device__ __forceinline__ void gemm_phase(PG8_LAS unsigned char* lds, const Gemm g, const Sched& S, const Epi& E, const int wid) {
;     ...
;             PG8_LDA(At, 0, 1); PG8_STAGE(PG8_SB(0, 0), b2, voffB); PG8_STAGE(PG8_SB(0, 1), b2 + hstep, voffB); PG8_STAGE(PG8_SA(0, 0), a2, voffA);
;             PG8_WAIT_V(8); PG8_WAIT_L(0); PG8_BAR; PG8_MMA(1, 0, At, B0); PG8_MMA(1, 1, At, B1); PG8_BAR; PG8_SCHED;
;             PG8_LDB(B0, 1, 0); PG8_LDB(B1, 1, 1); PG8_SCHED; PG8_LDA(At, 1, 0); PG8_STAGE(PG8_SA(0, 1), a2 + hstep, voffA);
;             PG8_WAIT_V(8); PG8_WAIT_L(0); PG8_BAR; PG8_MMA(0, 0, At, B0); PG8_MMA(0, 1, At, B1); PG8_BAR; PG8_SCHED;
	s_add_i32 s48, s39, s26
	v_lshl_add_u64 v[144:145], s[22:23], 0, v[132:133]
	s_mov_b32 m0, s48
	ds_read_b128 v[184:187], v151 offset:16384
	ds_read_b128 v[188:191], v151 offset:17408
	ds_read_b128 v[192:195], v151 offset:18432
	ds_read_b128 v[196:199], v151 offset:19456
	ds_read_b128 v[200:203], v151 offset:20480
	ds_read_b128 v[204:207], v151 offset:21504
	ds_read_b128 v[212:215], v151 offset:22528
	ds_read_b128 v[216:219], v151 offset:23552
	global_load_lds_dwordx4 v[144:145], off
	s_add_i32 m0, s48, 0x2000
	s_add_u32 s48, s22, 0x40000
	v_lshl_add_u64 v[220:221], s[22:23], 0, v[128:129]
	s_addc_u32 s49, s23, 0
	s_add_i32 s50, s40, s26
	global_load_lds_dwordx4 v[220:221], off
	v_lshl_add_u64 v[222:223], s[48:49], 0, v[132:133]
	s_mov_b32 m0, s50
	v_lshl_add_u64 v[224:225], s[24:25], 0, v[130:131]
	global_load_lds_dwordx4 v[222:223], off
	v_lshl_add_u64 v[222:223], s[48:49], 0, v[128:129]
	s_add_i32 m0, s50, 0x2000
	s_nop 0
	global_load_lds_dwordx4 v[222:223], off
	v_lshl_add_u64 v[222:223], s[24:25], 0, v[134:135]
	s_mov_b32 m0, s17
	s_nop 0
	global_load_lds_dwordx4 v[222:223], off
	s_mov_b32 m0, s29
	s_nop 0
	global_load_lds_dwordx4 v[224:225], off
	s_waitcnt vmcnt(8)
	s_waitcnt lgkmcnt(0)
	s_barrier
	s_setprio 1
	s_waitcnt lgkmcnt(0)
	v_mfma_f32_16x16x32_bf16 v[60:63], v[152:155], v[184:187], v[60:63]
	v_mfma_f32_16x16x32_bf16 v[56:59], v[160:163], v[184:187], v[56:59]
	v_mfma_f32_16x16x32_bf16 v[52:55], v[152:155], v[192:195], v[52:55]
	v_mfma_f32_16x16x32_bf16 v[44:47], v[160:163], v[192:195], v[44:47]
	v_mfma_f32_16x16x32_bf16 v[36:39], v[152:155], v[200:203], v[36:39]
	v_mfma_f32_16x16x32_bf16 v[28:31], v[160:163], v[200:203], v[28:31]
	v_mfma_f32_16x16x32_bf16 v[20:23], v[152:155], v[212:215], v[20:23]
	v_mfma_f32_16x16x32_bf16 v[12:15], v[160:163], v[212:215], v[12:15]
	v_mfma_f32_16x16x32_bf16 v[60:63], v[156:159], v[188:191], v[60:63]
	v_mfma_f32_16x16x32_bf16 v[56:59], v[164:167], v[188:191], v[56:59]
	v_mfma_f32_16x16x32_bf16 v[52:55], v[156:159], v[196:199], v[52:55]
	v_mfma_f32_16x16x32_bf16 v[44:47], v[164:167], v[196:199], v[44:47]
	v_mfma_f32_16x16x32_bf16 v[36:39], v[156:159], v[204:207], v[36:39]
	v_mfma_f32_16x16x32_bf16 v[28:31], v[164:167], v[204:207], v[28:31]
	v_mfma_f32_16x16x32_bf16 v[20:23], v[156:159], v[216:219], v[20:23]
	v_mfma_f32_16x16x32_bf16 v[12:15], v[164:167], v[216:219], v[12:15]
	v_mfma_f32_16x16x32_bf16 v[48:51], v[168:171], v[184:187], v[48:51]
	v_mfma_f32_16x16x32_bf16 v[40:43], v[176:179], v[184:187], v[40:43]
	v_mfma_f32_16x16x32_bf16 v[32:35], v[168:171], v[192:195], v[32:35]
	v_mfma_f32_16x16x32_bf16 v[24:27], v[176:179], v[192:195], v[24:27]
	v_mfma_f32_16x16x32_bf16 v[16:19], v[168:171], v[200:203], v[16:19]
	v_mfma_f32_16x16x32_bf16 v[8:11], v[176:179], v[200:203], v[8:11]
	v_mfma_f32_16x16x32_bf16 v[4:7], v[168:171], v[212:215], v[4:7]
	v_mfma_f32_16x16x32_bf16 v[0:3], v[176:179], v[212:215], v[0:3]
	v_mfma_f32_16x16x32_bf16 v[48:51], v[172:175], v[188:191], v[48:51]
	v_mfma_f32_16x16x32_bf16 v[40:43], v[180:183], v[188:191], v[40:43]
	v_mfma_f32_16x16x32_bf16 v[32:35], v[172:175], v[196:199], v[32:35]
	v_mfma_f32_16x16x32_bf16 v[24:27], v[180:183], v[196:199], v[24:27]
	v_mfma_f32_16x16x32_bf16 v[16:19], v[172:175], v[204:207], v[16:19]
	v_mfma_f32_16x16x32_bf16 v[8:11], v[180:183], v[204:207], v[8:11]
	v_mfma_f32_16x16x32_bf16 v[4:7], v[172:175], v[216:219], v[4:7]
	v_mfma_f32_16x16x32_bf16 v[0:3], v[180:183], v[216:219], v[0:3]
	s_setprio 0
	s_barrier
	s_add_i32 s48, 0, 0x18000
	s_add_i32 s49, 0, 0x1c000
	v_add_u32_e32 v164, s48, v147
	v_add_u32_e32 v180, s49, v147
	ds_read_b128 v[152:155], v164
	ds_read_b128 v[156:159], v164 offset:1024
	ds_read_b128 v[160:163], v164 offset:2048
	ds_read_b128 v[164:167], v164 offset:3072
	ds_read_b128 v[168:171], v180
	ds_read_b128 v[172:175], v180 offset:1024
	ds_read_b128 v[176:179], v180 offset:2048
	ds_read_b128 v[180:183], v180 offset:3072
	s_add_u32 s24, s24, 0x40000
	s_addc_u32 s25, s25, 0
	s_mov_b32 m0, s30
	v_lshl_add_u64 v[226:227], s[24:25], 0, v[134:135]
	ds_read_b128 v[184:187], v151 offset:32768
	ds_read_b128 v[188:191], v151 offset:33792
	ds_read_b128 v[192:195], v151 offset:34816
	ds_read_b128 v[196:199], v151 offset:35840
	ds_read_b128 v[200:203], v151 offset:36864
	ds_read_b128 v[204:207], v151 offset:37888
	ds_read_b128 v[212:215], v151 offset:38912
	ds_read_b128 v[216:219], v151 offset:39936
	global_load_lds_dwordx4 v[226:227], off
	v_lshl_add_u64 v[226:227], s[24:25], 0, v[130:131]
	s_mov_b32 m0, s31
	s_nop 0
	global_load_lds_dwordx4 v[226:227], off
	s_waitcnt vmcnt(8)
	s_waitcnt lgkmcnt(0)
	s_barrier
; #define PG8_STAGE(bufoff, gbase, voff) do { _Pragma("unroll") for (int _i = 0; _i < 2; ++_i) \
;         __builtin_amdgcn_global_load_lds((const unsigned*)((const char*)(gbase) + (voff)[_i]), (PG8_LAS unsigned*)(lds + (bufoff) + ldsw + _i * 8192), 16, 0, 0); } while (0)
; #define PG8_LDA(dst, b, h) do { _Pragma("unroll") for (int m = 0; m < 4; ++m) _Pragma("unroll") for (int k = 0; k < 2; ++k) dst[m][k] = *(const PG8_LAS bf16x8*)(lds + PG8_SA(b, h) + aoff + m * 2048 + k * 1024); } while (0)
; #define PG8_MMA(ai, bj, At, Bt) do { __builtin_amdgcn_s_setprio(1); _Pragma("unroll") for (int m = 0; m < 4; ++m) _Pragma("unroll") for (int n = 0; n < 2; ++n) _Pragma("unroll") for (int k = 0; k < 2; ++k) \
;         acc[ai][bj][m][n] = __builtin_amdgcn_mfma_f32_16x16x32_bf16(Bt[n][k], At[m][k], acc[ai][bj][m][n], 0, 0, 0); __builtin_amdgcn_s_setprio(0); } while (0)
; #define PG8_WAIT_V(n) asm volatile("s_waitcnt vmcnt(" #n ")" ::: "memory")
; #define PG8_WAIT_L(n) asm volatile("s_waitcnt lgkmcnt(" #n ")" ::: "memory")
; #define PG8_BAR __builtin_amdgcn_s_barrier()
; #define PG8_SCHED __builtin_amdgcn_sched_barrier(0)
; template <class Epi, class Sched, bool ALIGN_EPI = false, bool SP2 = false>
; __device__ __forceinline__ void gemm_phase(PG8_LAS unsigned char* lds, const Gemm g, const Sched& S, const Epi& E, const int wid) {
;     ...
;             PG8_WAIT_V(8); PG8_WAIT_L(0); PG8_BAR; PG8_MMA(0, 0, At, B0); PG8_MMA(0, 1, At, B1); PG8_BAR; PG8_SCHED;
;             PG8_LDA(At, 1, 1); PG8_STAGE(PG8_SB(1, 0), b3, voffB); PG8_STAGE(PG8_SB(1, 1), b3 + hstep, voffB); PG8_STAGE(PG8_SA(1, 0), a3, voffA);
;             PG8_WAIT_V(8); PG8_WAIT_L(0); PG8_BAR; PG8_MMA(1, 0, At, B0); PG8_MMA(1, 1, At, B1); PG8_BAR; PG8_SCHED;
	s_setprio 1
	s_waitcnt lgkmcnt(0)
	v_mfma_f32_16x16x32_bf16 v[124:127], v[152:155], v[184:187], v[124:127]
	v_mfma_f32_16x16x32_bf16 v[120:123], v[160:163], v[184:187], v[120:123]
	v_mfma_f32_16x16x32_bf16 v[116:119], v[152:155], v[192:195], v[116:119]
	v_mfma_f32_16x16x32_bf16 v[108:111], v[160:163], v[192:195], v[108:111]
	v_mfma_f32_16x16x32_bf16 v[100:103], v[152:155], v[200:203], v[100:103]
	v_mfma_f32_16x16x32_bf16 v[92:95], v[160:163], v[200:203], v[92:95]
	v_mfma_f32_16x16x32_bf16 v[84:87], v[152:155], v[212:215], v[84:87]
	v_mfma_f32_16x16x32_bf16 v[76:79], v[160:163], v[212:215], v[76:79]
	v_mfma_f32_16x16x32_bf16 v[124:127], v[156:159], v[188:191], v[124:127]
	v_mfma_f32_16x16x32_bf16 v[120:123], v[164:167], v[188:191], v[120:123]
	v_mfma_f32_16x16x32_bf16 v[116:119], v[156:159], v[196:199], v[116:119]
	v_mfma_f32_16x16x32_bf16 v[108:111], v[164:167], v[196:199], v[108:111]
	v_mfma_f32_16x16x32_bf16 v[100:103], v[156:159], v[204:207], v[100:103]
	v_mfma_f32_16x16x32_bf16 v[92:95], v[164:167], v[204:207], v[92:95]
	v_mfma_f32_16x16x32_bf16 v[84:87], v[156:159], v[216:219], v[84:87]
	v_mfma_f32_16x16x32_bf16 v[76:79], v[164:167], v[216:219], v[76:79]
	v_mfma_f32_16x16x32_bf16 v[112:115], v[168:171], v[184:187], v[112:115]
	v_mfma_f32_16x16x32_bf16 v[104:107], v[176:179], v[184:187], v[104:107]
	v_mfma_f32_16x16x32_bf16 v[96:99], v[168:171], v[192:195], v[96:99]
	v_mfma_f32_16x16x32_bf16 v[88:91], v[176:179], v[192:195], v[88:91]
	v_mfma_f32_16x16x32_bf16 v[80:83], v[168:171], v[200:203], v[80:83]
	v_mfma_f32_16x16x32_bf16 v[72:75], v[176:179], v[200:203], v[72:75]
	v_mfma_f32_16x16x32_bf16 v[68:71], v[168:171], v[212:215], v[68:71]
	v_mfma_f32_16x16x32_bf16 v[64:67], v[176:179], v[212:215], v[64:67]
	v_mfma_f32_16x16x32_bf16 v[112:115], v[172:175], v[188:191], v[112:115]
	v_mfma_f32_16x16x32_bf16 v[104:107], v[180:183], v[188:191], v[104:107]
	v_mfma_f32_16x16x32_bf16 v[96:99], v[172:175], v[196:199], v[96:99]
	v_mfma_f32_16x16x32_bf16 v[88:91], v[180:183], v[196:199], v[88:91]
	v_mfma_f32_16x16x32_bf16 v[80:83], v[172:175], v[204:207], v[80:83]
	v_mfma_f32_16x16x32_bf16 v[72:75], v[180:183], v[204:207], v[72:75]
	v_mfma_f32_16x16x32_bf16 v[68:71], v[172:175], v[216:219], v[68:71]
	v_mfma_f32_16x16x32_bf16 v[64:67], v[180:183], v[216:219], v[64:67]
	s_setprio 0
	s_barrier
	s_add_i32 s24, s48, s26
	v_lshl_add_u64 v[144:145], v[144:145], 0, s[6:7]
	s_mov_b32 m0, s24
	ds_read_b128 v[184:187], v151 offset:49152
	ds_read_b128 v[188:191], v151 offset:50176
	ds_read_b128 v[192:195], v151 offset:51200
	ds_read_b128 v[196:199], v151 offset:52224
	ds_read_b128 v[200:203], v151 offset:53248
	ds_read_b128 v[204:207], v151 offset:54272
	ds_read_b128 v[212:215], v151 offset:55296
	ds_read_b128 v[216:219], v151 offset:56320
	global_load_lds_dwordx4 v[144:145], off
	s_add_i32 m0, s24, 0x2000
	s_add_u32 s22, s22, 0x40080
	v_lshl_add_u64 v[144:145], v[220:221], 0, s[6:7]
	s_addc_u32 s23, s23, 0
	s_add_i32 s24, s49, s26
	global_load_lds_dwordx4 v[144:145], off
	v_lshl_add_u64 v[144:145], s[22:23], 0, v[132:133]
	s_mov_b32 m0, s24
	s_nop 0
	global_load_lds_dwordx4 v[144:145], off
	v_lshl_add_u64 v[144:145], s[22:23], 0, v[128:129]
	s_add_i32 m0, s24, 0x2000
	s_nop 0
	global_load_lds_dwordx4 v[144:145], off
	v_lshl_add_u64 v[144:145], v[222:223], 0, s[6:7]
	s_mov_b32 m0, s37
	s_nop 0
	global_load_lds_dwordx4 v[144:145], off
	v_lshl_add_u64 v[144:145], v[224:225], 0, s[6:7]
	s_mov_b32 m0, s38
	s_nop 0
	global_load_lds_dwordx4 v[144:145], off
	s_waitcnt vmcnt(8)
	s_waitcnt lgkmcnt(0)
	s_barrier
	s_setprio 1
	s_waitcnt lgkmcnt(0)
	v_mfma_f32_16x16x32_bf16 v[60:63], v[152:155], v[184:187], v[60:63]
	v_mfma_f32_16x16x32_bf16 v[56:59], v[160:163], v[184:187], v[56:59]
	v_mfma_f32_16x16x32_bf16 v[52:55], v[152:155], v[192:195], v[52:55]
	v_mfma_f32_16x16x32_bf16 v[44:47], v[160:163], v[192:195], v[44:47]
	v_mfma_f32_16x16x32_bf16 v[36:39], v[152:155], v[200:203], v[36:39]
	v_mfma_f32_16x16x32_bf16 v[28:31], v[160:163], v[200:203], v[28:31]
	v_mfma_f32_16x16x32_bf16 v[20:23], v[152:155], v[212:215], v[20:23]
	v_mfma_f32_16x16x32_bf16 v[12:15], v[160:163], v[212:215], v[12:15]
	v_mfma_f32_16x16x32_bf16 v[60:63], v[156:159], v[188:191], v[60:63]
	v_mfma_f32_16x16x32_bf16 v[56:59], v[164:167], v[188:191], v[56:59]
	v_mfma_f32_16x16x32_bf16 v[52:55], v[156:159], v[196:199], v[52:55]
	v_mfma_f32_16x16x32_bf16 v[44:47], v[164:167], v[196:199], v[44:47]
	v_mfma_f32_16x16x32_bf16 v[36:39], v[156:159], v[204:207], v[36:39]
	v_mfma_f32_16x16x32_bf16 v[28:31], v[164:167], v[204:207], v[28:31]
	v_mfma_f32_16x16x32_bf16 v[20:23], v[156:159], v[216:219], v[20:23]
	v_mfma_f32_16x16x32_bf16 v[12:15], v[164:167], v[216:219], v[12:15]
	v_mfma_f32_16x16x32_bf16 v[48:51], v[168:171], v[184:187], v[48:51]
	v_mfma_f32_16x16x32_bf16 v[40:43], v[176:179], v[184:187], v[40:43]
	v_mfma_f32_16x16x32_bf16 v[32:35], v[168:171], v[192:195], v[32:35]
	v_mfma_f32_16x16x32_bf16 v[24:27], v[176:179], v[192:195], v[24:27]
	v_mfma_f32_16x16x32_bf16 v[16:19], v[168:171], v[200:203], v[16:19]
	v_mfma_f32_16x16x32_bf16 v[8:11], v[176:179], v[200:203], v[8:11]
	v_mfma_f32_16x16x32_bf16 v[4:7], v[168:171], v[212:215], v[4:7]
	v_mfma_f32_16x16x32_bf16 v[0:3], v[176:179], v[212:215], v[0:3]
	v_mfma_f32_16x16x32_bf16 v[48:51], v[172:175], v[188:191], v[48:51]
	v_mfma_f32_16x16x32_bf16 v[40:43], v[180:183], v[188:191], v[40:43]
	v_mfma_f32_16x16x32_bf16 v[32:35], v[172:175], v[196:199], v[32:35]
	v_mfma_f32_16x16x32_bf16 v[24:27], v[180:183], v[196:199], v[24:27]
	v_mfma_f32_16x16x32_bf16 v[16:19], v[172:175], v[204:207], v[16:19]
	v_mfma_f32_16x16x32_bf16 v[8:11], v[180:183], v[204:207], v[8:11]
	v_mfma_f32_16x16x32_bf16 v[4:7], v[172:175], v[216:219], v[4:7]
	v_mfma_f32_16x16x32_bf16 v[0:3], v[180:183], v[216:219], v[0:3]
	s_setprio 0
	s_barrier
	s_add_i32 s47, s47, 2
	s_add_u32 s20, s20, 0x100
	s_addc_u32 s21, s21, 0
	s_add_u32 s45, s45, 0x100
	s_addc_u32 s46, s46, 0
	s_cmp_gt_u32 s47, 13
	s_cbranch_scc0 .LBB0_882

; #define PG8_STAGE(bufoff, gbase, voff) do { _Pragma("unroll") for (int _i = 0; _i < 2; ++_i) \
;         __builtin_amdgcn_global_load_lds((const unsigned*)((const char*)(gbase) + (voff)[_i]), (PG8_LAS unsigned*)(lds + (bufoff) + ldsw + _i * 8192), 16, 0, 0); } while (0)
; #define PG8_LDA(dst, b, h) do { _Pragma("unroll") for (int m = 0; m < 4; ++m) _Pragma("unroll") for (int k = 0; k < 2; ++k) dst[m][k] = *(const PG8_LAS bf16x8*)(lds + PG8_SA(b, h) + aoff + m * 2048 + k * 1024); } while (0)
; #define PG8_LDB(dst, b, h) do { _Pragma("unroll") for (int n = 0; n < 2; ++n) _Pragma("unroll") for (int k = 0; k < 2; ++k) dst[n][k] = *(const PG8_LAS bf16x8*)(lds + PG8_SB(b, h) + boff + n * 2048 + k * 1024); } while (0)
; #define PG8_MMA(ai, bj, At, Bt) do { __builtin_amdgcn_s_setprio(1); _Pragma("unroll") for (int m = 0; m < 4; ++m) _Pragma("unroll") for (int n = 0; n < 2; ++n) _Pragma("unroll") for (int k = 0; k < 2; ++k) \
;         acc[ai][bj][m][n] = __builtin_amdgcn_mfma_f32_16x16x32_bf16(Bt[n][k], At[m][k], acc[ai][bj][m][n], 0, 0, 0); __builtin_amdgcn_s_setprio(0); } while (0)
; #define PG8_WAIT_V(n) asm volatile("s_waitcnt vmcnt(" #n ")" ::: "memory")
; #define PG8_WAIT_L(n) asm volatile("s_waitcnt lgkmcnt(" #n ")" ::: "memory")
; #define PG8_BAR __builtin_amdgcn_s_barrier()
; #define PG8_SCHED __builtin_amdgcn_sched_barrier(0)
; template <class Epi, class Sched, bool ALIGN_EPI = false, bool SP2 = false>
; __device__ __forceinline__ void gemm_phase(PG8_LAS unsigned char* lds, const Gemm g, const Sched& S, const Epi& E, const int wid) {
;     ...
;             PG8_LDB(B0, 0, 0); PG8_LDB(B1, 0, 1); PG8_SCHED; PG8_LDA(At, 0, 0); PG8_STAGE(PG8_SA(1, 1), a1 + hstep, voffA);
;             PG8_WAIT_V(8); PG8_WAIT_L(0); PG8_BAR; PG8_MMA(0, 0, At, B0); PG8_MMA(0, 1, At, B1); PG8_BAR; PG8_SCHED;
;             PG8_LDA(At, 0, 1); PG8_STAGE(PG8_SB(0, 0), b2, voffB); PG8_STAGE(PG8_SB(0, 1), b2 + hstep, voffB); PG8_STAGE(PG8_SA(0, 0), a2, voffA);
;             PG8_WAIT_V(8); PG8_WAIT_L(0); PG8_BAR; PG8_MMA(1, 0, At, B0); PG8_MMA(1, 1, At, B1); PG8_BAR; PG8_SCHED;
;             PG8_LDB(B0, 1, 0); PG8_LDB(B1, 1, 1); PG8_SCHED; PG8_LDA(At, 1, 0); PG8_STAGE(PG8_SA(0, 1), a2 + hstep, voffA);
.LBB0_1786:
	v_add_u32_e32 v164, s41, v150
	v_add_u32_e32 v180, s42, v150
	s_add_u32 s22, s8, s20
	ds_read_b128 v[152:155], v164
	ds_read_b128 v[156:159], v164 offset:1024
	ds_read_b128 v[160:163], v164 offset:2048
	ds_read_b128 v[164:167], v164 offset:3072
	ds_read_b128 v[168:171], v180
	ds_read_b128 v[172:175], v180 offset:1024
	ds_read_b128 v[176:179], v180 offset:2048
	ds_read_b128 v[180:183], v180 offset:3072
	s_addc_u32 s23, s9, s21
	s_add_u32 s22, s22, 0x100
	s_addc_u32 s23, s23, 0
	s_add_u32 s49, s44, s20
	s_addc_u32 s50, s45, s21
	s_cmpk_eq_i32 s20, 0x700
	s_cselect_b32 s25, s15, s23
	s_cselect_b32 s24, s46, s22
	s_cselect_b32 s23, s13, s50
	s_cselect_b32 s22, s47, s49
	v_lshl_add_u64 v[206:207], v[144:145], 0, s[20:21]
	s_add_i32 m0, s33, 0xc000
	ds_read_b128 v[186:189], v151
	ds_read_b128 v[190:193], v151 offset:1024
	ds_read_b128 v[194:197], v151 offset:2048
	ds_read_b128 v[198:201], v151 offset:3072
	ds_read_b128 v[202:205], v151 offset:4096
	ds_read_b128 v[210:213], v151 offset:5120
	ds_read_b128 v[214:217], v151 offset:6144
	ds_read_b128 v[218:221], v151 offset:7168
	global_load_lds_dwordx4 v[206:207], off
	v_lshl_add_u64 v[206:207], v[146:147], 0, s[20:21]
	s_add_i32 m0, s33, 0xe000
	s_nop 0
	global_load_lds_dwordx4 v[206:207], off
	s_waitcnt vmcnt(8)
	s_waitcnt lgkmcnt(0)
	s_barrier
	s_setprio 1
	s_waitcnt lgkmcnt(0)
	v_mfma_f32_16x16x32_bf16 v[124:127], v[152:155], v[186:189], v[124:127]
	v_mfma_f32_16x16x32_bf16 v[120:123], v[160:163], v[186:189], v[120:123]
	v_mfma_f32_16x16x32_bf16 v[112:115], v[152:155], v[194:197], v[112:115]
	v_mfma_f32_16x16x32_bf16 v[104:107], v[160:163], v[194:197], v[104:107]
	v_mfma_f32_16x16x32_bf16 v[96:99], v[152:155], v[202:205], v[96:99]
	v_mfma_f32_16x16x32_bf16 v[88:91], v[160:163], v[202:205], v[88:91]
	v_mfma_f32_16x16x32_bf16 v[80:83], v[152:155], v[214:217], v[80:83]
	v_mfma_f32_16x16x32_bf16 v[72:75], v[160:163], v[214:217], v[72:75]
	v_mfma_f32_16x16x32_bf16 v[124:127], v[156:159], v[190:193], v[124:127]
	v_mfma_f32_16x16x32_bf16 v[120:123], v[164:167], v[190:193], v[120:123]
	v_mfma_f32_16x16x32_bf16 v[112:115], v[156:159], v[198:201], v[112:115]
	v_mfma_f32_16x16x32_bf16 v[104:107], v[164:167], v[198:201], v[104:107]
	v_mfma_f32_16x16x32_bf16 v[96:99], v[156:159], v[210:213], v[96:99]
	v_mfma_f32_16x16x32_bf16 v[88:91], v[164:167], v[210:213], v[88:91]
	v_mfma_f32_16x16x32_bf16 v[80:83], v[156:159], v[218:221], v[80:83]
	v_mfma_f32_16x16x32_bf16 v[72:75], v[164:167], v[218:221], v[72:75]
	v_mfma_f32_16x16x32_bf16 v[116:119], v[168:171], v[186:189], v[116:119]
	v_mfma_f32_16x16x32_bf16 v[108:111], v[176:179], v[186:189], v[108:111]
	v_mfma_f32_16x16x32_bf16 v[100:103], v[168:171], v[194:197], v[100:103]
	v_mfma_f32_16x16x32_bf16 v[92:95], v[176:179], v[194:197], v[92:95]
	v_mfma_f32_16x16x32_bf16 v[84:87], v[168:171], v[202:205], v[84:87]
	v_mfma_f32_16x16x32_bf16 v[76:79], v[176:179], v[202:205], v[76:79]
	v_mfma_f32_16x16x32_bf16 v[68:71], v[168:171], v[214:217], v[68:71]
	v_mfma_f32_16x16x32_bf16 v[64:67], v[176:179], v[214:217], v[64:67]
	v_mfma_f32_16x16x32_bf16 v[116:119], v[172:175], v[190:193], v[116:119]
	v_mfma_f32_16x16x32_bf16 v[108:111], v[180:183], v[190:193], v[108:111]
	v_mfma_f32_16x16x32_bf16 v[100:103], v[172:175], v[198:201], v[100:103]
	v_mfma_f32_16x16x32_bf16 v[92:95], v[180:183], v[198:201], v[92:95]
	v_mfma_f32_16x16x32_bf16 v[84:87], v[172:175], v[210:213], v[84:87]
	v_mfma_f32_16x16x32_bf16 v[76:79], v[180:183], v[210:213], v[76:79]
	v_mfma_f32_16x16x32_bf16 v[68:71], v[172:175], v[218:221], v[68:71]
	v_mfma_f32_16x16x32_bf16 v[64:67], v[180:183], v[218:221], v[64:67]
	s_setprio 0
	s_barrier
	s_add_i32 s49, s41, s31
	v_lshl_add_u64 v[206:207], s[22:23], 0, v[130:131]
	s_mov_b32 m0, s49
	ds_read_b128 v[186:189], v151 offset:16384
	ds_read_b128 v[190:193], v151 offset:17408
	ds_read_b128 v[194:197], v151 offset:18432
	ds_read_b128 v[198:201], v151 offset:19456
	ds_read_b128 v[202:205], v151 offset:20480
	ds_read_b128 v[210:213], v151 offset:21504
	ds_read_b128 v[214:217], v151 offset:22528
	ds_read_b128 v[218:221], v151 offset:23552
	global_load_lds_dwordx4 v[206:207], off
	s_add_i32 m0, s49, 0x2000
	s_add_u32 s50, s22, 0x40000
	v_lshl_add_u64 v[222:223], s[22:23], 0, v[134:135]
	s_addc_u32 s51, s23, 0
	s_add_i32 s49, s42, s31
	global_load_lds_dwordx4 v[222:223], off
	v_lshl_add_u64 v[224:225], s[50:51], 0, v[130:131]
	s_mov_b32 m0, s49
	v_lshl_add_u64 v[226:227], s[24:25], 0, v[132:133]
	global_load_lds_dwordx4 v[224:225], off
	v_lshl_add_u64 v[224:225], s[50:51], 0, v[134:135]
	s_add_i32 m0, s49, 0x2000
	s_nop 0
	global_load_lds_dwordx4 v[224:225], off
	v_lshl_add_u64 v[224:225], s[24:25], 0, v[128:129]
	s_mov_b32 m0, s33
	s_nop 0
	global_load_lds_dwordx4 v[224:225], off
	s_mov_b32 m0, s34
	s_nop 0
	global_load_lds_dwordx4 v[226:227], off
	s_waitcnt vmcnt(8)
	s_waitcnt lgkmcnt(0)
	s_barrier
; #define PG8_STAGE(bufoff, gbase, voff) do { _Pragma("unroll") for (int _i = 0; _i < 2; ++_i) \
;         __builtin_amdgcn_global_load_lds((const unsigned*)((const char*)(gbase) + (voff)[_i]), (PG8_LAS unsigned*)(lds + (bufoff) + ldsw + _i * 8192), 16, 0, 0); } while (0)
; #define PG8_LDA(dst, b, h) do { _Pragma("unroll") for (int m = 0; m < 4; ++m) _Pragma("unroll") for (int k = 0; k < 2; ++k) dst[m][k] = *(const PG8_LAS bf16x8*)(lds + PG8_SA(b, h) + aoff + m * 2048 + k * 1024); } while (0)
; #define PG8_LDB(dst, b, h) do { _Pragma("unroll") for (int n = 0; n < 2; ++n) _Pragma("unroll") for (int k = 0; k < 2; ++k) dst[n][k] = *(const PG8_LAS bf16x8*)(lds + PG8_SB(b, h) + boff + n * 2048 + k * 1024); } while (0)
; #define PG8_MMA(ai, bj, At, Bt) do { __builtin_amdgcn_s_setprio(1); _Pragma("unroll") for (int m = 0; m < 4; ++m) _Pragma("unroll") for (int n = 0; n < 2; ++n) _Pragma("unroll") for (int k = 0; k < 2; ++k) \
;         acc[ai][bj][m][n] = __builtin_amdgcn_mfma_f32_16x16x32_bf16(Bt[n][k], At[m][k], acc[ai][bj][m][n], 0, 0, 0); __builtin_amdgcn_s_setprio(0); } while (0)
; #define PG8_WAIT_V(n) asm volatile("s_waitcnt vmcnt(" #n ")" ::: "memory")
; #define PG8_WAIT_L(n) asm volatile("s_waitcnt lgkmcnt(" #n ")" ::: "memory")
; #define PG8_BAR __builtin_amdgcn_s_barrier()
; #define PG8_SCHED __builtin_amdgcn_sched_barrier(0)
; template <class Epi, class Sched, bool ALIGN_EPI = false, bool SP2 = false>
; __device__ __forceinline__ void gemm_phase(PG8_LAS unsigned char* lds, const Gemm g, const Sched& S, const Epi& E, const int wid) {
;     ...
;             PG8_WAIT_V(8); PG8_WAIT_L(0); PG8_BAR; PG8_MMA(1, 0, At, B0); PG8_MMA(1, 1, At, B1); PG8_BAR; PG8_SCHED;
;             PG8_LDB(B0, 1, 0); PG8_LDB(B1, 1, 1); PG8_SCHED; PG8_LDA(At, 1, 0); PG8_STAGE(PG8_SA(0, 1), a2 + hstep, voffA);
;             PG8_WAIT_V(8); PG8_WAIT_L(0); PG8_BAR; PG8_MMA(0, 0, At, B0); PG8_MMA(0, 1, At, B1); PG8_BAR; PG8_SCHED;
	s_setprio 1
	s_waitcnt lgkmcnt(0)
	v_mfma_f32_16x16x32_bf16 v[60:63], v[152:155], v[186:189], v[60:63]
	v_mfma_f32_16x16x32_bf16 v[56:59], v[160:163], v[186:189], v[56:59]
	v_mfma_f32_16x16x32_bf16 v[44:47], v[152:155], v[194:197], v[44:47]
	v_mfma_f32_16x16x32_bf16 v[40:43], v[160:163], v[194:197], v[40:43]
	v_mfma_f32_16x16x32_bf16 v[28:31], v[152:155], v[202:205], v[28:31]
	v_mfma_f32_16x16x32_bf16 v[24:27], v[160:163], v[202:205], v[24:27]
	v_mfma_f32_16x16x32_bf16 v[12:15], v[152:155], v[214:217], v[12:15]
	v_mfma_f32_16x16x32_bf16 v[8:11], v[160:163], v[214:217], v[8:11]
	v_mfma_f32_16x16x32_bf16 v[60:63], v[156:159], v[190:193], v[60:63]
	v_mfma_f32_16x16x32_bf16 v[56:59], v[164:167], v[190:193], v[56:59]
	v_mfma_f32_16x16x32_bf16 v[44:47], v[156:159], v[198:201], v[44:47]
	v_mfma_f32_16x16x32_bf16 v[40:43], v[164:167], v[198:201], v[40:43]
	v_mfma_f32_16x16x32_bf16 v[28:31], v[156:159], v[210:213], v[28:31]
	v_mfma_f32_16x16x32_bf16 v[24:27], v[164:167], v[210:213], v[24:27]
	v_mfma_f32_16x16x32_bf16 v[12:15], v[156:159], v[218:221], v[12:15]
	v_mfma_f32_16x16x32_bf16 v[8:11], v[164:167], v[218:221], v[8:11]
	v_mfma_f32_16x16x32_bf16 v[52:55], v[168:171], v[186:189], v[52:55]
	v_mfma_f32_16x16x32_bf16 v[48:51], v[176:179], v[186:189], v[48:51]
	v_mfma_f32_16x16x32_bf16 v[36:39], v[168:171], v[194:197], v[36:39]
	v_mfma_f32_16x16x32_bf16 v[32:35], v[176:179], v[194:197], v[32:35]
	v_mfma_f32_16x16x32_bf16 v[20:23], v[168:171], v[202:205], v[20:23]
	v_mfma_f32_16x16x32_bf16 v[16:19], v[176:179], v[202:205], v[16:19]
	v_mfma_f32_16x16x32_bf16 v[4:7], v[168:171], v[214:217], v[4:7]
	v_mfma_f32_16x16x32_bf16 v[0:3], v[176:179], v[214:217], v[0:3]
	v_mfma_f32_16x16x32_bf16 v[52:55], v[172:175], v[190:193], v[52:55]
	v_mfma_f32_16x16x32_bf16 v[48:51], v[180:183], v[190:193], v[48:51]
	v_mfma_f32_16x16x32_bf16 v[36:39], v[172:175], v[198:201], v[36:39]
	v_mfma_f32_16x16x32_bf16 v[32:35], v[180:183], v[198:201], v[32:35]
	v_mfma_f32_16x16x32_bf16 v[20:23], v[172:175], v[210:213], v[20:23]
	v_mfma_f32_16x16x32_bf16 v[16:19], v[180:183], v[210:213], v[16:19]
	v_mfma_f32_16x16x32_bf16 v[4:7], v[172:175], v[218:221], v[4:7]
	v_mfma_f32_16x16x32_bf16 v[0:3], v[180:183], v[218:221], v[0:3]
	s_setprio 0
	s_barrier
	s_add_i32 s49, 0, 0x18000
	s_add_i32 s50, 0, 0x1c000
	v_add_u32_e32 v164, s49, v150
	v_add_u32_e32 v180, s50, v150
	ds_read_b128 v[152:155], v164
	ds_read_b128 v[156:159], v164 offset:1024
	ds_read_b128 v[160:163], v164 offset:2048
	ds_read_b128 v[164:167], v164 offset:3072
	ds_read_b128 v[168:171], v180
	ds_read_b128 v[172:175], v180 offset:1024
	ds_read_b128 v[176:179], v180 offset:2048
	ds_read_b128 v[180:183], v180 offset:3072
	s_add_u32 s24, s24, 0x40000
	s_addc_u32 s25, s25, 0
	s_mov_b32 m0, s35
	v_lshl_add_u64 v[228:229], s[24:25], 0, v[128:129]
	ds_read_b128 v[186:189], v151 offset:32768
	ds_read_b128 v[190:193], v151 offset:33792
	ds_read_b128 v[194:197], v151 offset:34816
	ds_read_b128 v[198:201], v151 offset:35840
	ds_read_b128 v[202:205], v151 offset:36864
	ds_read_b128 v[210:213], v151 offset:37888
	ds_read_b128 v[214:217], v151 offset:38912
	ds_read_b128 v[218:221], v151 offset:39936
	global_load_lds_dwordx4 v[228:229], off
	v_lshl_add_u64 v[228:229], s[24:25], 0, v[132:133]
	s_mov_b32 m0, s36
	s_nop 0
	global_load_lds_dwordx4 v[228:229], off
	s_waitcnt vmcnt(8)
	s_waitcnt lgkmcnt(0)
	s_barrier
	s_setprio 1
	s_waitcnt lgkmcnt(0)
	v_mfma_f32_16x16x32_bf16 v[124:127], v[152:155], v[186:189], v[124:127]
	v_mfma_f32_16x16x32_bf16 v[120:123], v[160:163], v[186:189], v[120:123]
	v_mfma_f32_16x16x32_bf16 v[112:115], v[152:155], v[194:197], v[112:115]
	v_mfma_f32_16x16x32_bf16 v[104:107], v[160:163], v[194:197], v[104:107]
	v_mfma_f32_16x16x32_bf16 v[96:99], v[152:155], v[202:205], v[96:99]
	v_mfma_f32_16x16x32_bf16 v[88:91], v[160:163], v[202:205], v[88:91]
	v_mfma_f32_16x16x32_bf16 v[80:83], v[152:155], v[214:217], v[80:83]
	v_mfma_f32_16x16x32_bf16 v[72:75], v[160:163], v[214:217], v[72:75]
	v_mfma_f32_16x16x32_bf16 v[124:127], v[156:159], v[190:193], v[124:127]
	v_mfma_f32_16x16x32_bf16 v[120:123], v[164:167], v[190:193], v[120:123]
	v_mfma_f32_16x16x32_bf16 v[112:115], v[156:159], v[198:201], v[112:115]
	v_mfma_f32_16x16x32_bf16 v[104:107], v[164:167], v[198:201], v[104:107]
	v_mfma_f32_16x16x32_bf16 v[96:99], v[156:159], v[210:213], v[96:99]
	v_mfma_f32_16x16x32_bf16 v[88:91], v[164:167], v[210:213], v[88:91]
	v_mfma_f32_16x16x32_bf16 v[80:83], v[156:159], v[218:221], v[80:83]
	v_mfma_f32_16x16x32_bf16 v[72:75], v[164:167], v[218:221], v[72:75]
	v_mfma_f32_16x16x32_bf16 v[116:119], v[168:171], v[186:189], v[116:119]
	v_mfma_f32_16x16x32_bf16 v[108:111], v[176:179], v[186:189], v[108:111]
	v_mfma_f32_16x16x32_bf16 v[100:103], v[168:171], v[194:197], v[100:103]
	v_mfma_f32_16x16x32_bf16 v[92:95], v[176:179], v[194:197], v[92:95]
	v_mfma_f32_16x16x32_bf16 v[84:87], v[168:171], v[202:205], v[84:87]
	v_mfma_f32_16x16x32_bf16 v[76:79], v[176:179], v[202:205], v[76:79]
	v_mfma_f32_16x16x32_bf16 v[68:71], v[168:171], v[214:217], v[68:71]
	v_mfma_f32_16x16x32_bf16 v[64:67], v[176:179], v[214:217], v[64:67]
	v_mfma_f32_16x16x32_bf16 v[116:119], v[172:175], v[190:193], v[116:119]
	v_mfma_f32_16x16x32_bf16 v[108:111], v[180:183], v[190:193], v[108:111]
	v_mfma_f32_16x16x32_bf16 v[100:103], v[172:175], v[198:201], v[100:103]
	v_mfma_f32_16x16x32_bf16 v[92:95], v[180:183], v[198:201], v[92:95]
	v_mfma_f32_16x16x32_bf16 v[84:87], v[172:175], v[210:213], v[84:87]
	v_mfma_f32_16x16x32_bf16 v[76:79], v[180:183], v[210:213], v[76:79]
	v_mfma_f32_16x16x32_bf16 v[68:71], v[172:175], v[218:221], v[68:71]
	v_mfma_f32_16x16x32_bf16 v[64:67], v[180:183], v[218:221], v[64:67]
	s_setprio 0
	s_barrier
; #define PG8_STAGE(bufoff, gbase, voff) do { _Pragma("unroll") for (int _i = 0; _i < 2; ++_i) \
;         __builtin_amdgcn_global_load_lds((const unsigned*)((const char*)(gbase) + (voff)[_i]), (PG8_LAS unsigned*)(lds + (bufoff) + ldsw + _i * 8192), 16, 0, 0); } while (0)
; #define PG8_LDA(dst, b, h) do { _Pragma("unroll") for (int m = 0; m < 4; ++m) _Pragma("unroll") for (int k = 0; k < 2; ++k) dst[m][k] = *(const PG8_LAS bf16x8*)(lds + PG8_SA(b, h) + aoff + m * 2048 + k * 1024); } while (0)
; #define PG8_MMA(ai, bj, At, Bt) do { __builtin_amdgcn_s_setprio(1); _Pragma("unroll") for (int m = 0; m < 4; ++m) _Pragma("unroll") for (int n = 0; n < 2; ++n) _Pragma("unroll") for (int k = 0; k < 2; ++k) \
;         acc[ai][bj][m][n] = __builtin_amdgcn_mfma_f32_16x16x32_bf16(Bt[n][k], At[m][k], acc[ai][bj][m][n], 0, 0, 0); __builtin_amdgcn_s_setprio(0); } while (0)
; #define PG8_WAIT_V(n) asm volatile("s_waitcnt vmcnt(" #n ")" ::: "memory")
; #define PG8_WAIT_L(n) asm volatile("s_waitcnt lgkmcnt(" #n ")" ::: "memory")
; #define PG8_BAR __builtin_amdgcn_s_barrier()
; #define PG8_SCHED __builtin_amdgcn_sched_barrier(0)
; template <class Epi, class Sched, bool ALIGN_EPI = false, bool SP2 = false>
; __device__ __forceinline__ void gemm_phase(PG8_LAS unsigned char* lds, const Gemm g, const Sched& S, const Epi& E, const int wid) {
;     ...
;             PG8_LDA(At, 1, 1); PG8_STAGE(PG8_SB(1, 0), b3, voffB); PG8_STAGE(PG8_SB(1, 1), b3 + hstep, voffB); PG8_STAGE(PG8_SA(1, 0), a3, voffA);
;             PG8_WAIT_V(8); PG8_WAIT_L(0); PG8_BAR; PG8_MMA(1, 0, At, B0); PG8_MMA(1, 1, At, B1); PG8_BAR; PG8_SCHED;
;     ...
;         if (!has_next) break;
; #pragma unroll
;         for (int a = 0; a < 2; ++a)
; #pragma unroll
;             for (int b = 0; b < 2; ++b)
; #pragma unroll
;                 for (int m = 0; m < 4; ++m)
; #pragma unroll
;                     for (int n = 0; n < 2; ++n) acc[a][b][m][n] = (f32x4){0.f, 0.f, 0.f, 0.f};
;         cur = nxt; cA = nA; cB = nB; ++ui;
	s_add_i32 s24, s49, s31
	v_lshl_add_u64 v[206:207], v[206:207], 0, s[10:11]
	s_mov_b32 m0, s24
	ds_read_b128 v[186:189], v151 offset:49152
	ds_read_b128 v[190:193], v151 offset:50176
	ds_read_b128 v[194:197], v151 offset:51200
	ds_read_b128 v[198:201], v151 offset:52224
	ds_read_b128 v[202:205], v151 offset:53248
	ds_read_b128 v[210:213], v151 offset:54272
	ds_read_b128 v[214:217], v151 offset:55296
	ds_read_b128 v[218:221], v151 offset:56320
	global_load_lds_dwordx4 v[206:207], off
	s_add_i32 m0, s24, 0x2000
	s_add_u32 s22, s22, 0x40080
	v_lshl_add_u64 v[206:207], v[222:223], 0, s[10:11]
	s_addc_u32 s23, s23, 0
	s_add_i32 s24, s50, s31
	global_load_lds_dwordx4 v[206:207], off
	v_lshl_add_u64 v[206:207], s[22:23], 0, v[130:131]
	s_mov_b32 m0, s24
	s_nop 0
	global_load_lds_dwordx4 v[206:207], off
	v_lshl_add_u64 v[206:207], s[22:23], 0, v[134:135]
	s_add_i32 m0, s24, 0x2000
	s_nop 0
	global_load_lds_dwordx4 v[206:207], off
	v_lshl_add_u64 v[206:207], v[224:225], 0, s[10:11]
	s_mov_b32 m0, s38
	s_nop 0
	global_load_lds_dwordx4 v[206:207], off
	v_lshl_add_u64 v[206:207], v[226:227], 0, s[10:11]
	s_mov_b32 m0, s39
	s_nop 0
	global_load_lds_dwordx4 v[206:207], off
	s_waitcnt vmcnt(8)
	s_waitcnt lgkmcnt(0)
	s_barrier
	s_setprio 1
	s_waitcnt lgkmcnt(0)
	v_mfma_f32_16x16x32_bf16 v[60:63], v[152:155], v[186:189], v[60:63]
	v_mfma_f32_16x16x32_bf16 v[56:59], v[160:163], v[186:189], v[56:59]
	v_mfma_f32_16x16x32_bf16 v[44:47], v[152:155], v[194:197], v[44:47]
	v_mfma_f32_16x16x32_bf16 v[40:43], v[160:163], v[194:197], v[40:43]
	v_mfma_f32_16x16x32_bf16 v[28:31], v[152:155], v[202:205], v[28:31]
	v_mfma_f32_16x16x32_bf16 v[24:27], v[160:163], v[202:205], v[24:27]
	v_mfma_f32_16x16x32_bf16 v[12:15], v[152:155], v[214:217], v[12:15]
	v_mfma_f32_16x16x32_bf16 v[8:11], v[160:163], v[214:217], v[8:11]
	v_mfma_f32_16x16x32_bf16 v[60:63], v[156:159], v[190:193], v[60:63]
	v_mfma_f32_16x16x32_bf16 v[56:59], v[164:167], v[190:193], v[56:59]
	v_mfma_f32_16x16x32_bf16 v[44:47], v[156:159], v[198:201], v[44:47]
	v_mfma_f32_16x16x32_bf16 v[40:43], v[164:167], v[198:201], v[40:43]
	v_mfma_f32_16x16x32_bf16 v[28:31], v[156:159], v[210:213], v[28:31]
	v_mfma_f32_16x16x32_bf16 v[24:27], v[164:167], v[210:213], v[24:27]
	v_mfma_f32_16x16x32_bf16 v[12:15], v[156:159], v[218:221], v[12:15]
	v_mfma_f32_16x16x32_bf16 v[8:11], v[164:167], v[218:221], v[8:11]
	v_mfma_f32_16x16x32_bf16 v[52:55], v[168:171], v[186:189], v[52:55]
	v_mfma_f32_16x16x32_bf16 v[48:51], v[176:179], v[186:189], v[48:51]
	v_mfma_f32_16x16x32_bf16 v[36:39], v[168:171], v[194:197], v[36:39]
	v_mfma_f32_16x16x32_bf16 v[32:35], v[176:179], v[194:197], v[32:35]
	v_mfma_f32_16x16x32_bf16 v[20:23], v[168:171], v[202:205], v[20:23]
	v_mfma_f32_16x16x32_bf16 v[16:19], v[176:179], v[202:205], v[16:19]
	v_mfma_f32_16x16x32_bf16 v[4:7], v[168:171], v[214:217], v[4:7]
	v_mfma_f32_16x16x32_bf16 v[0:3], v[176:179], v[214:217], v[0:3]
	v_mfma_f32_16x16x32_bf16 v[52:55], v[172:175], v[190:193], v[52:55]
	v_mfma_f32_16x16x32_bf16 v[48:51], v[180:183], v[190:193], v[48:51]
	v_mfma_f32_16x16x32_bf16 v[36:39], v[172:175], v[198:201], v[36:39]
	v_mfma_f32_16x16x32_bf16 v[32:35], v[180:183], v[198:201], v[32:35]
	v_mfma_f32_16x16x32_bf16 v[20:23], v[172:175], v[210:213], v[20:23]
	v_mfma_f32_16x16x32_bf16 v[16:19], v[180:183], v[210:213], v[16:19]
	v_mfma_f32_16x16x32_bf16 v[4:7], v[172:175], v[218:221], v[4:7]
	v_mfma_f32_16x16x32_bf16 v[0:3], v[180:183], v[218:221], v[0:3]
	s_setprio 0
	s_barrier
	s_add_i32 s48, s48, 2
	s_add_u32 s20, s20, 0x100
	s_addc_u32 s21, s21, 0
	s_cmp_gt_u32 s48, 13
	s_cbranch_scc0 .LBB0_1786
	s_add_u32 s20, s44, 0xffffff00
	s_addc_u32 s21, s45, -1
	s_andn2_b64 vcc, exec, s[6:7]
	s_cbranch_vccnz .LBB0_1777
	v_mov_b32_e32 v0, 0
	s_mov_b32 s2, s12
	s_mov_b32 s0, s14
	s_mov_b64 s[8:9], s[18:19]
	s_mov_b32 s40, s43
	v_mov_b32_e32 v1, v0
	v_mov_b32_e32 v2, v0
	v_mov_b32_e32 v3, v0
	v_mov_b32_e32 v4, v0
	v_mov_b32_e32 v5, v0
	v_mov_b32_e32 v6, v0
	v_mov_b32_e32 v7, v0
	v_mov_b32_e32 v16, v0
	v_mov_b32_e32 v17, v0
	v_mov_b32_e32 v18, v0
	v_mov_b32_e32 v19, v0
	v_mov_b32_e32 v20, v0
	v_mov_b32_e32 v21, v0
	v_mov_b32_e32 v22, v0
	v_mov_b32_e32 v23, v0
	v_mov_b32_e32 v32, v0
	v_mov_b32_e32 v33, v0
	v_mov_b32_e32 v34, v0
	v_mov_b32_e32 v35, v0
	v_mov_b32_e32 v36, v0
	v_mov_b32_e32 v37, v0
	v_mov_b32_e32 v38, v0
	v_mov_b32_e32 v39, v0
	v_mov_b32_e32 v48, v0
	v_mov_b32_e32 v49, v0
	v_mov_b32_e32 v50, v0
	v_mov_b32_e32 v51, v0
	v_mov_b32_e32 v52, v0
	v_mov_b32_e32 v53, v0
	v_mov_b32_e32 v54, v0
	v_mov_b32_e32 v55, v0
	v_mov_b32_e32 v8, v0
	v_mov_b32_e32 v9, v0
	v_mov_b32_e32 v10, v0
	v_mov_b32_e32 v11, v0
	v_mov_b32_e32 v12, v0
	v_mov_b32_e32 v13, v0
	v_mov_b32_e32 v14, v0
	v_mov_b32_e32 v15, v0
	v_mov_b32_e32 v24, v0
	v_mov_b32_e32 v25, v0
	v_mov_b32_e32 v26, v0
	v_mov_b32_e32 v27, v0
	v_mov_b32_e32 v28, v0
	v_mov_b32_e32 v29, v0
	v_mov_b32_e32 v30, v0
	v_mov_b32_e32 v31, v0
	v_mov_b32_e32 v40, v0
	v_mov_b32_e32 v41, v0
	v_mov_b32_e32 v42, v0
	v_mov_b32_e32 v43, v0
	v_mov_b32_e32 v44, v0
	v_mov_b32_e32 v45, v0
	v_mov_b32_e32 v46, v0
	v_mov_b32_e32 v47, v0
	v_mov_b32_e32 v56, v0
	v_mov_b32_e32 v57, v0
	v_mov_b32_e32 v58, v0
	v_mov_b32_e32 v59, v0
	v_mov_b32_e32 v60, v0
	v_mov_b32_e32 v61, v0
	v_mov_b32_e32 v62, v0
	v_mov_b32_e32 v63, v0
	v_mov_b32_e32 v64, v0
	v_mov_b32_e32 v65, v0
	v_mov_b32_e32 v66, v0
	v_mov_b32_e32 v67, v0
	v_mov_b32_e32 v68, v0
	v_mov_b32_e32 v69, v0
	v_mov_b32_e32 v70, v0
	v_mov_b32_e32 v71, v0
	v_mov_b32_e32 v76, v0
	v_mov_b32_e32 v77, v0
	v_mov_b32_e32 v78, v0
	v_mov_b32_e32 v79, v0
	v_mov_b32_e32 v84, v0
	v_mov_b32_e32 v85, v0
	v_mov_b32_e32 v86, v0
	v_mov_b32_e32 v87, v0
	v_mov_b32_e32 v92, v0
	v_mov_b32_e32 v93, v0
	v_mov_b32_e32 v94, v0
	v_mov_b32_e32 v95, v0
	v_mov_b32_e32 v100, v0
	v_mov_b32_e32 v101, v0
	v_mov_b32_e32 v102, v0
	v_mov_b32_e32 v103, v0
	v_mov_b32_e32 v108, v0
	v_mov_b32_e32 v109, v0
	v_mov_b32_e32 v110, v0
	v_mov_b32_e32 v111, v0
	v_mov_b32_e32 v116, v0
	v_mov_b32_e32 v117, v0
	v_mov_b32_e32 v118, v0
	v_mov_b32_e32 v119, v0
	v_mov_b32_e32 v72, v0
	v_mov_b32_e32 v73, v0
	v_mov_b32_e32 v74, v0
	v_mov_b32_e32 v75, v0
	v_mov_b32_e32 v80, v0
	v_mov_b32_e32 v81, v0
	v_mov_b32_e32 v82, v0
	v_mov_b32_e32 v83, v0
	v_mov_b32_e32 v88, v0
	v_mov_b32_e32 v89, v0
	v_mov_b32_e32 v90, v0
	v_mov_b32_e32 v91, v0
	v_mov_b32_e32 v96, v0
	v_mov_b32_e32 v97, v0
	v_mov_b32_e32 v98, v0
	v_mov_b32_e32 v99, v0
	v_mov_b32_e32 v104, v0
	v_mov_b32_e32 v105, v0
	v_mov_b32_e32 v106, v0
	v_mov_b32_e32 v107, v0
	v_mov_b32_e32 v112, v0
	v_mov_b32_e32 v113, v0
	v_mov_b32_e32 v114, v0
	v_mov_b32_e32 v115, v0
	v_mov_b32_e32 v120, v0
	v_mov_b32_e32 v121, v0
	v_mov_b32_e32 v122, v0
	v_mov_b32_e32 v123, v0
	v_mov_b32_e32 v124, v0
	v_mov_b32_e32 v125, v0
	v_mov_b32_e32 v126, v0
	v_mov_b32_e32 v127, v0
	s_andn2_b64 vcc, exec, s[4:5]
	s_cbranch_vccnz .LBB0_1778

; template <class Epi, class Sched, bool ALIGN_EPI = false, bool SP2 = false>
; __device__ __forceinline__ void gemm_phase(PG8_LAS unsigned char* lds, const Gemm g, const Sched& S, const Epi& E, const int wid) {
;     ...
;         const bool has_next = S.next(ui + 1, nxt);
;         const char* nA = has_next ? (const char*)g.A + (size_t)nxt.pm * tstep : cA; const char* nB = has_next ? (const char*)g.Bt + (size_t)nxt.pn * tstep : cB;
;         for (int t = 0; t < nt; t += 2) {
;             const bool last = (t == nt - 2);
;             const char* a1 = cA + (size_t)(t + 1) * kstep;
;             const char* a2 = last ? nA : cA + (size_t)(t + 2) * kstep; const char* b2 = last ? nB : cB + (size_t)(t + 2) * kstep;
;             const char* a3 = a2 + kstep; const char* b3 = b2 + kstep;
.LBB0_1911:
	s_ashr_i32 s15, s14, 31
	s_lshl_b64 s[16:17], s[14:15], 19
	s_add_u32 s16, s80, s16
	s_addc_u32 s17, s81, s17
	s_and_b64 s[18:19], s[4:5], exec
	s_cselect_b32 s15, s17, s23
	s_cselect_b32 s42, s16, s22
	s_ashr_i32 s13, s12, 31
	s_lshl_b64 s[18:19], s[12:13], 19
	s_add_u32 s18, s10, s18
	s_addc_u32 s19, s11, s19
	s_and_b64 s[26:27], s[4:5], exec
	s_cselect_b32 s13, s19, s25
	s_cselect_b32 s43, s18, s24
	s_add_u32 s22, s22, 0x40080
	s_addc_u32 s23, s23, 0
	s_add_u32 s44, s24, 0x100

; template <class Epi, class Sched, bool ALIGN_EPI = false, bool SP2 = false>
; __device__ __forceinline__ void gemm_phase(PG8_LAS unsigned char* lds, const Gemm g, const Sched& S, const Epi& E, const int wid) {
;     ...
;         for (int t = 0; t < nt; t += 2) {
;             const bool last = (t == nt - 2);
	s_addc_u32 s45, s25, 0
	s_mov_b32 s46, -2


; #define PG8_STAGE(bufoff, gbase, voff) do { _Pragma("unroll") for (int _i = 0; _i < 2; ++_i) \
;         __builtin_amdgcn_global_load_lds((const unsigned*)((const char*)(gbase) + (voff)[_i]), (PG8_LAS unsigned*)(lds + (bufoff) + ldsw + _i * 8192), 16, 0, 0); } while (0)
; #define PG8_LDA(dst, b, h) do { _Pragma("unroll") for (int m = 0; m < 4; ++m) _Pragma("unroll") for (int k = 0; k < 2; ++k) dst[m][k] = *(const PG8_LAS bf16x8*)(lds + PG8_SA(b, h) + aoff + m * 2048 + k * 1024); } while (0)
; #define PG8_LDB(dst, b, h) do { _Pragma("unroll") for (int n = 0; n < 2; ++n) _Pragma("unroll") for (int k = 0; k < 2; ++k) dst[n][k] = *(const PG8_LAS bf16x8*)(lds + PG8_SB(b, h) + boff + n * 2048 + k * 1024); } while (0)
; #define PG8_MMA(ai, bj, At, Bt) do { __builtin_amdgcn_s_setprio(1); _Pragma("unroll") for (int m = 0; m < 4; ++m) _Pragma("unroll") for (int n = 0; n < 2; ++n) _Pragma("unroll") for (int k = 0; k < 2; ++k) \
;         acc[ai][bj][m][n] = __builtin_amdgcn_mfma_f32_16x16x32_bf16(Bt[n][k], At[m][k], acc[ai][bj][m][n], 0, 0, 0); __builtin_amdgcn_s_setprio(0); } while (0)
; #define PG8_WAIT_V(n) asm volatile("s_waitcnt vmcnt(" #n ")" ::: "memory")
; #define PG8_WAIT_L(n) asm volatile("s_waitcnt lgkmcnt(" #n ")" ::: "memory")
; #define PG8_BAR __builtin_amdgcn_s_barrier()
; #define PG8_SCHED __builtin_amdgcn_sched_barrier(0)
; template <class Epi, class Sched, bool ALIGN_EPI = false, bool SP2 = false>
; __device__ __forceinline__ void gemm_phase(PG8_LAS unsigned char* lds, const Gemm g, const Sched& S, const Epi& E, const int wid) {
;     ...
;             PG8_LDB(B0, 0, 0); PG8_LDB(B1, 0, 1); PG8_SCHED; PG8_LDA(At, 0, 0); PG8_STAGE(PG8_SA(1, 1), a1 + hstep, voffA);
;             PG8_WAIT_V(8); PG8_WAIT_L(0); PG8_BAR; PG8_MMA(0, 0, At, B0); PG8_MMA(0, 1, At, B1); PG8_BAR; PG8_SCHED;
;             PG8_LDA(At, 0, 1); PG8_STAGE(PG8_SB(0, 0), b2, voffB); PG8_STAGE(PG8_SB(0, 1), b2 + hstep, voffB); PG8_STAGE(PG8_SA(0, 0), a2, voffA);
;             PG8_WAIT_V(8); PG8_WAIT_L(0); PG8_BAR; PG8_MMA(1, 0, At, B0); PG8_MMA(1, 1, At, B1); PG8_BAR; PG8_SCHED;
	ds_read_b128 v[144:147], v151
	ds_read_b128 v[154:157], v151 offset:1024
	ds_read_b128 v[158:161], v151 offset:2048
	ds_read_b128 v[162:165], v151 offset:3072
	ds_read_b128 v[166:169], v152
	ds_read_b128 v[170:173], v152 offset:1024
	ds_read_b128 v[174:177], v152 offset:2048
	ds_read_b128 v[178:181], v152 offset:3072
	s_add_u32 s24, s22, 0xfffc0080
	s_addc_u32 s25, s23, -1
	s_cmp_eq_u32 s46, 12
	s_cselect_b32 s27, s15, s25
	s_cselect_b32 s26, s42, s24
	s_cselect_b32 s25, s13, s45
	s_cselect_b32 s24, s43, s44
	v_lshl_add_u64 v[206:207], s[22:23], 0, v[136:137]
	s_add_i32 m0, s21, 0xc000
	ds_read_b128 v[182:185], v153
	ds_read_b128 v[186:189], v153 offset:1024
	ds_read_b128 v[190:193], v153 offset:2048
	ds_read_b128 v[194:197], v153 offset:3072
	ds_read_b128 v[198:201], v153 offset:4096
	ds_read_b128 v[202:205], v153 offset:5120
	ds_read_b128 v[210:213], v153 offset:6144
	ds_read_b128 v[214:217], v153 offset:7168
	global_load_lds_dwordx4 v[206:207], off
	v_lshl_add_u64 v[206:207], s[22:23], 0, v[138:139]
	s_add_i32 m0, s21, 0xe000
	s_nop 0
	global_load_lds_dwordx4 v[206:207], off
	s_waitcnt vmcnt(8)
	s_waitcnt lgkmcnt(0)
	s_barrier
	s_setprio 1
	s_waitcnt lgkmcnt(0)
	v_mfma_f32_16x16x32_bf16 v[124:127], v[144:147], v[182:185], 0
	v_mfma_f32_16x16x32_bf16 v[116:119], v[158:161], v[182:185], 0
	v_mfma_f32_16x16x32_bf16 v[108:111], v[144:147], v[190:193], 0
	v_mfma_f32_16x16x32_bf16 v[100:103], v[158:161], v[190:193], 0
	v_mfma_f32_16x16x32_bf16 v[92:95], v[144:147], v[198:201], 0
	v_mfma_f32_16x16x32_bf16 v[84:87], v[158:161], v[198:201], 0
	v_mfma_f32_16x16x32_bf16 v[76:79], v[144:147], v[210:213], 0
	v_mfma_f32_16x16x32_bf16 v[68:71], v[158:161], v[210:213], 0
	v_mfma_f32_16x16x32_bf16 v[124:127], v[154:157], v[186:189], v[124:127]
	v_mfma_f32_16x16x32_bf16 v[116:119], v[162:165], v[186:189], v[116:119]
	v_mfma_f32_16x16x32_bf16 v[108:111], v[154:157], v[194:197], v[108:111]
	v_mfma_f32_16x16x32_bf16 v[100:103], v[162:165], v[194:197], v[100:103]
	v_mfma_f32_16x16x32_bf16 v[92:95], v[154:157], v[202:205], v[92:95]
	v_mfma_f32_16x16x32_bf16 v[84:87], v[162:165], v[202:205], v[84:87]
	v_mfma_f32_16x16x32_bf16 v[76:79], v[154:157], v[214:217], v[76:79]
	v_mfma_f32_16x16x32_bf16 v[68:71], v[162:165], v[214:217], v[68:71]
	v_mfma_f32_16x16x32_bf16 v[120:123], v[166:169], v[182:185], 0
	v_mfma_f32_16x16x32_bf16 v[112:115], v[174:177], v[182:185], 0
	v_mfma_f32_16x16x32_bf16 v[104:107], v[166:169], v[190:193], 0
	v_mfma_f32_16x16x32_bf16 v[96:99], v[174:177], v[190:193], 0
	v_mfma_f32_16x16x32_bf16 v[88:91], v[166:169], v[198:201], 0
	v_mfma_f32_16x16x32_bf16 v[80:83], v[174:177], v[198:201], 0
	v_mfma_f32_16x16x32_bf16 v[72:75], v[166:169], v[210:213], 0
	v_mfma_f32_16x16x32_bf16 v[64:67], v[174:177], v[210:213], 0
	v_mfma_f32_16x16x32_bf16 v[120:123], v[170:173], v[186:189], v[120:123]
	v_mfma_f32_16x16x32_bf16 v[112:115], v[178:181], v[186:189], v[112:115]
	v_mfma_f32_16x16x32_bf16 v[104:107], v[170:173], v[194:197], v[104:107]
	v_mfma_f32_16x16x32_bf16 v[96:99], v[178:181], v[194:197], v[96:99]
	v_mfma_f32_16x16x32_bf16 v[88:91], v[170:173], v[202:205], v[88:91]
	v_mfma_f32_16x16x32_bf16 v[80:83], v[178:181], v[202:205], v[80:83]
	v_mfma_f32_16x16x32_bf16 v[72:75], v[170:173], v[214:217], v[72:75]
	v_mfma_f32_16x16x32_bf16 v[64:67], v[178:181], v[214:217], v[64:67]
	s_setprio 0
	s_barrier
	s_add_i32 s47, s38, s9
	v_lshl_add_u64 v[206:207], s[24:25], 0, v[132:133]
	s_mov_b32 m0, s47
	ds_read_b128 v[182:185], v153 offset:16384
	ds_read_b128 v[186:189], v153 offset:17408
	ds_read_b128 v[190:193], v153 offset:18432
	ds_read_b128 v[194:197], v153 offset:19456
	ds_read_b128 v[198:201], v153 offset:20480
	ds_read_b128 v[202:205], v153 offset:21504
	ds_read_b128 v[210:213], v153 offset:22528
	ds_read_b128 v[214:217], v153 offset:23552
	global_load_lds_dwordx4 v[206:207], off
	s_add_i32 m0, s47, 0x2000
	s_add_u32 s48, s24, 0x40000
	v_lshl_add_u64 v[218:219], s[24:25], 0, v[128:129]
	s_addc_u32 s49, s25, 0
	s_add_i32 s47, s39, s9
	global_load_lds_dwordx4 v[218:219], off
	v_lshl_add_u64 v[220:221], s[48:49], 0, v[132:133]
	s_mov_b32 m0, s47
	v_lshl_add_u64 v[222:223], s[26:27], 0, v[130:131]
	global_load_lds_dwordx4 v[220:221], off
	v_lshl_add_u64 v[220:221], s[48:49], 0, v[128:129]
	s_add_i32 m0, s47, 0x2000
	s_nop 0
	global_load_lds_dwordx4 v[220:221], off
	v_lshl_add_u64 v[220:221], s[26:27], 0, v[134:135]
	s_mov_b32 m0, s21
	s_nop 0
	global_load_lds_dwordx4 v[220:221], off
	s_mov_b32 m0, s30
	s_nop 0
	global_load_lds_dwordx4 v[222:223], off
	s_waitcnt vmcnt(8)
	s_waitcnt lgkmcnt(0)
	s_barrier
	s_setprio 1
	s_waitcnt lgkmcnt(0)
	v_mfma_f32_16x16x32_bf16 v[60:63], v[144:147], v[182:185], 0
	v_mfma_f32_16x16x32_bf16 v[52:55], v[158:161], v[182:185], 0
	v_mfma_f32_16x16x32_bf16 v[44:47], v[144:147], v[190:193], 0
	v_mfma_f32_16x16x32_bf16 v[36:39], v[158:161], v[190:193], 0
	v_mfma_f32_16x16x32_bf16 v[28:31], v[144:147], v[198:201], 0
	v_mfma_f32_16x16x32_bf16 v[20:23], v[158:161], v[198:201], 0
	v_mfma_f32_16x16x32_bf16 v[12:15], v[144:147], v[210:213], 0
	v_mfma_f32_16x16x32_bf16 v[4:7], v[158:161], v[210:213], 0
	v_mfma_f32_16x16x32_bf16 v[60:63], v[154:157], v[186:189], v[60:63]
	v_mfma_f32_16x16x32_bf16 v[52:55], v[162:165], v[186:189], v[52:55]
	v_mfma_f32_16x16x32_bf16 v[44:47], v[154:157], v[194:197], v[44:47]
	v_mfma_f32_16x16x32_bf16 v[36:39], v[162:165], v[194:197], v[36:39]
	v_mfma_f32_16x16x32_bf16 v[28:31], v[154:157], v[202:205], v[28:31]
	v_mfma_f32_16x16x32_bf16 v[20:23], v[162:165], v[202:205], v[20:23]
	v_mfma_f32_16x16x32_bf16 v[12:15], v[154:157], v[214:217], v[12:15]
	v_mfma_f32_16x16x32_bf16 v[4:7], v[162:165], v[214:217], v[4:7]
	v_mfma_f32_16x16x32_bf16 v[56:59], v[166:169], v[182:185], 0
	v_mfma_f32_16x16x32_bf16 v[48:51], v[174:177], v[182:185], 0
	v_mfma_f32_16x16x32_bf16 v[40:43], v[166:169], v[190:193], 0
	v_mfma_f32_16x16x32_bf16 v[32:35], v[174:177], v[190:193], 0
	v_mfma_f32_16x16x32_bf16 v[24:27], v[166:169], v[198:201], 0
	v_mfma_f32_16x16x32_bf16 v[16:19], v[174:177], v[198:201], 0
	v_mfma_f32_16x16x32_bf16 v[8:11], v[166:169], v[210:213], 0
	v_mfma_f32_16x16x32_bf16 v[0:3], v[174:177], v[210:213], 0
	v_mfma_f32_16x16x32_bf16 v[56:59], v[170:173], v[186:189], v[56:59]
	v_mfma_f32_16x16x32_bf16 v[48:51], v[178:181], v[186:189], v[48:51]
	v_mfma_f32_16x16x32_bf16 v[40:43], v[170:173], v[194:197], v[40:43]
	v_mfma_f32_16x16x32_bf16 v[32:35], v[178:181], v[194:197], v[32:35]
	v_mfma_f32_16x16x32_bf16 v[24:27], v[170:173], v[202:205], v[24:27]
	v_mfma_f32_16x16x32_bf16 v[16:19], v[178:181], v[202:205], v[16:19]
	v_mfma_f32_16x16x32_bf16 v[8:11], v[170:173], v[214:217], v[8:11]
	v_mfma_f32_16x16x32_bf16 v[0:3], v[178:181], v[214:217], v[0:3]
	s_setprio 0
	s_barrier
; #define PG8_STAGE(bufoff, gbase, voff) do { _Pragma("unroll") for (int _i = 0; _i < 2; ++_i) \
;         __builtin_amdgcn_global_load_lds((const unsigned*)((const char*)(gbase) + (voff)[_i]), (PG8_LAS unsigned*)(lds + (bufoff) + ldsw + _i * 8192), 16, 0, 0); } while (0)
; #define PG8_LDA(dst, b, h) do { _Pragma("unroll") for (int m = 0; m < 4; ++m) _Pragma("unroll") for (int k = 0; k < 2; ++k) dst[m][k] = *(const PG8_LAS bf16x8*)(lds + PG8_SA(b, h) + aoff + m * 2048 + k * 1024); } while (0)
; #define PG8_LDB(dst, b, h) do { _Pragma("unroll") for (int n = 0; n < 2; ++n) _Pragma("unroll") for (int k = 0; k < 2; ++k) dst[n][k] = *(const PG8_LAS bf16x8*)(lds + PG8_SB(b, h) + boff + n * 2048 + k * 1024); } while (0)
; #define PG8_MMA(ai, bj, At, Bt) do { __builtin_amdgcn_s_setprio(1); _Pragma("unroll") for (int m = 0; m < 4; ++m) _Pragma("unroll") for (int n = 0; n < 2; ++n) _Pragma("unroll") for (int k = 0; k < 2; ++k) \
;         acc[ai][bj][m][n] = __builtin_amdgcn_mfma_f32_16x16x32_bf16(Bt[n][k], At[m][k], acc[ai][bj][m][n], 0, 0, 0); __builtin_amdgcn_s_setprio(0); } while (0)
; #define PG8_WAIT_V(n) asm volatile("s_waitcnt vmcnt(" #n ")" ::: "memory")
; #define PG8_WAIT_L(n) asm volatile("s_waitcnt lgkmcnt(" #n ")" ::: "memory")
; #define PG8_BAR __builtin_amdgcn_s_barrier()
; #define PG8_SCHED __builtin_amdgcn_sched_barrier(0)
; template <class Epi, class Sched, bool ALIGN_EPI = false, bool SP2 = false>
; __device__ __forceinline__ void gemm_phase(PG8_LAS unsigned char* lds, const Gemm g, const Sched& S, const Epi& E, const int wid) {
;     ...
;             PG8_LDB(B0, 1, 0); PG8_LDB(B1, 1, 1); PG8_SCHED; PG8_LDA(At, 1, 0); PG8_STAGE(PG8_SA(0, 1), a2 + hstep, voffA);
;             PG8_WAIT_V(8); PG8_WAIT_L(0); PG8_BAR; PG8_MMA(0, 0, At, B0); PG8_MMA(0, 1, At, B1); PG8_BAR; PG8_SCHED;
;             PG8_LDA(At, 1, 1); PG8_STAGE(PG8_SB(1, 0), b3, voffB); PG8_STAGE(PG8_SB(1, 1), b3 + hstep, voffB); PG8_STAGE(PG8_SA(1, 0), a3, voffA);
;             PG8_WAIT_V(8); PG8_WAIT_L(0); PG8_BAR; PG8_MMA(1, 0, At, B0); PG8_MMA(1, 1, At, B1); PG8_BAR; PG8_SCHED;
	s_add_i32 s47, 0, 0x18000
	s_add_i32 s48, 0, 0x1c000
	v_add_u32_e32 v162, s47, v149
	v_add_u32_e32 v178, s48, v149
	ds_read_b128 v[144:147], v162
	ds_read_b128 v[154:157], v162 offset:1024
	ds_read_b128 v[158:161], v162 offset:2048
	ds_read_b128 v[162:165], v162 offset:3072
	ds_read_b128 v[166:169], v178
	ds_read_b128 v[170:173], v178 offset:1024
	ds_read_b128 v[174:177], v178 offset:2048
	ds_read_b128 v[178:181], v178 offset:3072
	s_add_u32 s26, s26, 0x40000
	s_addc_u32 s27, s27, 0
	s_mov_b32 m0, s31
	v_lshl_add_u64 v[224:225], s[26:27], 0, v[134:135]
	ds_read_b128 v[182:185], v153 offset:32768
	ds_read_b128 v[186:189], v153 offset:33792
	ds_read_b128 v[190:193], v153 offset:34816
	ds_read_b128 v[194:197], v153 offset:35840
	ds_read_b128 v[198:201], v153 offset:36864
	ds_read_b128 v[202:205], v153 offset:37888
	ds_read_b128 v[210:213], v153 offset:38912
	ds_read_b128 v[214:217], v153 offset:39936
	global_load_lds_dwordx4 v[224:225], off
	v_lshl_add_u64 v[224:225], s[26:27], 0, v[130:131]
	s_mov_b32 m0, s33
	s_nop 0
	global_load_lds_dwordx4 v[224:225], off
	s_waitcnt vmcnt(8)
	s_waitcnt lgkmcnt(0)
	s_barrier
	s_setprio 1
	s_waitcnt lgkmcnt(0)
	v_mfma_f32_16x16x32_bf16 v[124:127], v[144:147], v[182:185], v[124:127]
	v_mfma_f32_16x16x32_bf16 v[116:119], v[158:161], v[182:185], v[116:119]
	v_mfma_f32_16x16x32_bf16 v[108:111], v[144:147], v[190:193], v[108:111]
	v_mfma_f32_16x16x32_bf16 v[100:103], v[158:161], v[190:193], v[100:103]
	v_mfma_f32_16x16x32_bf16 v[92:95], v[144:147], v[198:201], v[92:95]
	v_mfma_f32_16x16x32_bf16 v[84:87], v[158:161], v[198:201], v[84:87]
	v_mfma_f32_16x16x32_bf16 v[76:79], v[144:147], v[210:213], v[76:79]
	v_mfma_f32_16x16x32_bf16 v[68:71], v[158:161], v[210:213], v[68:71]
	v_mfma_f32_16x16x32_bf16 v[124:127], v[154:157], v[186:189], v[124:127]
	v_mfma_f32_16x16x32_bf16 v[116:119], v[162:165], v[186:189], v[116:119]
	v_mfma_f32_16x16x32_bf16 v[108:111], v[154:157], v[194:197], v[108:111]
	v_mfma_f32_16x16x32_bf16 v[100:103], v[162:165], v[194:197], v[100:103]
	v_mfma_f32_16x16x32_bf16 v[92:95], v[154:157], v[202:205], v[92:95]
	v_mfma_f32_16x16x32_bf16 v[84:87], v[162:165], v[202:205], v[84:87]
	v_mfma_f32_16x16x32_bf16 v[76:79], v[154:157], v[214:217], v[76:79]
	v_mfma_f32_16x16x32_bf16 v[68:71], v[162:165], v[214:217], v[68:71]
	v_mfma_f32_16x16x32_bf16 v[120:123], v[166:169], v[182:185], v[120:123]
	v_mfma_f32_16x16x32_bf16 v[112:115], v[174:177], v[182:185], v[112:115]
	v_mfma_f32_16x16x32_bf16 v[104:107], v[166:169], v[190:193], v[104:107]
	v_mfma_f32_16x16x32_bf16 v[96:99], v[174:177], v[190:193], v[96:99]
	v_mfma_f32_16x16x32_bf16 v[88:91], v[166:169], v[198:201], v[88:91]
	v_mfma_f32_16x16x32_bf16 v[80:83], v[174:177], v[198:201], v[80:83]
	v_mfma_f32_16x16x32_bf16 v[72:75], v[166:169], v[210:213], v[72:75]
	v_mfma_f32_16x16x32_bf16 v[64:67], v[174:177], v[210:213], v[64:67]
	v_mfma_f32_16x16x32_bf16 v[120:123], v[170:173], v[186:189], v[120:123]
	v_mfma_f32_16x16x32_bf16 v[112:115], v[178:181], v[186:189], v[112:115]
	v_mfma_f32_16x16x32_bf16 v[104:107], v[170:173], v[194:197], v[104:107]
	v_mfma_f32_16x16x32_bf16 v[96:99], v[178:181], v[194:197], v[96:99]
	v_mfma_f32_16x16x32_bf16 v[88:91], v[170:173], v[202:205], v[88:91]
	v_mfma_f32_16x16x32_bf16 v[80:83], v[178:181], v[202:205], v[80:83]
	v_mfma_f32_16x16x32_bf16 v[72:75], v[170:173], v[214:217], v[72:75]
	v_mfma_f32_16x16x32_bf16 v[64:67], v[178:181], v[214:217], v[64:67]
	s_setprio 0
	s_barrier
	s_add_i32 s26, s47, s9
	v_lshl_add_u64 v[206:207], v[206:207], 0, s[2:3]
	s_mov_b32 m0, s26
	ds_read_b128 v[182:185], v153 offset:49152
	ds_read_b128 v[186:189], v153 offset:50176
	ds_read_b128 v[190:193], v153 offset:51200
	ds_read_b128 v[194:197], v153 offset:52224
	ds_read_b128 v[198:201], v153 offset:53248
	ds_read_b128 v[202:205], v153 offset:54272
	ds_read_b128 v[210:213], v153 offset:55296
	ds_read_b128 v[214:217], v153 offset:56320
	global_load_lds_dwordx4 v[206:207], off
	s_add_i32 m0, s26, 0x2000
	s_add_u32 s24, s24, 0x40080
	v_lshl_add_u64 v[206:207], v[218:219], 0, s[2:3]
	s_addc_u32 s25, s25, 0
	s_add_i32 s26, s48, s9
	global_load_lds_dwordx4 v[206:207], off
	v_lshl_add_u64 v[206:207], s[24:25], 0, v[132:133]
	s_mov_b32 m0, s26
	s_nop 0
	global_load_lds_dwordx4 v[206:207], off
	v_lshl_add_u64 v[206:207], s[24:25], 0, v[128:129]
	s_add_i32 m0, s26, 0x2000
	s_nop 0
	global_load_lds_dwordx4 v[206:207], off
	v_lshl_add_u64 v[206:207], v[220:221], 0, s[2:3]
	s_mov_b32 m0, s35
	s_nop 0
	global_load_lds_dwordx4 v[206:207], off
	v_lshl_add_u64 v[206:207], v[222:223], 0, s[2:3]
	s_mov_b32 m0, s36
	s_nop 0
	global_load_lds_dwordx4 v[206:207], off
	s_waitcnt vmcnt(8)
	s_waitcnt lgkmcnt(0)
	s_barrier
; #define PG8_STAGE(bufoff, gbase, voff) do { _Pragma("unroll") for (int _i = 0; _i < 2; ++_i) \
;         __builtin_amdgcn_global_load_lds((const unsigned*)((const char*)(gbase) + (voff)[_i]), (PG8_LAS unsigned*)(lds + (bufoff) + ldsw + _i * 8192), 16, 0, 0); } while (0)
; #define PG8_LDA(dst, b, h) do { _Pragma("unroll") for (int m = 0; m < 4; ++m) _Pragma("unroll") for (int k = 0; k < 2; ++k) dst[m][k] = *(const PG8_LAS bf16x8*)(lds + PG8_SA(b, h) + aoff + m * 2048 + k * 1024); } while (0)
; #define PG8_LDB(dst, b, h) do { _Pragma("unroll") for (int n = 0; n < 2; ++n) _Pragma("unroll") for (int k = 0; k < 2; ++k) dst[n][k] = *(const PG8_LAS bf16x8*)(lds + PG8_SB(b, h) + boff + n * 2048 + k * 1024); } while (0)
; #define PG8_MMA(ai, bj, At, Bt) do { __builtin_amdgcn_s_setprio(1); _Pragma("unroll") for (int m = 0; m < 4; ++m) _Pragma("unroll") for (int n = 0; n < 2; ++n) _Pragma("unroll") for (int k = 0; k < 2; ++k) \
;         acc[ai][bj][m][n] = __builtin_amdgcn_mfma_f32_16x16x32_bf16(Bt[n][k], At[m][k], acc[ai][bj][m][n], 0, 0, 0); __builtin_amdgcn_s_setprio(0); } while (0)
; #define PG8_BAR __builtin_amdgcn_s_barrier()
; template <class Epi, class Sched, bool ALIGN_EPI = false, bool SP2 = false>
; __device__ __forceinline__ void gemm_phase(PG8_LAS unsigned char* lds, const Gemm g, const Sched& S, const Epi& E, const int wid) {
;     ...
;             PG8_LDB(B0, 0, 0); PG8_LDB(B1, 0, 1); PG8_SCHED; PG8_LDA(At, 0, 0); PG8_STAGE(PG8_SA(1, 1), a1 + hstep, voffA);
;             PG8_WAIT_V(8); PG8_WAIT_L(0); PG8_BAR; PG8_MMA(0, 0, At, B0); PG8_MMA(0, 1, At, B1); PG8_BAR; PG8_SCHED;
;             PG8_LDA(At, 0, 1); PG8_STAGE(PG8_SB(0, 0), b2, voffB); PG8_STAGE(PG8_SB(0, 1), b2 + hstep, voffB); PG8_STAGE(PG8_SA(0, 0), a2, voffA);
;             PG8_WAIT_V(8); PG8_WAIT_L(0); PG8_BAR; PG8_MMA(1, 0, At, B0); PG8_MMA(1, 1, At, B1); PG8_BAR; PG8_SCHED;
;             PG8_LDB(B0, 1, 0); PG8_LDB(B1, 1, 1); PG8_SCHED; PG8_LDA(At, 1, 0); PG8_STAGE(PG8_SA(0, 1), a2 + hstep, voffA);
;             PG8_WAIT_V(8); PG8_WAIT_L(0); PG8_BAR; PG8_MMA(0, 0, At, B0); PG8_MMA(0, 1, At, B1); PG8_BAR; PG8_SCHED;
;             PG8_LDA(At, 1, 1); PG8_STAGE(PG8_SB(1, 0), b3, voffB); PG8_STAGE(PG8_SB(1, 1), b3 + hstep, voffB); PG8_STAGE(PG8_SA(1, 0), a3, voffA);
;             PG8_WAIT_V(8); PG8_WAIT_L(0); PG8_BAR; PG8_MMA(1, 0, At, B0); PG8_MMA(1, 1, At, B1); PG8_BAR; PG8_SCHED;
	s_setprio 1
	s_waitcnt lgkmcnt(0)
	v_mfma_f32_16x16x32_bf16 v[60:63], v[144:147], v[182:185], v[60:63]
	v_mfma_f32_16x16x32_bf16 v[52:55], v[158:161], v[182:185], v[52:55]
	v_mfma_f32_16x16x32_bf16 v[44:47], v[144:147], v[190:193], v[44:47]
	v_mfma_f32_16x16x32_bf16 v[36:39], v[158:161], v[190:193], v[36:39]
	v_mfma_f32_16x16x32_bf16 v[28:31], v[144:147], v[198:201], v[28:31]
	v_mfma_f32_16x16x32_bf16 v[20:23], v[158:161], v[198:201], v[20:23]
	v_mfma_f32_16x16x32_bf16 v[12:15], v[144:147], v[210:213], v[12:15]
	v_mfma_f32_16x16x32_bf16 v[4:7], v[158:161], v[210:213], v[4:7]
	v_mfma_f32_16x16x32_bf16 v[60:63], v[154:157], v[186:189], v[60:63]
	v_mfma_f32_16x16x32_bf16 v[52:55], v[162:165], v[186:189], v[52:55]
	v_mfma_f32_16x16x32_bf16 v[44:47], v[154:157], v[194:197], v[44:47]
	v_mfma_f32_16x16x32_bf16 v[36:39], v[162:165], v[194:197], v[36:39]
	v_mfma_f32_16x16x32_bf16 v[28:31], v[154:157], v[202:205], v[28:31]
	v_mfma_f32_16x16x32_bf16 v[20:23], v[162:165], v[202:205], v[20:23]
	v_mfma_f32_16x16x32_bf16 v[12:15], v[154:157], v[214:217], v[12:15]
	v_mfma_f32_16x16x32_bf16 v[4:7], v[162:165], v[214:217], v[4:7]
	v_mfma_f32_16x16x32_bf16 v[56:59], v[166:169], v[182:185], v[56:59]
	v_mfma_f32_16x16x32_bf16 v[48:51], v[174:177], v[182:185], v[48:51]
	v_mfma_f32_16x16x32_bf16 v[40:43], v[166:169], v[190:193], v[40:43]
	v_mfma_f32_16x16x32_bf16 v[32:35], v[174:177], v[190:193], v[32:35]
	v_mfma_f32_16x16x32_bf16 v[24:27], v[166:169], v[198:201], v[24:27]
	v_mfma_f32_16x16x32_bf16 v[16:19], v[174:177], v[198:201], v[16:19]
	v_mfma_f32_16x16x32_bf16 v[8:11], v[166:169], v[210:213], v[8:11]
	v_mfma_f32_16x16x32_bf16 v[0:3], v[174:177], v[210:213], v[0:3]
	v_mfma_f32_16x16x32_bf16 v[56:59], v[170:173], v[186:189], v[56:59]
	v_mfma_f32_16x16x32_bf16 v[48:51], v[178:181], v[186:189], v[48:51]
	v_mfma_f32_16x16x32_bf16 v[40:43], v[170:173], v[194:197], v[40:43]
	v_mfma_f32_16x16x32_bf16 v[32:35], v[178:181], v[194:197], v[32:35]
	v_mfma_f32_16x16x32_bf16 v[24:27], v[170:173], v[202:205], v[24:27]
	v_mfma_f32_16x16x32_bf16 v[16:19], v[178:181], v[202:205], v[16:19]
	v_mfma_f32_16x16x32_bf16 v[8:11], v[170:173], v[214:217], v[8:11]
	v_mfma_f32_16x16x32_bf16 v[0:3], v[178:181], v[214:217], v[0:3]
	s_setprio 0
	s_barrier
	s_add_i32 s46, s46, 2
	s_add_u32 s22, s22, 0x100
	s_addc_u32 s23, s23, 0
	s_add_u32 s44, s44, 0x100
	s_addc_u32 s45, s45, 0
	s_cmp_gt_u32 s46, 13
	s_cbranch_scc0 .LBB0_1912
	s_branch .Lkp_exit_4
.LBB0_1912:
	ds_read_b128 v[144:147], v151
	ds_read_b128 v[154:157], v151 offset:1024
	ds_read_b128 v[158:161], v151 offset:2048
	ds_read_b128 v[162:165], v151 offset:3072
	ds_read_b128 v[166:169], v152
	ds_read_b128 v[170:173], v152 offset:1024
	ds_read_b128 v[174:177], v152 offset:2048
	ds_read_b128 v[178:181], v152 offset:3072
	s_add_u32 s24, s22, 0xfffc0080
	s_addc_u32 s25, s23, -1
	s_cmp_eq_u32 s46, 12
	s_cselect_b32 s27, s15, s25
	s_cselect_b32 s26, s42, s24
	s_cselect_b32 s25, s13, s45
	s_cselect_b32 s24, s43, s44
	v_lshl_add_u64 v[206:207], s[22:23], 0, v[136:137]
	s_add_i32 m0, s21, 0xc000
	ds_read_b128 v[182:185], v153
	ds_read_b128 v[186:189], v153 offset:1024
	ds_read_b128 v[190:193], v153 offset:2048
	ds_read_b128 v[194:197], v153 offset:3072
	ds_read_b128 v[198:201], v153 offset:4096
	ds_read_b128 v[202:205], v153 offset:5120
	ds_read_b128 v[210:213], v153 offset:6144
	ds_read_b128 v[214:217], v153 offset:7168
	global_load_lds_dwordx4 v[206:207], off
	v_lshl_add_u64 v[206:207], s[22:23], 0, v[138:139]
	s_add_i32 m0, s21, 0xe000
	s_nop 0
	global_load_lds_dwordx4 v[206:207], off
	s_waitcnt vmcnt(8)
	s_waitcnt lgkmcnt(0)
	s_barrier
	s_setprio 1
	s_waitcnt lgkmcnt(0)
	v_mfma_f32_16x16x32_bf16 v[124:127], v[144:147], v[182:185], v[124:127]
	v_mfma_f32_16x16x32_bf16 v[116:119], v[158:161], v[182:185], v[116:119]
	v_mfma_f32_16x16x32_bf16 v[108:111], v[144:147], v[190:193], v[108:111]
	v_mfma_f32_16x16x32_bf16 v[100:103], v[158:161], v[190:193], v[100:103]
	v_mfma_f32_16x16x32_bf16 v[92:95], v[144:147], v[198:201], v[92:95]
	v_mfma_f32_16x16x32_bf16 v[84:87], v[158:161], v[198:201], v[84:87]
	v_mfma_f32_16x16x32_bf16 v[76:79], v[144:147], v[210:213], v[76:79]
	v_mfma_f32_16x16x32_bf16 v[68:71], v[158:161], v[210:213], v[68:71]
	v_mfma_f32_16x16x32_bf16 v[124:127], v[154:157], v[186:189], v[124:127]
	v_mfma_f32_16x16x32_bf16 v[116:119], v[162:165], v[186:189], v[116:119]
	v_mfma_f32_16x16x32_bf16 v[108:111], v[154:157], v[194:197], v[108:111]
	v_mfma_f32_16x16x32_bf16 v[100:103], v[162:165], v[194:197], v[100:103]
	v_mfma_f32_16x16x32_bf16 v[92:95], v[154:157], v[202:205], v[92:95]
	v_mfma_f32_16x16x32_bf16 v[84:87], v[162:165], v[202:205], v[84:87]
	v_mfma_f32_16x16x32_bf16 v[76:79], v[154:157], v[214:217], v[76:79]
	v_mfma_f32_16x16x32_bf16 v[68:71], v[162:165], v[214:217], v[68:71]
	v_mfma_f32_16x16x32_bf16 v[120:123], v[166:169], v[182:185], v[120:123]
	v_mfma_f32_16x16x32_bf16 v[112:115], v[174:177], v[182:185], v[112:115]
	v_mfma_f32_16x16x32_bf16 v[104:107], v[166:169], v[190:193], v[104:107]
	v_mfma_f32_16x16x32_bf16 v[96:99], v[174:177], v[190:193], v[96:99]
	v_mfma_f32_16x16x32_bf16 v[88:91], v[166:169], v[198:201], v[88:91]
	v_mfma_f32_16x16x32_bf16 v[80:83], v[174:177], v[198:201], v[80:83]
	v_mfma_f32_16x16x32_bf16 v[72:75], v[166:169], v[210:213], v[72:75]
	v_mfma_f32_16x16x32_bf16 v[64:67], v[174:177], v[210:213], v[64:67]
	v_mfma_f32_16x16x32_bf16 v[120:123], v[170:173], v[186:189], v[120:123]
	v_mfma_f32_16x16x32_bf16 v[112:115], v[178:181], v[186:189], v[112:115]
	v_mfma_f32_16x16x32_bf16 v[104:107], v[170:173], v[194:197], v[104:107]
	v_mfma_f32_16x16x32_bf16 v[96:99], v[178:181], v[194:197], v[96:99]
	v_mfma_f32_16x16x32_bf16 v[88:91], v[170:173], v[202:205], v[88:91]
	v_mfma_f32_16x16x32_bf16 v[80:83], v[178:181], v[202:205], v[80:83]
	v_mfma_f32_16x16x32_bf16 v[72:75], v[170:173], v[214:217], v[72:75]
	v_mfma_f32_16x16x32_bf16 v[64:67], v[178:181], v[214:217], v[64:67]
	s_setprio 0
	s_barrier
; #define PG8_STAGE(bufoff, gbase, voff) do { _Pragma("unroll") for (int _i = 0; _i < 2; ++_i) \
;         __builtin_amdgcn_global_load_lds((const unsigned*)((const char*)(gbase) + (voff)[_i]), (PG8_LAS unsigned*)(lds + (bufoff) + ldsw + _i * 8192), 16, 0, 0); } while (0)
; #define PG8_LDA(dst, b, h) do { _Pragma("unroll") for (int m = 0; m < 4; ++m) _Pragma("unroll") for (int k = 0; k < 2; ++k) dst[m][k] = *(const PG8_LAS bf16x8*)(lds + PG8_SA(b, h) + aoff + m * 2048 + k * 1024); } while (0)
; #define PG8_LDB(dst, b, h) do { _Pragma("unroll") for (int n = 0; n < 2; ++n) _Pragma("unroll") for (int k = 0; k < 2; ++k) dst[n][k] = *(const PG8_LAS bf16x8*)(lds + PG8_SB(b, h) + boff + n * 2048 + k * 1024); } while (0)
; #define PG8_MMA(ai, bj, At, Bt) do { __builtin_amdgcn_s_setprio(1); _Pragma("unroll") for (int m = 0; m < 4; ++m) _Pragma("unroll") for (int n = 0; n < 2; ++n) _Pragma("unroll") for (int k = 0; k < 2; ++k) \
;         acc[ai][bj][m][n] = __builtin_amdgcn_mfma_f32_16x16x32_bf16(Bt[n][k], At[m][k], acc[ai][bj][m][n], 0, 0, 0); __builtin_amdgcn_s_setprio(0); } while (0)
; #define PG8_WAIT_V(n) asm volatile("s_waitcnt vmcnt(" #n ")" ::: "memory")
; #define PG8_WAIT_L(n) asm volatile("s_waitcnt lgkmcnt(" #n ")" ::: "memory")
; #define PG8_BAR __builtin_amdgcn_s_barrier()
; #define PG8_SCHED __builtin_amdgcn_sched_barrier(0)
; template <class Epi, class Sched, bool ALIGN_EPI = false, bool SP2 = false>
; __device__ __forceinline__ void gemm_phase(PG8_LAS unsigned char* lds, const Gemm g, const Sched& S, const Epi& E, const int wid) {
;     ...
;             PG8_LDA(At, 0, 1); PG8_STAGE(PG8_SB(0, 0), b2, voffB); PG8_STAGE(PG8_SB(0, 1), b2 + hstep, voffB); PG8_STAGE(PG8_SA(0, 0), a2, voffA);
;             PG8_WAIT_V(8); PG8_WAIT_L(0); PG8_BAR; PG8_MMA(1, 0, At, B0); PG8_MMA(1, 1, At, B1); PG8_BAR; PG8_SCHED;
;             PG8_LDB(B0, 1, 0); PG8_LDB(B1, 1, 1); PG8_SCHED; PG8_LDA(At, 1, 0); PG8_STAGE(PG8_SA(0, 1), a2 + hstep, voffA);
;             PG8_WAIT_V(8); PG8_WAIT_L(0); PG8_BAR; PG8_MMA(0, 0, At, B0); PG8_MMA(0, 1, At, B1); PG8_BAR; PG8_SCHED;
	s_add_i32 s47, s38, s9
	v_lshl_add_u64 v[206:207], s[24:25], 0, v[132:133]
	s_mov_b32 m0, s47
	ds_read_b128 v[182:185], v153 offset:16384
	ds_read_b128 v[186:189], v153 offset:17408
	ds_read_b128 v[190:193], v153 offset:18432
	ds_read_b128 v[194:197], v153 offset:19456
	ds_read_b128 v[198:201], v153 offset:20480
	ds_read_b128 v[202:205], v153 offset:21504
	ds_read_b128 v[210:213], v153 offset:22528
	ds_read_b128 v[214:217], v153 offset:23552
	global_load_lds_dwordx4 v[206:207], off
	s_add_i32 m0, s47, 0x2000
	s_add_u32 s48, s24, 0x40000
	v_lshl_add_u64 v[218:219], s[24:25], 0, v[128:129]
	s_addc_u32 s49, s25, 0
	s_add_i32 s47, s39, s9
	global_load_lds_dwordx4 v[218:219], off
	v_lshl_add_u64 v[220:221], s[48:49], 0, v[132:133]
	s_mov_b32 m0, s47
	v_lshl_add_u64 v[222:223], s[26:27], 0, v[130:131]
	global_load_lds_dwordx4 v[220:221], off
	v_lshl_add_u64 v[220:221], s[48:49], 0, v[128:129]
	s_add_i32 m0, s47, 0x2000
	s_nop 0
	global_load_lds_dwordx4 v[220:221], off
	v_lshl_add_u64 v[220:221], s[26:27], 0, v[134:135]
	s_mov_b32 m0, s21
	s_nop 0
	global_load_lds_dwordx4 v[220:221], off
	s_mov_b32 m0, s30
	s_nop 0
	global_load_lds_dwordx4 v[222:223], off
	s_waitcnt vmcnt(8)
	s_waitcnt lgkmcnt(0)
	s_barrier
	s_setprio 1
	s_waitcnt lgkmcnt(0)
	v_mfma_f32_16x16x32_bf16 v[60:63], v[144:147], v[182:185], v[60:63]
	v_mfma_f32_16x16x32_bf16 v[52:55], v[158:161], v[182:185], v[52:55]
	v_mfma_f32_16x16x32_bf16 v[44:47], v[144:147], v[190:193], v[44:47]
	v_mfma_f32_16x16x32_bf16 v[36:39], v[158:161], v[190:193], v[36:39]
	v_mfma_f32_16x16x32_bf16 v[28:31], v[144:147], v[198:201], v[28:31]
	v_mfma_f32_16x16x32_bf16 v[20:23], v[158:161], v[198:201], v[20:23]
	v_mfma_f32_16x16x32_bf16 v[12:15], v[144:147], v[210:213], v[12:15]
	v_mfma_f32_16x16x32_bf16 v[4:7], v[158:161], v[210:213], v[4:7]
	v_mfma_f32_16x16x32_bf16 v[60:63], v[154:157], v[186:189], v[60:63]
	v_mfma_f32_16x16x32_bf16 v[52:55], v[162:165], v[186:189], v[52:55]
	v_mfma_f32_16x16x32_bf16 v[44:47], v[154:157], v[194:197], v[44:47]
	v_mfma_f32_16x16x32_bf16 v[36:39], v[162:165], v[194:197], v[36:39]
	v_mfma_f32_16x16x32_bf16 v[28:31], v[154:157], v[202:205], v[28:31]
	v_mfma_f32_16x16x32_bf16 v[20:23], v[162:165], v[202:205], v[20:23]
	v_mfma_f32_16x16x32_bf16 v[12:15], v[154:157], v[214:217], v[12:15]
	v_mfma_f32_16x16x32_bf16 v[4:7], v[162:165], v[214:217], v[4:7]
	v_mfma_f32_16x16x32_bf16 v[56:59], v[166:169], v[182:185], v[56:59]
	v_mfma_f32_16x16x32_bf16 v[48:51], v[174:177], v[182:185], v[48:51]
	v_mfma_f32_16x16x32_bf16 v[40:43], v[166:169], v[190:193], v[40:43]
	v_mfma_f32_16x16x32_bf16 v[32:35], v[174:177], v[190:193], v[32:35]
	v_mfma_f32_16x16x32_bf16 v[24:27], v[166:169], v[198:201], v[24:27]
	v_mfma_f32_16x16x32_bf16 v[16:19], v[174:177], v[198:201], v[16:19]
	v_mfma_f32_16x16x32_bf16 v[8:11], v[166:169], v[210:213], v[8:11]
	v_mfma_f32_16x16x32_bf16 v[0:3], v[174:177], v[210:213], v[0:3]
	v_mfma_f32_16x16x32_bf16 v[56:59], v[170:173], v[186:189], v[56:59]
	v_mfma_f32_16x16x32_bf16 v[48:51], v[178:181], v[186:189], v[48:51]
	v_mfma_f32_16x16x32_bf16 v[40:43], v[170:173], v[194:197], v[40:43]
	v_mfma_f32_16x16x32_bf16 v[32:35], v[178:181], v[194:197], v[32:35]
	v_mfma_f32_16x16x32_bf16 v[24:27], v[170:173], v[202:205], v[24:27]
	v_mfma_f32_16x16x32_bf16 v[16:19], v[178:181], v[202:205], v[16:19]
	v_mfma_f32_16x16x32_bf16 v[8:11], v[170:173], v[214:217], v[8:11]
	v_mfma_f32_16x16x32_bf16 v[0:3], v[178:181], v[214:217], v[0:3]
	s_setprio 0
	s_barrier
	s_add_i32 s47, 0, 0x18000
	s_add_i32 s48, 0, 0x1c000
	v_add_u32_e32 v162, s47, v149
	v_add_u32_e32 v178, s48, v149
	ds_read_b128 v[144:147], v162
	ds_read_b128 v[154:157], v162 offset:1024
	ds_read_b128 v[158:161], v162 offset:2048
	ds_read_b128 v[162:165], v162 offset:3072
	ds_read_b128 v[166:169], v178
	ds_read_b128 v[170:173], v178 offset:1024
	ds_read_b128 v[174:177], v178 offset:2048
	ds_read_b128 v[178:181], v178 offset:3072
	s_add_u32 s26, s26, 0x40000
	s_addc_u32 s27, s27, 0
	s_mov_b32 m0, s31
	v_lshl_add_u64 v[224:225], s[26:27], 0, v[134:135]
	ds_read_b128 v[182:185], v153 offset:32768
	ds_read_b128 v[186:189], v153 offset:33792
	ds_read_b128 v[190:193], v153 offset:34816
	ds_read_b128 v[194:197], v153 offset:35840
	ds_read_b128 v[198:201], v153 offset:36864
	ds_read_b128 v[202:205], v153 offset:37888
	ds_read_b128 v[210:213], v153 offset:38912
	ds_read_b128 v[214:217], v153 offset:39936
	global_load_lds_dwordx4 v[224:225], off
	v_lshl_add_u64 v[224:225], s[26:27], 0, v[130:131]
	s_mov_b32 m0, s33
	s_nop 0
	global_load_lds_dwordx4 v[224:225], off
	s_waitcnt vmcnt(8)
	s_waitcnt lgkmcnt(0)
	s_barrier
; #define PG8_STAGE(bufoff, gbase, voff) do { _Pragma("unroll") for (int _i = 0; _i < 2; ++_i) \
;         __builtin_amdgcn_global_load_lds((const unsigned*)((const char*)(gbase) + (voff)[_i]), (PG8_LAS unsigned*)(lds + (bufoff) + ldsw + _i * 8192), 16, 0, 0); } while (0)
; #define PG8_LDA(dst, b, h) do { _Pragma("unroll") for (int m = 0; m < 4; ++m) _Pragma("unroll") for (int k = 0; k < 2; ++k) dst[m][k] = *(const PG8_LAS bf16x8*)(lds + PG8_SA(b, h) + aoff + m * 2048 + k * 1024); } while (0)
; #define PG8_MMA(ai, bj, At, Bt) do { __builtin_amdgcn_s_setprio(1); _Pragma("unroll") for (int m = 0; m < 4; ++m) _Pragma("unroll") for (int n = 0; n < 2; ++n) _Pragma("unroll") for (int k = 0; k < 2; ++k) \
;         acc[ai][bj][m][n] = __builtin_amdgcn_mfma_f32_16x16x32_bf16(Bt[n][k], At[m][k], acc[ai][bj][m][n], 0, 0, 0); __builtin_amdgcn_s_setprio(0); } while (0)
; #define PG8_WAIT_V(n) asm volatile("s_waitcnt vmcnt(" #n ")" ::: "memory")
; #define PG8_WAIT_L(n) asm volatile("s_waitcnt lgkmcnt(" #n ")" ::: "memory")
; #define PG8_BAR __builtin_amdgcn_s_barrier()
; #define PG8_SCHED __builtin_amdgcn_sched_barrier(0)
; template <class Epi, class Sched, bool ALIGN_EPI = false, bool SP2 = false>
; __device__ __forceinline__ void gemm_phase(PG8_LAS unsigned char* lds, const Gemm g, const Sched& S, const Epi& E, const int wid) {
;     ...
;             PG8_WAIT_V(8); PG8_WAIT_L(0); PG8_BAR; PG8_MMA(0, 0, At, B0); PG8_MMA(0, 1, At, B1); PG8_BAR; PG8_SCHED;
;             PG8_LDA(At, 1, 1); PG8_STAGE(PG8_SB(1, 0), b3, voffB); PG8_STAGE(PG8_SB(1, 1), b3 + hstep, voffB); PG8_STAGE(PG8_SA(1, 0), a3, voffA);
;             PG8_WAIT_V(8); PG8_WAIT_L(0); PG8_BAR; PG8_MMA(1, 0, At, B0); PG8_MMA(1, 1, At, B1); PG8_BAR; PG8_SCHED;
	s_setprio 1
	s_waitcnt lgkmcnt(0)
	v_mfma_f32_16x16x32_bf16 v[124:127], v[144:147], v[182:185], v[124:127]
	v_mfma_f32_16x16x32_bf16 v[116:119], v[158:161], v[182:185], v[116:119]
	v_mfma_f32_16x16x32_bf16 v[108:111], v[144:147], v[190:193], v[108:111]
	v_mfma_f32_16x16x32_bf16 v[100:103], v[158:161], v[190:193], v[100:103]
	v_mfma_f32_16x16x32_bf16 v[92:95], v[144:147], v[198:201], v[92:95]
	v_mfma_f32_16x16x32_bf16 v[84:87], v[158:161], v[198:201], v[84:87]
	v_mfma_f32_16x16x32_bf16 v[76:79], v[144:147], v[210:213], v[76:79]
	v_mfma_f32_16x16x32_bf16 v[68:71], v[158:161], v[210:213], v[68:71]
	v_mfma_f32_16x16x32_bf16 v[124:127], v[154:157], v[186:189], v[124:127]
	v_mfma_f32_16x16x32_bf16 v[116:119], v[162:165], v[186:189], v[116:119]
	v_mfma_f32_16x16x32_bf16 v[108:111], v[154:157], v[194:197], v[108:111]
	v_mfma_f32_16x16x32_bf16 v[100:103], v[162:165], v[194:197], v[100:103]
	v_mfma_f32_16x16x32_bf16 v[92:95], v[154:157], v[202:205], v[92:95]
	v_mfma_f32_16x16x32_bf16 v[84:87], v[162:165], v[202:205], v[84:87]
	v_mfma_f32_16x16x32_bf16 v[76:79], v[154:157], v[214:217], v[76:79]
	v_mfma_f32_16x16x32_bf16 v[68:71], v[162:165], v[214:217], v[68:71]
	v_mfma_f32_16x16x32_bf16 v[120:123], v[166:169], v[182:185], v[120:123]
	v_mfma_f32_16x16x32_bf16 v[112:115], v[174:177], v[182:185], v[112:115]
	v_mfma_f32_16x16x32_bf16 v[104:107], v[166:169], v[190:193], v[104:107]
	v_mfma_f32_16x16x32_bf16 v[96:99], v[174:177], v[190:193], v[96:99]
	v_mfma_f32_16x16x32_bf16 v[88:91], v[166:169], v[198:201], v[88:91]
	v_mfma_f32_16x16x32_bf16 v[80:83], v[174:177], v[198:201], v[80:83]
	v_mfma_f32_16x16x32_bf16 v[72:75], v[166:169], v[210:213], v[72:75]
	v_mfma_f32_16x16x32_bf16 v[64:67], v[174:177], v[210:213], v[64:67]
	v_mfma_f32_16x16x32_bf16 v[120:123], v[170:173], v[186:189], v[120:123]
	v_mfma_f32_16x16x32_bf16 v[112:115], v[178:181], v[186:189], v[112:115]
	v_mfma_f32_16x16x32_bf16 v[104:107], v[170:173], v[194:197], v[104:107]
	v_mfma_f32_16x16x32_bf16 v[96:99], v[178:181], v[194:197], v[96:99]
	v_mfma_f32_16x16x32_bf16 v[88:91], v[170:173], v[202:205], v[88:91]
	v_mfma_f32_16x16x32_bf16 v[80:83], v[178:181], v[202:205], v[80:83]
	v_mfma_f32_16x16x32_bf16 v[72:75], v[170:173], v[214:217], v[72:75]
	v_mfma_f32_16x16x32_bf16 v[64:67], v[178:181], v[214:217], v[64:67]
	s_setprio 0
	s_barrier
	s_add_i32 s26, s47, s9
	v_lshl_add_u64 v[206:207], v[206:207], 0, s[2:3]
	s_mov_b32 m0, s26
	ds_read_b128 v[182:185], v153 offset:49152
	ds_read_b128 v[186:189], v153 offset:50176
	ds_read_b128 v[190:193], v153 offset:51200
	ds_read_b128 v[194:197], v153 offset:52224
	ds_read_b128 v[198:201], v153 offset:53248
	ds_read_b128 v[202:205], v153 offset:54272
	ds_read_b128 v[210:213], v153 offset:55296
	ds_read_b128 v[214:217], v153 offset:56320
	global_load_lds_dwordx4 v[206:207], off
	s_add_i32 m0, s26, 0x2000
	s_add_u32 s24, s24, 0x40080
	v_lshl_add_u64 v[206:207], v[218:219], 0, s[2:3]
	s_addc_u32 s25, s25, 0
	s_add_i32 s26, s48, s9
	global_load_lds_dwordx4 v[206:207], off
	v_lshl_add_u64 v[206:207], s[24:25], 0, v[132:133]
	s_mov_b32 m0, s26
	s_nop 0
	global_load_lds_dwordx4 v[206:207], off
	v_lshl_add_u64 v[206:207], s[24:25], 0, v[128:129]
	s_add_i32 m0, s26, 0x2000
	s_nop 0
	global_load_lds_dwordx4 v[206:207], off
	v_lshl_add_u64 v[206:207], v[220:221], 0, s[2:3]
	s_mov_b32 m0, s35
	s_nop 0
	global_load_lds_dwordx4 v[206:207], off
	v_lshl_add_u64 v[206:207], v[222:223], 0, s[2:3]
	s_mov_b32 m0, s36
	s_nop 0
	global_load_lds_dwordx4 v[206:207], off
	s_waitcnt vmcnt(8)
	s_waitcnt lgkmcnt(0)
	s_barrier
	s_setprio 1
	s_waitcnt lgkmcnt(0)
	v_mfma_f32_16x16x32_bf16 v[60:63], v[144:147], v[182:185], v[60:63]
	v_mfma_f32_16x16x32_bf16 v[52:55], v[158:161], v[182:185], v[52:55]
	v_mfma_f32_16x16x32_bf16 v[44:47], v[144:147], v[190:193], v[44:47]
	v_mfma_f32_16x16x32_bf16 v[36:39], v[158:161], v[190:193], v[36:39]
	v_mfma_f32_16x16x32_bf16 v[28:31], v[144:147], v[198:201], v[28:31]
	v_mfma_f32_16x16x32_bf16 v[20:23], v[158:161], v[198:201], v[20:23]
	v_mfma_f32_16x16x32_bf16 v[12:15], v[144:147], v[210:213], v[12:15]
	v_mfma_f32_16x16x32_bf16 v[4:7], v[158:161], v[210:213], v[4:7]
	v_mfma_f32_16x16x32_bf16 v[60:63], v[154:157], v[186:189], v[60:63]
	v_mfma_f32_16x16x32_bf16 v[52:55], v[162:165], v[186:189], v[52:55]
	v_mfma_f32_16x16x32_bf16 v[44:47], v[154:157], v[194:197], v[44:47]
	v_mfma_f32_16x16x32_bf16 v[36:39], v[162:165], v[194:197], v[36:39]
	v_mfma_f32_16x16x32_bf16 v[28:31], v[154:157], v[202:205], v[28:31]
	v_mfma_f32_16x16x32_bf16 v[20:23], v[162:165], v[202:205], v[20:23]
	v_mfma_f32_16x16x32_bf16 v[12:15], v[154:157], v[214:217], v[12:15]
	v_mfma_f32_16x16x32_bf16 v[4:7], v[162:165], v[214:217], v[4:7]
	v_mfma_f32_16x16x32_bf16 v[56:59], v[166:169], v[182:185], v[56:59]
	v_mfma_f32_16x16x32_bf16 v[48:51], v[174:177], v[182:185], v[48:51]
	v_mfma_f32_16x16x32_bf16 v[40:43], v[166:169], v[190:193], v[40:43]
	v_mfma_f32_16x16x32_bf16 v[32:35], v[174:177], v[190:193], v[32:35]
	v_mfma_f32_16x16x32_bf16 v[24:27], v[166:169], v[198:201], v[24:27]
	v_mfma_f32_16x16x32_bf16 v[16:19], v[174:177], v[198:201], v[16:19]
	v_mfma_f32_16x16x32_bf16 v[8:11], v[166:169], v[210:213], v[8:11]
	v_mfma_f32_16x16x32_bf16 v[0:3], v[174:177], v[210:213], v[0:3]
	v_mfma_f32_16x16x32_bf16 v[56:59], v[170:173], v[186:189], v[56:59]
	v_mfma_f32_16x16x32_bf16 v[48:51], v[178:181], v[186:189], v[48:51]
	v_mfma_f32_16x16x32_bf16 v[40:43], v[170:173], v[194:197], v[40:43]
	v_mfma_f32_16x16x32_bf16 v[32:35], v[178:181], v[194:197], v[32:35]
	v_mfma_f32_16x16x32_bf16 v[24:27], v[170:173], v[202:205], v[24:27]
	v_mfma_f32_16x16x32_bf16 v[16:19], v[178:181], v[202:205], v[16:19]
	v_mfma_f32_16x16x32_bf16 v[8:11], v[170:173], v[214:217], v[8:11]
	v_mfma_f32_16x16x32_bf16 v[0:3], v[178:181], v[214:217], v[0:3]
	s_setprio 0
	s_barrier
	s_add_i32 s46, s46, 2
	s_add_u32 s22, s22, 0x100
	s_addc_u32 s23, s23, 0
	s_add_u32 s44, s44, 0x100
	s_addc_u32 s45, s45, 0
	s_cmp_gt_u32 s46, 13
	s_cbranch_scc0 .LBB0_1912

; #define PG8_STAGE(bufoff, gbase, voff) do { _Pragma("unroll") for (int _i = 0; _i < 2; ++_i) \
;         __builtin_amdgcn_global_load_lds((const unsigned*)((const char*)(gbase) + (voff)[_i]), (PG8_LAS unsigned*)(lds + (bufoff) + ldsw + _i * 8192), 16, 0, 0); } while (0)
; #define PG8_LDA(dst, b, h) do { _Pragma("unroll") for (int m = 0; m < 4; ++m) _Pragma("unroll") for (int k = 0; k < 2; ++k) dst[m][k] = *(const PG8_LAS bf16x8*)(lds + PG8_SA(b, h) + aoff + m * 2048 + k * 1024); } while (0)
; #define PG8_LDB(dst, b, h) do { _Pragma("unroll") for (int n = 0; n < 2; ++n) _Pragma("unroll") for (int k = 0; k < 2; ++k) dst[n][k] = *(const PG8_LAS bf16x8*)(lds + PG8_SB(b, h) + boff + n * 2048 + k * 1024); } while (0)
; #define PG8_MMA(ai, bj, At, Bt) do { __builtin_amdgcn_s_setprio(1); _Pragma("unroll") for (int m = 0; m < 4; ++m) _Pragma("unroll") for (int n = 0; n < 2; ++n) _Pragma("unroll") for (int k = 0; k < 2; ++k) \
;         acc[ai][bj][m][n] = __builtin_amdgcn_mfma_f32_16x16x32_bf16(Bt[n][k], At[m][k], acc[ai][bj][m][n], 0, 0, 0); __builtin_amdgcn_s_setprio(0); } while (0)
; #define PG8_WAIT_V(n) asm volatile("s_waitcnt vmcnt(" #n ")" ::: "memory")
; #define PG8_WAIT_L(n) asm volatile("s_waitcnt lgkmcnt(" #n ")" ::: "memory")
; #define PG8_BAR __builtin_amdgcn_s_barrier()
; #define PG8_SCHED __builtin_amdgcn_sched_barrier(0)
; template <class Epi, class Sched, bool ALIGN_EPI = false, bool SP2 = false>
; __device__ __forceinline__ void gemm_phase(PG8_LAS unsigned char* lds, const Gemm g, const Sched& S, const Epi& E, const int wid) {
;     ...
;             PG8_LDB(B0, 0, 0); PG8_LDB(B1, 0, 1); PG8_SCHED; PG8_LDA(At, 0, 0); PG8_STAGE(PG8_SA(1, 1), a1 + hstep, voffA);
;             PG8_WAIT_V(8); PG8_WAIT_L(0); PG8_BAR; PG8_MMA(0, 0, At, B0); PG8_MMA(0, 1, At, B1); PG8_BAR; PG8_SCHED;
;             PG8_LDA(At, 0, 1); PG8_STAGE(PG8_SB(0, 0), b2, voffB); PG8_STAGE(PG8_SB(0, 1), b2 + hstep, voffB); PG8_STAGE(PG8_SA(0, 0), a2, voffA);
;             PG8_WAIT_V(8); PG8_WAIT_L(0); PG8_BAR; PG8_MMA(1, 0, At, B0); PG8_MMA(1, 1, At, B1); PG8_BAR; PG8_SCHED;
.LBB0_2460:
	v_add_u32_e32 v151, s35, v149
	ds_read_b128 v[152:155], v151
	ds_read_b128 v[156:159], v151 offset:1024
	ds_read_b128 v[160:163], v151 offset:2048
	ds_read_b128 v[168:171], v151 offset:3072
	v_add_u32_e32 v151, s36, v149
	s_add_u32 s16, s8, s14
	ds_read_b128 v[172:175], v151
	ds_read_b128 v[178:181], v151 offset:1024
	ds_read_b128 v[182:185], v151 offset:2048
	ds_read_b128 v[186:189], v151 offset:3072
	s_addc_u32 s17, s9, s15
	s_add_u32 s16, s16, 0x100
	s_addc_u32 s17, s17, 0
	s_add_u32 s43, s40, s14
	s_addc_u32 s44, s41, s15
	s_cmpk_eq_i32 s14, 0x1500
	s_cselect_b32 s19, s13, s17
	s_cselect_b32 s18, s12, s16
	s_cselect_b32 s17, s5, s44
	s_cselect_b32 s16, s4, s43
	v_lshl_add_u64 v[222:223], v[144:145], 0, s[14:15]
	s_add_i32 m0, s26, 0xc000
	ds_read_b128 v[190:193], v150
	ds_read_b128 v[194:197], v150 offset:1024
	ds_read_b128 v[198:201], v150 offset:2048
	ds_read_b128 v[202:205], v150 offset:3072
	ds_read_b128 v[206:209], v150 offset:4096
	ds_read_b128 v[210:213], v150 offset:5120
	ds_read_b128 v[214:217], v150 offset:6144
	ds_read_b128 v[218:221], v150 offset:7168
	global_load_lds_dwordx4 v[222:223], off
	v_lshl_add_u64 v[222:223], v[146:147], 0, s[14:15]
	s_add_i32 m0, s26, 0xe000
	s_nop 0
	global_load_lds_dwordx4 v[222:223], off
	s_waitcnt vmcnt(8)
	s_waitcnt lgkmcnt(0)
	s_barrier
	s_setprio 1
	s_waitcnt lgkmcnt(0)
	v_mfma_f32_16x16x32_bf16 v[124:127], v[152:155], v[190:193], v[124:127]
	v_mfma_f32_16x16x32_bf16 v[120:123], v[160:163], v[190:193], v[120:123]
	v_mfma_f32_16x16x32_bf16 v[112:115], v[152:155], v[198:201], v[112:115]
	v_mfma_f32_16x16x32_bf16 v[104:107], v[160:163], v[198:201], v[104:107]
	v_mfma_f32_16x16x32_bf16 v[96:99], v[152:155], v[206:209], v[96:99]
	v_mfma_f32_16x16x32_bf16 v[88:91], v[160:163], v[206:209], v[88:91]
	v_mfma_f32_16x16x32_bf16 v[80:83], v[152:155], v[214:217], v[80:83]
	v_mfma_f32_16x16x32_bf16 v[72:75], v[160:163], v[214:217], v[72:75]
	v_mfma_f32_16x16x32_bf16 v[124:127], v[156:159], v[194:197], v[124:127]
	v_mfma_f32_16x16x32_bf16 v[120:123], v[168:171], v[194:197], v[120:123]
	v_mfma_f32_16x16x32_bf16 v[112:115], v[156:159], v[202:205], v[112:115]
	v_mfma_f32_16x16x32_bf16 v[104:107], v[168:171], v[202:205], v[104:107]
	v_mfma_f32_16x16x32_bf16 v[96:99], v[156:159], v[210:213], v[96:99]
	v_mfma_f32_16x16x32_bf16 v[88:91], v[168:171], v[210:213], v[88:91]
	v_mfma_f32_16x16x32_bf16 v[80:83], v[156:159], v[218:221], v[80:83]
	v_mfma_f32_16x16x32_bf16 v[72:75], v[168:171], v[218:221], v[72:75]
	v_mfma_f32_16x16x32_bf16 v[116:119], v[172:175], v[190:193], v[116:119]
	v_mfma_f32_16x16x32_bf16 v[108:111], v[182:185], v[190:193], v[108:111]
	v_mfma_f32_16x16x32_bf16 v[100:103], v[172:175], v[198:201], v[100:103]
	v_mfma_f32_16x16x32_bf16 v[92:95], v[182:185], v[198:201], v[92:95]
	v_mfma_f32_16x16x32_bf16 v[84:87], v[172:175], v[206:209], v[84:87]
	v_mfma_f32_16x16x32_bf16 v[76:79], v[182:185], v[206:209], v[76:79]
	v_mfma_f32_16x16x32_bf16 v[68:71], v[172:175], v[214:217], v[68:71]
	v_mfma_f32_16x16x32_bf16 v[64:67], v[182:185], v[214:217], v[64:67]
	v_mfma_f32_16x16x32_bf16 v[116:119], v[178:181], v[194:197], v[116:119]
	v_mfma_f32_16x16x32_bf16 v[108:111], v[186:189], v[194:197], v[108:111]
	v_mfma_f32_16x16x32_bf16 v[100:103], v[178:181], v[202:205], v[100:103]
	v_mfma_f32_16x16x32_bf16 v[92:95], v[186:189], v[202:205], v[92:95]
	v_mfma_f32_16x16x32_bf16 v[84:87], v[178:181], v[210:213], v[84:87]
	v_mfma_f32_16x16x32_bf16 v[76:79], v[186:189], v[210:213], v[76:79]
	v_mfma_f32_16x16x32_bf16 v[68:71], v[178:181], v[218:221], v[68:71]
	v_mfma_f32_16x16x32_bf16 v[64:67], v[186:189], v[218:221], v[64:67]
	s_setprio 0
	s_barrier
	s_add_i32 s43, s35, s24
	v_lshl_add_u64 v[222:223], s[16:17], 0, v[130:131]
	s_mov_b32 m0, s43
	ds_read_b128 v[190:193], v150 offset:16384
	ds_read_b128 v[194:197], v150 offset:17408
	ds_read_b128 v[198:201], v150 offset:18432
	ds_read_b128 v[202:205], v150 offset:19456
	ds_read_b128 v[206:209], v150 offset:20480
	ds_read_b128 v[210:213], v150 offset:21504
	ds_read_b128 v[214:217], v150 offset:22528
	ds_read_b128 v[218:221], v150 offset:23552
	global_load_lds_dwordx4 v[222:223], off
	s_add_i32 m0, s43, 0x2000
	s_add_u32 s44, s16, 0xb0000
	v_lshl_add_u64 v[224:225], s[16:17], 0, v[134:135]
	s_addc_u32 s45, s17, 0
	s_add_i32 s43, s36, s24
	global_load_lds_dwordx4 v[224:225], off
	v_lshl_add_u64 v[226:227], s[44:45], 0, v[130:131]
	s_mov_b32 m0, s43
	v_lshl_add_u64 v[228:229], s[18:19], 0, v[132:133]
	global_load_lds_dwordx4 v[226:227], off
	v_lshl_add_u64 v[226:227], s[44:45], 0, v[134:135]
	s_add_i32 m0, s43, 0x2000
	s_nop 0
	global_load_lds_dwordx4 v[226:227], off
	v_lshl_add_u64 v[226:227], s[18:19], 0, v[128:129]
	s_mov_b32 m0, s26
	s_nop 0
	global_load_lds_dwordx4 v[226:227], off
	s_mov_b32 m0, s27
	s_nop 0
	global_load_lds_dwordx4 v[228:229], off
	s_waitcnt vmcnt(8)
	s_waitcnt lgkmcnt(0)
	s_barrier
; #define PG8_STAGE(bufoff, gbase, voff) do { _Pragma("unroll") for (int _i = 0; _i < 2; ++_i) \
;         __builtin_amdgcn_global_load_lds((const unsigned*)((const char*)(gbase) + (voff)[_i]), (PG8_LAS unsigned*)(lds + (bufoff) + ldsw + _i * 8192), 16, 0, 0); } while (0)
; #define PG8_LDA(dst, b, h) do { _Pragma("unroll") for (int m = 0; m < 4; ++m) _Pragma("unroll") for (int k = 0; k < 2; ++k) dst[m][k] = *(const PG8_LAS bf16x8*)(lds + PG8_SA(b, h) + aoff + m * 2048 + k * 1024); } while (0)
; #define PG8_LDB(dst, b, h) do { _Pragma("unroll") for (int n = 0; n < 2; ++n) _Pragma("unroll") for (int k = 0; k < 2; ++k) dst[n][k] = *(const PG8_LAS bf16x8*)(lds + PG8_SB(b, h) + boff + n * 2048 + k * 1024); } while (0)
; #define PG8_MMA(ai, bj, At, Bt) do { __builtin_amdgcn_s_setprio(1); _Pragma("unroll") for (int m = 0; m < 4; ++m) _Pragma("unroll") for (int n = 0; n < 2; ++n) _Pragma("unroll") for (int k = 0; k < 2; ++k) \
;         acc[ai][bj][m][n] = __builtin_amdgcn_mfma_f32_16x16x32_bf16(Bt[n][k], At[m][k], acc[ai][bj][m][n], 0, 0, 0); __builtin_amdgcn_s_setprio(0); } while (0)
; #define PG8_WAIT_V(n) asm volatile("s_waitcnt vmcnt(" #n ")" ::: "memory")
; #define PG8_WAIT_L(n) asm volatile("s_waitcnt lgkmcnt(" #n ")" ::: "memory")
; #define PG8_BAR __builtin_amdgcn_s_barrier()
; #define PG8_SCHED __builtin_amdgcn_sched_barrier(0)
; template <class Epi, class Sched, bool ALIGN_EPI = false, bool SP2 = false>
; __device__ __forceinline__ void gemm_phase(PG8_LAS unsigned char* lds, const Gemm g, const Sched& S, const Epi& E, const int wid) {
;     ...
;             PG8_WAIT_V(8); PG8_WAIT_L(0); PG8_BAR; PG8_MMA(1, 0, At, B0); PG8_MMA(1, 1, At, B1); PG8_BAR; PG8_SCHED;
;             PG8_LDB(B0, 1, 0); PG8_LDB(B1, 1, 1); PG8_SCHED; PG8_LDA(At, 1, 0); PG8_STAGE(PG8_SA(0, 1), a2 + hstep, voffA);
;             PG8_WAIT_V(8); PG8_WAIT_L(0); PG8_BAR; PG8_MMA(0, 0, At, B0); PG8_MMA(0, 1, At, B1); PG8_BAR; PG8_SCHED;
	s_setprio 1
	s_waitcnt lgkmcnt(0)
	v_mfma_f32_16x16x32_bf16 v[60:63], v[152:155], v[190:193], v[60:63]
	v_mfma_f32_16x16x32_bf16 v[56:59], v[160:163], v[190:193], v[56:59]
	v_mfma_f32_16x16x32_bf16 v[44:47], v[152:155], v[198:201], v[44:47]
	v_mfma_f32_16x16x32_bf16 v[40:43], v[160:163], v[198:201], v[40:43]
	v_mfma_f32_16x16x32_bf16 v[28:31], v[152:155], v[206:209], v[28:31]
	v_mfma_f32_16x16x32_bf16 v[24:27], v[160:163], v[206:209], v[24:27]
	v_mfma_f32_16x16x32_bf16 v[12:15], v[152:155], v[214:217], v[12:15]
	v_mfma_f32_16x16x32_bf16 v[8:11], v[160:163], v[214:217], v[8:11]
	v_mfma_f32_16x16x32_bf16 v[60:63], v[156:159], v[194:197], v[60:63]
	v_mfma_f32_16x16x32_bf16 v[56:59], v[168:171], v[194:197], v[56:59]
	v_mfma_f32_16x16x32_bf16 v[44:47], v[156:159], v[202:205], v[44:47]
	v_mfma_f32_16x16x32_bf16 v[40:43], v[168:171], v[202:205], v[40:43]
	v_mfma_f32_16x16x32_bf16 v[28:31], v[156:159], v[210:213], v[28:31]
	v_mfma_f32_16x16x32_bf16 v[24:27], v[168:171], v[210:213], v[24:27]
	v_mfma_f32_16x16x32_bf16 v[12:15], v[156:159], v[218:221], v[12:15]
	v_mfma_f32_16x16x32_bf16 v[8:11], v[168:171], v[218:221], v[8:11]
	v_mfma_f32_16x16x32_bf16 v[52:55], v[172:175], v[190:193], v[52:55]
	v_mfma_f32_16x16x32_bf16 v[48:51], v[182:185], v[190:193], v[48:51]
	v_mfma_f32_16x16x32_bf16 v[36:39], v[172:175], v[198:201], v[36:39]
	v_mfma_f32_16x16x32_bf16 v[32:35], v[182:185], v[198:201], v[32:35]
	v_mfma_f32_16x16x32_bf16 v[20:23], v[172:175], v[206:209], v[20:23]
	v_mfma_f32_16x16x32_bf16 v[16:19], v[182:185], v[206:209], v[16:19]
	v_mfma_f32_16x16x32_bf16 v[4:7], v[172:175], v[214:217], v[4:7]
	v_mfma_f32_16x16x32_bf16 v[0:3], v[182:185], v[214:217], v[0:3]
	v_mfma_f32_16x16x32_bf16 v[52:55], v[178:181], v[194:197], v[52:55]
	v_mfma_f32_16x16x32_bf16 v[48:51], v[186:189], v[194:197], v[48:51]
	v_mfma_f32_16x16x32_bf16 v[36:39], v[178:181], v[202:205], v[36:39]
	v_mfma_f32_16x16x32_bf16 v[32:35], v[186:189], v[202:205], v[32:35]
	v_mfma_f32_16x16x32_bf16 v[20:23], v[178:181], v[210:213], v[20:23]
	v_mfma_f32_16x16x32_bf16 v[16:19], v[186:189], v[210:213], v[16:19]
	v_mfma_f32_16x16x32_bf16 v[4:7], v[178:181], v[218:221], v[4:7]
	v_mfma_f32_16x16x32_bf16 v[0:3], v[186:189], v[218:221], v[0:3]
	s_setprio 0
	s_barrier
	s_add_i32 s43, 0, 0x18000
	v_add_u32_e32 v151, s43, v149
	s_add_i32 s44, 0, 0x1c000
	ds_read_b128 v[152:155], v151
	ds_read_b128 v[156:159], v151 offset:1024
	ds_read_b128 v[160:163], v151 offset:2048
	ds_read_b128 v[168:171], v151 offset:3072
	v_add_u32_e32 v151, s44, v149
	ds_read_b128 v[172:175], v151
	ds_read_b128 v[178:181], v151 offset:1024
	ds_read_b128 v[182:185], v151 offset:2048
	ds_read_b128 v[186:189], v151 offset:3072
	s_add_u32 s18, s18, 0xb0000
	s_addc_u32 s19, s19, 0
	s_mov_b32 m0, s28
	v_lshl_add_u64 v[230:231], s[18:19], 0, v[128:129]
	ds_read_b128 v[190:193], v150 offset:32768
	ds_read_b128 v[194:197], v150 offset:33792
	ds_read_b128 v[198:201], v150 offset:34816
	ds_read_b128 v[202:205], v150 offset:35840
	ds_read_b128 v[206:209], v150 offset:36864
	ds_read_b128 v[210:213], v150 offset:37888
	ds_read_b128 v[214:217], v150 offset:38912
	ds_read_b128 v[218:221], v150 offset:39936
	global_load_lds_dwordx4 v[230:231], off
	v_lshl_add_u64 v[230:231], s[18:19], 0, v[132:133]
	s_mov_b32 m0, s29
	s_nop 0
	global_load_lds_dwordx4 v[230:231], off
	s_waitcnt vmcnt(8)
	s_waitcnt lgkmcnt(0)
	s_barrier
	s_setprio 1
	s_waitcnt lgkmcnt(0)
	v_mfma_f32_16x16x32_bf16 v[124:127], v[152:155], v[190:193], v[124:127]
	v_mfma_f32_16x16x32_bf16 v[120:123], v[160:163], v[190:193], v[120:123]
	v_mfma_f32_16x16x32_bf16 v[112:115], v[152:155], v[198:201], v[112:115]
	v_mfma_f32_16x16x32_bf16 v[104:107], v[160:163], v[198:201], v[104:107]
	v_mfma_f32_16x16x32_bf16 v[96:99], v[152:155], v[206:209], v[96:99]
	v_mfma_f32_16x16x32_bf16 v[88:91], v[160:163], v[206:209], v[88:91]
	v_mfma_f32_16x16x32_bf16 v[80:83], v[152:155], v[214:217], v[80:83]
	v_mfma_f32_16x16x32_bf16 v[72:75], v[160:163], v[214:217], v[72:75]
	v_mfma_f32_16x16x32_bf16 v[124:127], v[156:159], v[194:197], v[124:127]
	v_mfma_f32_16x16x32_bf16 v[120:123], v[168:171], v[194:197], v[120:123]
	v_mfma_f32_16x16x32_bf16 v[112:115], v[156:159], v[202:205], v[112:115]
	v_mfma_f32_16x16x32_bf16 v[104:107], v[168:171], v[202:205], v[104:107]
	v_mfma_f32_16x16x32_bf16 v[96:99], v[156:159], v[210:213], v[96:99]
	v_mfma_f32_16x16x32_bf16 v[88:91], v[168:171], v[210:213], v[88:91]
	v_mfma_f32_16x16x32_bf16 v[80:83], v[156:159], v[218:221], v[80:83]
	v_mfma_f32_16x16x32_bf16 v[72:75], v[168:171], v[218:221], v[72:75]
	v_mfma_f32_16x16x32_bf16 v[116:119], v[172:175], v[190:193], v[116:119]
	v_mfma_f32_16x16x32_bf16 v[108:111], v[182:185], v[190:193], v[108:111]
	v_mfma_f32_16x16x32_bf16 v[100:103], v[172:175], v[198:201], v[100:103]
	v_mfma_f32_16x16x32_bf16 v[92:95], v[182:185], v[198:201], v[92:95]
	v_mfma_f32_16x16x32_bf16 v[84:87], v[172:175], v[206:209], v[84:87]
	v_mfma_f32_16x16x32_bf16 v[76:79], v[182:185], v[206:209], v[76:79]
	v_mfma_f32_16x16x32_bf16 v[68:71], v[172:175], v[214:217], v[68:71]
	v_mfma_f32_16x16x32_bf16 v[64:67], v[182:185], v[214:217], v[64:67]
	v_mfma_f32_16x16x32_bf16 v[116:119], v[178:181], v[194:197], v[116:119]
	v_mfma_f32_16x16x32_bf16 v[108:111], v[186:189], v[194:197], v[108:111]
	v_mfma_f32_16x16x32_bf16 v[100:103], v[178:181], v[202:205], v[100:103]
	v_mfma_f32_16x16x32_bf16 v[92:95], v[186:189], v[202:205], v[92:95]
	v_mfma_f32_16x16x32_bf16 v[84:87], v[178:181], v[210:213], v[84:87]
	v_mfma_f32_16x16x32_bf16 v[76:79], v[186:189], v[210:213], v[76:79]
	v_mfma_f32_16x16x32_bf16 v[68:71], v[178:181], v[218:221], v[68:71]
	v_mfma_f32_16x16x32_bf16 v[64:67], v[186:189], v[218:221], v[64:67]
	s_setprio 0
	s_barrier
; #define PG8_STAGE(bufoff, gbase, voff) do { _Pragma("unroll") for (int _i = 0; _i < 2; ++_i) \
;         __builtin_amdgcn_global_load_lds((const unsigned*)((const char*)(gbase) + (voff)[_i]), (PG8_LAS unsigned*)(lds + (bufoff) + ldsw + _i * 8192), 16, 0, 0); } while (0)
; #define PG8_LDA(dst, b, h) do { _Pragma("unroll") for (int m = 0; m < 4; ++m) _Pragma("unroll") for (int k = 0; k < 2; ++k) dst[m][k] = *(const PG8_LAS bf16x8*)(lds + PG8_SA(b, h) + aoff + m * 2048 + k * 1024); } while (0)
; #define PG8_MMA(ai, bj, At, Bt) do { __builtin_amdgcn_s_setprio(1); _Pragma("unroll") for (int m = 0; m < 4; ++m) _Pragma("unroll") for (int n = 0; n < 2; ++n) _Pragma("unroll") for (int k = 0; k < 2; ++k) \
;         acc[ai][bj][m][n] = __builtin_amdgcn_mfma_f32_16x16x32_bf16(Bt[n][k], At[m][k], acc[ai][bj][m][n], 0, 0, 0); __builtin_amdgcn_s_setprio(0); } while (0)
; #define PG8_WAIT_V(n) asm volatile("s_waitcnt vmcnt(" #n ")" ::: "memory")
; #define PG8_WAIT_L(n) asm volatile("s_waitcnt lgkmcnt(" #n ")" ::: "memory")
; #define PG8_BAR __builtin_amdgcn_s_barrier()
; #define PG8_SCHED __builtin_amdgcn_sched_barrier(0)
; template <class Epi, class Sched, bool ALIGN_EPI = false, bool SP2 = false>
; __device__ __forceinline__ void gemm_phase(PG8_LAS unsigned char* lds, const Gemm g, const Sched& S, const Epi& E, const int wid) {
;     ...
;             PG8_LDA(At, 1, 1); PG8_STAGE(PG8_SB(1, 0), b3, voffB); PG8_STAGE(PG8_SB(1, 1), b3 + hstep, voffB); PG8_STAGE(PG8_SA(1, 0), a3, voffA);
;             PG8_WAIT_V(8); PG8_WAIT_L(0); PG8_BAR; PG8_MMA(1, 0, At, B0); PG8_MMA(1, 1, At, B1); PG8_BAR; PG8_SCHED;
;     ...
;         if (!has_next) break;
; #pragma unroll
;         for (int a = 0; a < 2; ++a)
; #pragma unroll
;             for (int b = 0; b < 2; ++b)
; #pragma unroll
;                 for (int m = 0; m < 4; ++m)
; #pragma unroll
;                     for (int n = 0; n < 2; ++n) acc[a][b][m][n] = (f32x4){0.f, 0.f, 0.f, 0.f};
;         cur = nxt; cA = nA; cB = nB; ++ui;
	s_add_i32 s18, s43, s24
	v_lshl_add_u64 v[222:223], v[222:223], 0, s[10:11]
	s_mov_b32 m0, s18
	ds_read_b128 v[190:193], v150 offset:49152
	ds_read_b128 v[194:197], v150 offset:50176
	ds_read_b128 v[198:201], v150 offset:51200
	ds_read_b128 v[202:205], v150 offset:52224
	ds_read_b128 v[206:209], v150 offset:53248
	ds_read_b128 v[210:213], v150 offset:54272
	ds_read_b128 v[214:217], v150 offset:55296
	ds_read_b128 v[218:221], v150 offset:56320
	global_load_lds_dwordx4 v[222:223], off
	s_add_i32 m0, s18, 0x2000
	s_add_u32 s16, s16, 0xb0080
	v_lshl_add_u64 v[222:223], v[224:225], 0, s[10:11]
	s_addc_u32 s17, s17, 0
	s_add_i32 s18, s44, s24
	global_load_lds_dwordx4 v[222:223], off
	v_lshl_add_u64 v[222:223], s[16:17], 0, v[130:131]
	s_mov_b32 m0, s18
	s_nop 0
	global_load_lds_dwordx4 v[222:223], off
	v_lshl_add_u64 v[222:223], s[16:17], 0, v[134:135]
	s_add_i32 m0, s18, 0x2000
	s_nop 0
	global_load_lds_dwordx4 v[222:223], off
	v_lshl_add_u64 v[222:223], v[226:227], 0, s[10:11]
	s_mov_b32 m0, s31
	s_nop 0
	global_load_lds_dwordx4 v[222:223], off
	v_lshl_add_u64 v[222:223], v[228:229], 0, s[10:11]
	s_mov_b32 m0, s33
	s_nop 0
	global_load_lds_dwordx4 v[222:223], off
	s_waitcnt vmcnt(8)
	s_waitcnt lgkmcnt(0)
	s_barrier
	s_setprio 1
	s_waitcnt lgkmcnt(0)
	v_mfma_f32_16x16x32_bf16 v[60:63], v[152:155], v[190:193], v[60:63]
	v_mfma_f32_16x16x32_bf16 v[56:59], v[160:163], v[190:193], v[56:59]
	v_mfma_f32_16x16x32_bf16 v[44:47], v[152:155], v[198:201], v[44:47]
	v_mfma_f32_16x16x32_bf16 v[40:43], v[160:163], v[198:201], v[40:43]
	v_mfma_f32_16x16x32_bf16 v[28:31], v[152:155], v[206:209], v[28:31]
	v_mfma_f32_16x16x32_bf16 v[24:27], v[160:163], v[206:209], v[24:27]
	v_mfma_f32_16x16x32_bf16 v[12:15], v[152:155], v[214:217], v[12:15]
	v_mfma_f32_16x16x32_bf16 v[8:11], v[160:163], v[214:217], v[8:11]
	v_mfma_f32_16x16x32_bf16 v[60:63], v[156:159], v[194:197], v[60:63]
	v_mfma_f32_16x16x32_bf16 v[56:59], v[168:171], v[194:197], v[56:59]
	v_mfma_f32_16x16x32_bf16 v[44:47], v[156:159], v[202:205], v[44:47]
	v_mfma_f32_16x16x32_bf16 v[40:43], v[168:171], v[202:205], v[40:43]
	v_mfma_f32_16x16x32_bf16 v[28:31], v[156:159], v[210:213], v[28:31]
	v_mfma_f32_16x16x32_bf16 v[24:27], v[168:171], v[210:213], v[24:27]
	v_mfma_f32_16x16x32_bf16 v[12:15], v[156:159], v[218:221], v[12:15]
	v_mfma_f32_16x16x32_bf16 v[8:11], v[168:171], v[218:221], v[8:11]
	v_mfma_f32_16x16x32_bf16 v[52:55], v[172:175], v[190:193], v[52:55]
	v_mfma_f32_16x16x32_bf16 v[48:51], v[182:185], v[190:193], v[48:51]
	v_mfma_f32_16x16x32_bf16 v[36:39], v[172:175], v[198:201], v[36:39]
	v_mfma_f32_16x16x32_bf16 v[32:35], v[182:185], v[198:201], v[32:35]
	v_mfma_f32_16x16x32_bf16 v[20:23], v[172:175], v[206:209], v[20:23]
	v_mfma_f32_16x16x32_bf16 v[16:19], v[182:185], v[206:209], v[16:19]
	v_mfma_f32_16x16x32_bf16 v[4:7], v[172:175], v[214:217], v[4:7]
	v_mfma_f32_16x16x32_bf16 v[0:3], v[182:185], v[214:217], v[0:3]
	v_mfma_f32_16x16x32_bf16 v[52:55], v[178:181], v[194:197], v[52:55]
	v_mfma_f32_16x16x32_bf16 v[48:51], v[186:189], v[194:197], v[48:51]
	v_mfma_f32_16x16x32_bf16 v[36:39], v[178:181], v[202:205], v[36:39]
	v_mfma_f32_16x16x32_bf16 v[32:35], v[186:189], v[202:205], v[32:35]
	v_mfma_f32_16x16x32_bf16 v[20:23], v[178:181], v[210:213], v[20:23]
	v_mfma_f32_16x16x32_bf16 v[16:19], v[186:189], v[210:213], v[16:19]
	v_mfma_f32_16x16x32_bf16 v[4:7], v[178:181], v[218:221], v[4:7]
	v_mfma_f32_16x16x32_bf16 v[0:3], v[186:189], v[218:221], v[0:3]
	s_setprio 0
	s_barrier
	s_add_i32 s42, s42, 2
	s_add_u32 s14, s14, 0x100
	s_addc_u32 s15, s15, 0
	s_cmp_gt_u32 s42, 41
	s_cbranch_scc0 .LBB0_2460
	s_add_u32 s14, s40, 0xffffff00
	s_addc_u32 s15, s41, -1
	s_and_b64 vcc, exec, s[6:7]
	s_cbranch_vccnz .LBB0_2447
	v_mov_b32_e32 v0, 0
	s_mov_b32 s2, s37
	s_mov_b32 s20, s38
	s_mov_b64 s[8:9], s[12:13]
	s_mov_b32 s34, s39
	v_mov_b32_e32 v1, v0
	v_mov_b32_e32 v2, v0
	v_mov_b32_e32 v3, v0
	v_mov_b32_e32 v4, v0
	v_mov_b32_e32 v5, v0
	v_mov_b32_e32 v6, v0
	v_mov_b32_e32 v7, v0
	v_mov_b32_e32 v16, v0
	v_mov_b32_e32 v17, v0
	v_mov_b32_e32 v18, v0
	v_mov_b32_e32 v19, v0
	v_mov_b32_e32 v20, v0
	v_mov_b32_e32 v21, v0
	v_mov_b32_e32 v22, v0
	v_mov_b32_e32 v23, v0
	v_mov_b32_e32 v32, v0
	v_mov_b32_e32 v33, v0
	v_mov_b32_e32 v34, v0
	v_mov_b32_e32 v35, v0
	v_mov_b32_e32 v36, v0
	v_mov_b32_e32 v37, v0
	v_mov_b32_e32 v38, v0
	v_mov_b32_e32 v39, v0
	v_mov_b32_e32 v48, v0
	v_mov_b32_e32 v49, v0
	v_mov_b32_e32 v50, v0
	v_mov_b32_e32 v51, v0
	v_mov_b32_e32 v52, v0
	v_mov_b32_e32 v53, v0
	v_mov_b32_e32 v54, v0
	v_mov_b32_e32 v55, v0
	v_mov_b32_e32 v8, v0
	v_mov_b32_e32 v9, v0
	v_mov_b32_e32 v10, v0
	v_mov_b32_e32 v11, v0
	v_mov_b32_e32 v12, v0
	v_mov_b32_e32 v13, v0
	v_mov_b32_e32 v14, v0
	v_mov_b32_e32 v15, v0
	v_mov_b32_e32 v24, v0
	v_mov_b32_e32 v25, v0
	v_mov_b32_e32 v26, v0
	v_mov_b32_e32 v27, v0
	v_mov_b32_e32 v28, v0
	v_mov_b32_e32 v29, v0
	v_mov_b32_e32 v30, v0
	v_mov_b32_e32 v31, v0
	v_mov_b32_e32 v40, v0
	v_mov_b32_e32 v41, v0
	v_mov_b32_e32 v42, v0
	v_mov_b32_e32 v43, v0
	v_mov_b32_e32 v44, v0
	v_mov_b32_e32 v45, v0
	v_mov_b32_e32 v46, v0
	v_mov_b32_e32 v47, v0
	v_mov_b32_e32 v56, v0
	v_mov_b32_e32 v57, v0
	v_mov_b32_e32 v58, v0
	v_mov_b32_e32 v59, v0
	v_mov_b32_e32 v60, v0
	v_mov_b32_e32 v61, v0
	v_mov_b32_e32 v62, v0
	v_mov_b32_e32 v63, v0
	v_mov_b32_e32 v64, v0
	v_mov_b32_e32 v65, v0
	v_mov_b32_e32 v66, v0
	v_mov_b32_e32 v67, v0
	v_mov_b32_e32 v68, v0
	v_mov_b32_e32 v69, v0
	v_mov_b32_e32 v70, v0
	v_mov_b32_e32 v71, v0
	v_mov_b32_e32 v76, v0
	v_mov_b32_e32 v77, v0
	v_mov_b32_e32 v78, v0
	v_mov_b32_e32 v79, v0
	v_mov_b32_e32 v84, v0
	v_mov_b32_e32 v85, v0
	v_mov_b32_e32 v86, v0
	v_mov_b32_e32 v87, v0
	v_mov_b32_e32 v92, v0
	v_mov_b32_e32 v93, v0
	v_mov_b32_e32 v94, v0
	v_mov_b32_e32 v95, v0
	v_mov_b32_e32 v100, v0
	v_mov_b32_e32 v101, v0
	v_mov_b32_e32 v102, v0
	v_mov_b32_e32 v103, v0
	v_mov_b32_e32 v108, v0
	v_mov_b32_e32 v109, v0
	v_mov_b32_e32 v110, v0
	v_mov_b32_e32 v111, v0
	v_mov_b32_e32 v116, v0
	v_mov_b32_e32 v117, v0
	v_mov_b32_e32 v118, v0
	v_mov_b32_e32 v119, v0
	v_mov_b32_e32 v72, v0
	v_mov_b32_e32 v73, v0
	v_mov_b32_e32 v74, v0
	v_mov_b32_e32 v75, v0
	v_mov_b32_e32 v80, v0
	v_mov_b32_e32 v81, v0
	v_mov_b32_e32 v82, v0
	v_mov_b32_e32 v83, v0
	v_mov_b32_e32 v88, v0
	v_mov_b32_e32 v89, v0
	v_mov_b32_e32 v90, v0
	v_mov_b32_e32 v91, v0
	v_mov_b32_e32 v96, v0
	v_mov_b32_e32 v97, v0
	v_mov_b32_e32 v98, v0
	v_mov_b32_e32 v99, v0
	v_mov_b32_e32 v104, v0
	v_mov_b32_e32 v105, v0
	v_mov_b32_e32 v106, v0
	v_mov_b32_e32 v107, v0
	v_mov_b32_e32 v112, v0
	v_mov_b32_e32 v113, v0
	v_mov_b32_e32 v114, v0
	v_mov_b32_e32 v115, v0
	v_mov_b32_e32 v120, v0
	v_mov_b32_e32 v121, v0
	v_mov_b32_e32 v122, v0
	v_mov_b32_e32 v123, v0
	v_mov_b32_e32 v124, v0
	v_mov_b32_e32 v125, v0
	v_mov_b32_e32 v126, v0
	v_mov_b32_e32 v127, v0
	s_andn2_b64 vcc, exec, s[0:1]
	s_cbranch_vccnz .LBB0_2448
